# strategy: waitcnt placement in the GEMM mainloops - the duplicate post-barrier s_waitcnt lgkmcnt(0) (already drained before the barrier) removed at 28 sites
# baseline (speedup 1.0000x reference)
; #define PG8_STAGE(bufoff, gbase, voff) do { _Pragma("unroll") for (int _i = 0; _i < 2; ++_i) \
;         __builtin_amdgcn_global_load_lds((const unsigned*)((const char*)(gbase) + (voff)[_i]), (LAS unsigned*)(lds + (bufoff) + ldsw + _i * 8192), 16, 0, 0); } while (0)
; #define PG8_LDA(dst, b, h) do { _Pragma("unroll") for (int m = 0; m < 4; ++m) _Pragma("unroll") for (int k = 0; k < 2; ++k) dst[m][k] = *(const LAS bf16x8*)(lds + PG8_SA(b, h) + aoff + m * 2048 + k * 1024); } while (0)
; #define PG8_LDB(dst, b, h) do { _Pragma("unroll") for (int n = 0; n < 2; ++n) _Pragma("unroll") for (int k = 0; k < 2; ++k) dst[n][k] = *(const LAS bf16x8*)(lds + PG8_SB(b, h) + boff + n * 2048 + k * 1024); } while (0)
; #define PG8_MMA(ai, bj, At, Bt) do { __builtin_amdgcn_s_setprio(1); _Pragma("unroll") for (int m = 0; m < 4; ++m) _Pragma("unroll") for (int n = 0; n < 2; ++n) _Pragma("unroll") for (int k = 0; k < 2; ++k) \
;         acc[ai][bj][m][n] = __builtin_amdgcn_mfma_f32_16x16x32_bf16(Bt[n][k], At[m][k], acc[ai][bj][m][n], 0, 0, 0); __builtin_amdgcn_s_setprio(0); } while (0)
; #define PG8_WAIT_V(n) asm volatile("s_waitcnt vmcnt(" #n ")" ::: "memory")
; #define PG8_BAR __builtin_amdgcn_s_barrier()
; template <class Epi>
; __device__ __forceinline__ void gemm_phase(LAS unsigned char* lds, const Gemm g, const StaticOrder& S, const Epi& E, const int tid) {
;     ...
;         const char* nA = has_next ? (const char*)g.A + (size_t)nxt.pm * tstep : cA; const char* nB = has_next ? (const char*)g.Bt + (size_t)nxt.pn * tstep : cB;
;         for (int t = 0; t < nt; t += 2) {
;             const bool last = (t == nt - 2);
;             const char* a1 = cA + (size_t)(t + 1) * kstep;
;             const char* a2 = last ? nA : cA + (size_t)(t + 2) * kstep; const char* b2 = last ? nB : cB + (size_t)(t + 2) * kstep;
;             const char* a3 = a2 + kstep; const char* b3 = b2 + kstep;
;             PG8_LDB(B0, 0, 0); PG8_LDB(B1, 0, 1); PG8_SCHED; PG8_LDA(At, 0, 0); PG8_STAGE(PG8_SA(1, 1), a1 + hstep, voffA);
;             PG8_WAIT_V(8); PG8_WAIT_L(0); PG8_BAR; PG8_MMA(0, 0, At, B0); PG8_MMA(0, 1, At, B1); PG8_BAR; PG8_SCHED;
;             PG8_LDA(At, 0, 1); PG8_STAGE(PG8_SB(0, 0), b2, voffB); PG8_STAGE(PG8_SB(0, 1), b2 + hstep, voffB); PG8_STAGE(PG8_SA(0, 0), a2, voffA);
;             PG8_WAIT_V(8); PG8_WAIT_L(0); PG8_BAR; PG8_MMA(1, 0, At, B0); PG8_MMA(1, 1, At, B1); PG8_BAR; PG8_SCHED;
.LBB0_150:
	s_add_u32 s10, s62, 0xfff80080
	s_addc_u32 s11, s63, -1
	s_add_i32 s78, 0, 0x10000
	s_cmp_eq_u32 vcc_hi, 28
	s_cselect_b32 s67, s53, s11
	s_cselect_b32 s66, s95, s10
	v_add_u32_e32 v146, s78, v149
	s_cselect_b32 s65, s29, vcc_lo
	s_cselect_b32 s64, s96, s97
	s_add_i32 s46, 0, 0x14000
	ds_read_b128 v[152:155], v146
	ds_read_b128 v[156:159], v146 offset:1024
	ds_read_b128 v[160:163], v146 offset:2048
	ds_read_b128 v[164:167], v146 offset:3072
	v_add_u32_e32 v146, s46, v149
	ds_read_b128 v[172:175], v146
	ds_read_b128 v[178:181], v146 offset:1024
	ds_read_b128 v[182:185], v146 offset:2048
	ds_read_b128 v[186:189], v146 offset:3072
	v_lshl_add_u64 v[146:147], s[62:63], 0, v[142:143]
	s_add_i32 m0, s88, 0xc000
	ds_read_b128 v[190:193], v151
	ds_read_b128 v[194:197], v151 offset:1024
	ds_read_b128 v[198:201], v151 offset:2048
	ds_read_b128 v[202:205], v151 offset:3072
	ds_read_b128 v[206:209], v151 offset:4096
	ds_read_b128 v[210:213], v151 offset:5120
	ds_read_b128 v[214:217], v151 offset:6144
	ds_read_b128 v[218:221], v151 offset:7168
	global_load_lds_dwordx4 v[146:147], off
	v_lshl_add_u64 v[146:147], s[62:63], 0, v[140:141]
	s_add_i32 m0, s88, 0xe000
	s_nop 0
	global_load_lds_dwordx4 v[146:147], off
	s_waitcnt vmcnt(8)
	s_waitcnt lgkmcnt(0)
	s_barrier
	s_setprio 1
	v_mfma_f32_16x16x32_bf16 v[124:127], v[152:155], v[190:193], v[124:127]
	v_mfma_f32_16x16x32_bf16 v[116:119], v[160:163], v[190:193], v[116:119]
	v_mfma_f32_16x16x32_bf16 v[108:111], v[152:155], v[198:201], v[108:111]
	v_mfma_f32_16x16x32_bf16 v[100:103], v[160:163], v[198:201], v[100:103]
	v_mfma_f32_16x16x32_bf16 v[92:95], v[152:155], v[206:209], v[92:95]
	v_mfma_f32_16x16x32_bf16 v[84:87], v[160:163], v[206:209], v[84:87]
	v_mfma_f32_16x16x32_bf16 v[76:79], v[152:155], v[214:217], v[76:79]
	v_mfma_f32_16x16x32_bf16 v[68:71], v[160:163], v[214:217], v[68:71]
	v_mfma_f32_16x16x32_bf16 v[124:127], v[156:159], v[194:197], v[124:127]
	v_mfma_f32_16x16x32_bf16 v[116:119], v[164:167], v[194:197], v[116:119]
	v_mfma_f32_16x16x32_bf16 v[108:111], v[156:159], v[202:205], v[108:111]
	v_mfma_f32_16x16x32_bf16 v[100:103], v[164:167], v[202:205], v[100:103]
	v_mfma_f32_16x16x32_bf16 v[92:95], v[156:159], v[210:213], v[92:95]
	v_mfma_f32_16x16x32_bf16 v[84:87], v[164:167], v[210:213], v[84:87]
	v_mfma_f32_16x16x32_bf16 v[76:79], v[156:159], v[218:221], v[76:79]
	v_mfma_f32_16x16x32_bf16 v[68:71], v[164:167], v[218:221], v[68:71]
	s_setprio 0
	s_setprio 1
	v_mfma_f32_16x16x32_bf16 v[120:123], v[172:175], v[190:193], v[120:123]
	v_mfma_f32_16x16x32_bf16 v[112:115], v[182:185], v[190:193], v[112:115]
	v_mfma_f32_16x16x32_bf16 v[104:107], v[172:175], v[198:201], v[104:107]
	v_mfma_f32_16x16x32_bf16 v[96:99], v[182:185], v[198:201], v[96:99]
	v_mfma_f32_16x16x32_bf16 v[88:91], v[172:175], v[206:209], v[88:91]
	v_mfma_f32_16x16x32_bf16 v[80:83], v[182:185], v[206:209], v[80:83]
	v_mfma_f32_16x16x32_bf16 v[72:75], v[172:175], v[214:217], v[72:75]
	v_mfma_f32_16x16x32_bf16 v[64:67], v[182:185], v[214:217], v[64:67]
	v_mfma_f32_16x16x32_bf16 v[120:123], v[178:181], v[194:197], v[120:123]
	v_mfma_f32_16x16x32_bf16 v[112:115], v[186:189], v[194:197], v[112:115]
	v_mfma_f32_16x16x32_bf16 v[104:107], v[178:181], v[202:205], v[104:107]
	v_mfma_f32_16x16x32_bf16 v[96:99], v[186:189], v[202:205], v[96:99]
	v_mfma_f32_16x16x32_bf16 v[88:91], v[178:181], v[210:213], v[88:91]
	v_mfma_f32_16x16x32_bf16 v[80:83], v[186:189], v[210:213], v[80:83]
	v_mfma_f32_16x16x32_bf16 v[72:75], v[178:181], v[218:221], v[72:75]
	v_mfma_f32_16x16x32_bf16 v[64:67], v[186:189], v[218:221], v[64:67]
	s_setprio 0
	s_barrier
	s_add_i32 s10, s78, s87
	v_lshl_add_u64 v[146:147], s[64:65], 0, v[128:129]
	s_mov_b32 m0, s10
	ds_read_b128 v[190:193], v151 offset:16384
	ds_read_b128 v[194:197], v151 offset:17408
	ds_read_b128 v[198:201], v151 offset:18432
	ds_read_b128 v[202:205], v151 offset:19456
	ds_read_b128 v[206:209], v151 offset:20480
	ds_read_b128 v[210:213], v151 offset:21504
	ds_read_b128 v[214:217], v151 offset:22528
	ds_read_b128 v[218:221], v151 offset:23552
	global_load_lds_dwordx4 v[146:147], off
	s_add_i32 m0, s10, 0x2000
	s_add_u32 s10, s64, 0x80000
	v_lshl_add_u64 v[168:169], s[64:65], 0, v[138:139]
	s_addc_u32 s11, s65, 0
	s_add_i32 s46, s46, s87
	global_load_lds_dwordx4 v[168:169], off
	v_lshl_add_u64 v[222:223], s[10:11], 0, v[128:129]
	s_mov_b32 m0, s46
	v_lshl_add_u64 v[226:227], s[66:67], 0, v[136:137]
	global_load_lds_dwordx4 v[222:223], off
	v_lshl_add_u64 v[222:223], s[10:11], 0, v[138:139]
	s_add_i32 m0, s46, 0x2000
	s_nop 0
	global_load_lds_dwordx4 v[222:223], off
	v_lshl_add_u64 v[222:223], s[66:67], 0, v[134:135]
	s_mov_b32 m0, s88
	s_nop 0
	global_load_lds_dwordx4 v[222:223], off
	s_mov_b32 m0, s89
	s_nop 0
	global_load_lds_dwordx4 v[226:227], off
	s_waitcnt vmcnt(8)
	s_waitcnt lgkmcnt(0)
	s_barrier
; #define PG8_STAGE(bufoff, gbase, voff) do { _Pragma("unroll") for (int _i = 0; _i < 2; ++_i) \
;         __builtin_amdgcn_global_load_lds((const unsigned*)((const char*)(gbase) + (voff)[_i]), (LAS unsigned*)(lds + (bufoff) + ldsw + _i * 8192), 16, 0, 0); } while (0)
; #define PG8_LDA(dst, b, h) do { _Pragma("unroll") for (int m = 0; m < 4; ++m) _Pragma("unroll") for (int k = 0; k < 2; ++k) dst[m][k] = *(const LAS bf16x8*)(lds + PG8_SA(b, h) + aoff + m * 2048 + k * 1024); } while (0)
; #define PG8_LDB(dst, b, h) do { _Pragma("unroll") for (int n = 0; n < 2; ++n) _Pragma("unroll") for (int k = 0; k < 2; ++k) dst[n][k] = *(const LAS bf16x8*)(lds + PG8_SB(b, h) + boff + n * 2048 + k * 1024); } while (0)
; #define PG8_MMA(ai, bj, At, Bt) do { __builtin_amdgcn_s_setprio(1); _Pragma("unroll") for (int m = 0; m < 4; ++m) _Pragma("unroll") for (int n = 0; n < 2; ++n) _Pragma("unroll") for (int k = 0; k < 2; ++k) \
;         acc[ai][bj][m][n] = __builtin_amdgcn_mfma_f32_16x16x32_bf16(Bt[n][k], At[m][k], acc[ai][bj][m][n], 0, 0, 0); __builtin_amdgcn_s_setprio(0); } while (0)
; #define PG8_WAIT_V(n) asm volatile("s_waitcnt vmcnt(" #n ")" ::: "memory")
; #define PG8_WAIT_L(n) asm volatile("s_waitcnt lgkmcnt(" #n ")" ::: "memory")
; #define PG8_BAR __builtin_amdgcn_s_barrier()
; #define PG8_SCHED __builtin_amdgcn_sched_barrier(0)
; template <class Epi>
; __device__ __forceinline__ void gemm_phase(LAS unsigned char* lds, const Gemm g, const StaticOrder& S, const Epi& E, const int tid) {
;     ...
;             PG8_WAIT_V(8); PG8_WAIT_L(0); PG8_BAR; PG8_MMA(1, 0, At, B0); PG8_MMA(1, 1, At, B1); PG8_BAR; PG8_SCHED;
;             PG8_LDB(B0, 1, 0); PG8_LDB(B1, 1, 1); PG8_SCHED; PG8_LDA(At, 1, 0); PG8_STAGE(PG8_SA(0, 1), a2 + hstep, voffA);
;             PG8_WAIT_V(8); PG8_WAIT_L(0); PG8_BAR; PG8_MMA(0, 0, At, B0); PG8_MMA(0, 1, At, B1); PG8_BAR; PG8_SCHED;
	s_setprio 1
	v_mfma_f32_16x16x32_bf16 v[60:63], v[152:155], v[190:193], v[60:63]
	v_mfma_f32_16x16x32_bf16 v[52:55], v[160:163], v[190:193], v[52:55]
	v_mfma_f32_16x16x32_bf16 v[44:47], v[152:155], v[198:201], v[44:47]
	v_mfma_f32_16x16x32_bf16 v[36:39], v[160:163], v[198:201], v[36:39]
	v_mfma_f32_16x16x32_bf16 v[28:31], v[152:155], v[206:209], v[28:31]
	v_mfma_f32_16x16x32_bf16 v[20:23], v[160:163], v[206:209], v[20:23]
	v_mfma_f32_16x16x32_bf16 v[12:15], v[152:155], v[214:217], v[12:15]
	v_mfma_f32_16x16x32_bf16 v[4:7], v[160:163], v[214:217], v[4:7]
	v_mfma_f32_16x16x32_bf16 v[60:63], v[156:159], v[194:197], v[60:63]
	v_mfma_f32_16x16x32_bf16 v[52:55], v[164:167], v[194:197], v[52:55]
	v_mfma_f32_16x16x32_bf16 v[44:47], v[156:159], v[202:205], v[44:47]
	v_mfma_f32_16x16x32_bf16 v[36:39], v[164:167], v[202:205], v[36:39]
	v_mfma_f32_16x16x32_bf16 v[28:31], v[156:159], v[210:213], v[28:31]
	v_mfma_f32_16x16x32_bf16 v[20:23], v[164:167], v[210:213], v[20:23]
	v_mfma_f32_16x16x32_bf16 v[12:15], v[156:159], v[218:221], v[12:15]
	v_mfma_f32_16x16x32_bf16 v[4:7], v[164:167], v[218:221], v[4:7]
	s_setprio 0
	s_setprio 1
	v_mfma_f32_16x16x32_bf16 v[56:59], v[172:175], v[190:193], v[56:59]
	v_mfma_f32_16x16x32_bf16 v[48:51], v[182:185], v[190:193], v[48:51]
	v_mfma_f32_16x16x32_bf16 v[40:43], v[172:175], v[198:201], v[40:43]
	v_mfma_f32_16x16x32_bf16 v[32:35], v[182:185], v[198:201], v[32:35]
	v_mfma_f32_16x16x32_bf16 v[24:27], v[172:175], v[206:209], v[24:27]
	v_mfma_f32_16x16x32_bf16 v[16:19], v[182:185], v[206:209], v[16:19]
	v_mfma_f32_16x16x32_bf16 v[8:11], v[172:175], v[214:217], v[8:11]
	v_mfma_f32_16x16x32_bf16 v[0:3], v[182:185], v[214:217], v[0:3]
	v_mfma_f32_16x16x32_bf16 v[56:59], v[178:181], v[194:197], v[56:59]
	v_mfma_f32_16x16x32_bf16 v[48:51], v[186:189], v[194:197], v[48:51]
	v_mfma_f32_16x16x32_bf16 v[40:43], v[178:181], v[202:205], v[40:43]
	v_mfma_f32_16x16x32_bf16 v[32:35], v[186:189], v[202:205], v[32:35]
	v_mfma_f32_16x16x32_bf16 v[24:27], v[178:181], v[210:213], v[24:27]
	v_mfma_f32_16x16x32_bf16 v[16:19], v[186:189], v[210:213], v[16:19]
	v_mfma_f32_16x16x32_bf16 v[8:11], v[178:181], v[218:221], v[8:11]
	v_mfma_f32_16x16x32_bf16 v[0:3], v[186:189], v[218:221], v[0:3]
	s_setprio 0
	s_barrier
	s_add_i32 s46, 0, 0x18000
	s_add_i32 s47, 0, 0x1c000
	v_add_u32_e32 v164, s46, v149
	v_add_u32_e32 v170, s47, v149
	ds_read_b128 v[152:155], v164
	ds_read_b128 v[156:159], v164 offset:1024
	ds_read_b128 v[160:163], v164 offset:2048
	ds_read_b128 v[164:167], v164 offset:3072
	ds_read_b128 v[172:175], v170
	ds_read_b128 v[178:181], v170 offset:1024
	ds_read_b128 v[182:185], v170 offset:2048
	ds_read_b128 v[186:189], v170 offset:3072
	s_add_u32 s10, s66, 0x80000
	s_addc_u32 s11, s67, 0
	s_mov_b32 m0, s90
	v_lshl_add_u64 v[228:229], s[10:11], 0, v[134:135]
	ds_read_b128 v[190:193], v151 offset:32768
	ds_read_b128 v[194:197], v151 offset:33792
	ds_read_b128 v[198:201], v151 offset:34816
	ds_read_b128 v[202:205], v151 offset:35840
	ds_read_b128 v[206:209], v151 offset:36864
	ds_read_b128 v[210:213], v151 offset:37888
	ds_read_b128 v[214:217], v151 offset:38912
	ds_read_b128 v[218:221], v151 offset:39936
	global_load_lds_dwordx4 v[228:229], off
	v_lshl_add_u64 v[228:229], s[10:11], 0, v[136:137]
	s_mov_b32 m0, s91
	s_nop 0
	global_load_lds_dwordx4 v[228:229], off
	s_waitcnt vmcnt(8)
	s_waitcnt lgkmcnt(0)
	s_barrier
	s_setprio 1
	v_mfma_f32_16x16x32_bf16 v[124:127], v[152:155], v[190:193], v[124:127]
	v_mfma_f32_16x16x32_bf16 v[116:119], v[160:163], v[190:193], v[116:119]
	v_mfma_f32_16x16x32_bf16 v[108:111], v[152:155], v[198:201], v[108:111]
	v_mfma_f32_16x16x32_bf16 v[100:103], v[160:163], v[198:201], v[100:103]
	v_mfma_f32_16x16x32_bf16 v[92:95], v[152:155], v[206:209], v[92:95]
	v_mfma_f32_16x16x32_bf16 v[84:87], v[160:163], v[206:209], v[84:87]
	v_mfma_f32_16x16x32_bf16 v[76:79], v[152:155], v[214:217], v[76:79]
	v_mfma_f32_16x16x32_bf16 v[68:71], v[160:163], v[214:217], v[68:71]
	v_mfma_f32_16x16x32_bf16 v[124:127], v[156:159], v[194:197], v[124:127]
	v_mfma_f32_16x16x32_bf16 v[116:119], v[164:167], v[194:197], v[116:119]
	v_mfma_f32_16x16x32_bf16 v[108:111], v[156:159], v[202:205], v[108:111]
	v_mfma_f32_16x16x32_bf16 v[100:103], v[164:167], v[202:205], v[100:103]
	v_mfma_f32_16x16x32_bf16 v[92:95], v[156:159], v[210:213], v[92:95]
	v_mfma_f32_16x16x32_bf16 v[84:87], v[164:167], v[210:213], v[84:87]
	v_mfma_f32_16x16x32_bf16 v[76:79], v[156:159], v[218:221], v[76:79]
	v_mfma_f32_16x16x32_bf16 v[68:71], v[164:167], v[218:221], v[68:71]
	s_setprio 0
	s_setprio 1
	v_mfma_f32_16x16x32_bf16 v[120:123], v[172:175], v[190:193], v[120:123]
	v_mfma_f32_16x16x32_bf16 v[112:115], v[182:185], v[190:193], v[112:115]
	v_mfma_f32_16x16x32_bf16 v[104:107], v[172:175], v[198:201], v[104:107]
	v_mfma_f32_16x16x32_bf16 v[96:99], v[182:185], v[198:201], v[96:99]
	v_mfma_f32_16x16x32_bf16 v[88:91], v[172:175], v[206:209], v[88:91]
	v_mfma_f32_16x16x32_bf16 v[80:83], v[182:185], v[206:209], v[80:83]
	v_mfma_f32_16x16x32_bf16 v[72:75], v[172:175], v[214:217], v[72:75]
	v_mfma_f32_16x16x32_bf16 v[64:67], v[182:185], v[214:217], v[64:67]
	v_mfma_f32_16x16x32_bf16 v[120:123], v[178:181], v[194:197], v[120:123]
	v_mfma_f32_16x16x32_bf16 v[112:115], v[186:189], v[194:197], v[112:115]
	v_mfma_f32_16x16x32_bf16 v[104:107], v[178:181], v[202:205], v[104:107]
	v_mfma_f32_16x16x32_bf16 v[96:99], v[186:189], v[202:205], v[96:99]
	v_mfma_f32_16x16x32_bf16 v[88:91], v[178:181], v[210:213], v[88:91]
	v_mfma_f32_16x16x32_bf16 v[80:83], v[186:189], v[210:213], v[80:83]
	v_mfma_f32_16x16x32_bf16 v[72:75], v[178:181], v[218:221], v[72:75]
	v_mfma_f32_16x16x32_bf16 v[64:67], v[186:189], v[218:221], v[64:67]
	s_setprio 0
	s_barrier
; #define PG8_STAGE(bufoff, gbase, voff) do { _Pragma("unroll") for (int _i = 0; _i < 2; ++_i) \
;         __builtin_amdgcn_global_load_lds((const unsigned*)((const char*)(gbase) + (voff)[_i]), (LAS unsigned*)(lds + (bufoff) + ldsw + _i * 8192), 16, 0, 0); } while (0)
; #define PG8_LDA(dst, b, h) do { _Pragma("unroll") for (int m = 0; m < 4; ++m) _Pragma("unroll") for (int k = 0; k < 2; ++k) dst[m][k] = *(const LAS bf16x8*)(lds + PG8_SA(b, h) + aoff + m * 2048 + k * 1024); } while (0)
; #define PG8_MMA(ai, bj, At, Bt) do { __builtin_amdgcn_s_setprio(1); _Pragma("unroll") for (int m = 0; m < 4; ++m) _Pragma("unroll") for (int n = 0; n < 2; ++n) _Pragma("unroll") for (int k = 0; k < 2; ++k) \
;         acc[ai][bj][m][n] = __builtin_amdgcn_mfma_f32_16x16x32_bf16(Bt[n][k], At[m][k], acc[ai][bj][m][n], 0, 0, 0); __builtin_amdgcn_s_setprio(0); } while (0)
; #define PG8_WAIT_V(n) asm volatile("s_waitcnt vmcnt(" #n ")" ::: "memory")
; #define PG8_WAIT_L(n) asm volatile("s_waitcnt lgkmcnt(" #n ")" ::: "memory")
; #define PG8_BAR __builtin_amdgcn_s_barrier()
; #define PG8_SCHED __builtin_amdgcn_sched_barrier(0)
; template <class Epi>
; __device__ __forceinline__ void gemm_phase(LAS unsigned char* lds, const Gemm g, const StaticOrder& S, const Epi& E, const int tid) {
;     ...
;             PG8_LDA(At, 1, 1); PG8_STAGE(PG8_SB(1, 0), b3, voffB); PG8_STAGE(PG8_SB(1, 1), b3 + hstep, voffB); PG8_STAGE(PG8_SA(1, 0), a3, voffA);
;             PG8_WAIT_V(8); PG8_WAIT_L(0); PG8_BAR; PG8_MMA(1, 0, At, B0); PG8_MMA(1, 1, At, B1); PG8_BAR; PG8_SCHED;
;         }
;         if (wr == 0) PG8_BAR;
	s_add_i32 s10, s46, s87
	v_lshl_add_u64 v[146:147], v[146:147], 0, s[8:9]
	s_mov_b32 m0, s10
	ds_read_b128 v[190:193], v151 offset:49152
	ds_read_b128 v[194:197], v151 offset:50176
	ds_read_b128 v[198:201], v151 offset:51200
	ds_read_b128 v[202:205], v151 offset:52224
	ds_read_b128 v[206:209], v151 offset:53248
	ds_read_b128 v[210:213], v151 offset:54272
	ds_read_b128 v[214:217], v151 offset:55296
	ds_read_b128 v[218:221], v151 offset:56320
	global_load_lds_dwordx4 v[146:147], off
	s_add_i32 m0, s10, 0x2000
	s_add_u32 s10, s64, 0x80080
	v_lshl_add_u64 v[146:147], v[168:169], 0, s[8:9]
	s_addc_u32 s11, s65, 0
	s_add_i32 s46, s47, s87
	global_load_lds_dwordx4 v[146:147], off
	v_lshl_add_u64 v[146:147], s[10:11], 0, v[128:129]
	s_mov_b32 m0, s46
	s_nop 0
	global_load_lds_dwordx4 v[146:147], off
	v_lshl_add_u64 v[146:147], s[10:11], 0, v[138:139]
	s_add_i32 m0, s46, 0x2000
	s_nop 0
	global_load_lds_dwordx4 v[146:147], off
	v_lshl_add_u64 v[146:147], v[222:223], 0, s[8:9]
	s_mov_b32 m0, s92
	s_nop 0
	global_load_lds_dwordx4 v[146:147], off
	v_lshl_add_u64 v[146:147], v[226:227], 0, s[8:9]
	s_mov_b32 m0, s93
	s_nop 0
	global_load_lds_dwordx4 v[146:147], off
	s_waitcnt vmcnt(8)
	s_waitcnt lgkmcnt(0)
	s_barrier
	s_setprio 1
	v_mfma_f32_16x16x32_bf16 v[60:63], v[152:155], v[190:193], v[60:63]
	v_mfma_f32_16x16x32_bf16 v[52:55], v[160:163], v[190:193], v[52:55]
	v_mfma_f32_16x16x32_bf16 v[44:47], v[152:155], v[198:201], v[44:47]
	v_mfma_f32_16x16x32_bf16 v[36:39], v[160:163], v[198:201], v[36:39]
	v_mfma_f32_16x16x32_bf16 v[28:31], v[152:155], v[206:209], v[28:31]
	v_mfma_f32_16x16x32_bf16 v[20:23], v[160:163], v[206:209], v[20:23]
	v_mfma_f32_16x16x32_bf16 v[12:15], v[152:155], v[214:217], v[12:15]
	v_mfma_f32_16x16x32_bf16 v[4:7], v[160:163], v[214:217], v[4:7]
	v_mfma_f32_16x16x32_bf16 v[60:63], v[156:159], v[194:197], v[60:63]
	v_mfma_f32_16x16x32_bf16 v[52:55], v[164:167], v[194:197], v[52:55]
	v_mfma_f32_16x16x32_bf16 v[44:47], v[156:159], v[202:205], v[44:47]
	v_mfma_f32_16x16x32_bf16 v[36:39], v[164:167], v[202:205], v[36:39]
	v_mfma_f32_16x16x32_bf16 v[28:31], v[156:159], v[210:213], v[28:31]
	v_mfma_f32_16x16x32_bf16 v[20:23], v[164:167], v[210:213], v[20:23]
	v_mfma_f32_16x16x32_bf16 v[12:15], v[156:159], v[218:221], v[12:15]
	v_mfma_f32_16x16x32_bf16 v[4:7], v[164:167], v[218:221], v[4:7]
	s_setprio 0
	s_setprio 1
	v_mfma_f32_16x16x32_bf16 v[56:59], v[172:175], v[190:193], v[56:59]
	v_mfma_f32_16x16x32_bf16 v[48:51], v[182:185], v[190:193], v[48:51]
	v_mfma_f32_16x16x32_bf16 v[40:43], v[172:175], v[198:201], v[40:43]
	v_mfma_f32_16x16x32_bf16 v[32:35], v[182:185], v[198:201], v[32:35]
	v_mfma_f32_16x16x32_bf16 v[24:27], v[172:175], v[206:209], v[24:27]
	v_mfma_f32_16x16x32_bf16 v[16:19], v[182:185], v[206:209], v[16:19]
	v_mfma_f32_16x16x32_bf16 v[8:11], v[172:175], v[214:217], v[8:11]
	v_mfma_f32_16x16x32_bf16 v[0:3], v[182:185], v[214:217], v[0:3]
	v_mfma_f32_16x16x32_bf16 v[56:59], v[178:181], v[194:197], v[56:59]
	v_mfma_f32_16x16x32_bf16 v[48:51], v[186:189], v[194:197], v[48:51]
	v_mfma_f32_16x16x32_bf16 v[40:43], v[178:181], v[202:205], v[40:43]
	v_mfma_f32_16x16x32_bf16 v[32:35], v[186:189], v[202:205], v[32:35]
	v_mfma_f32_16x16x32_bf16 v[24:27], v[178:181], v[210:213], v[24:27]
	v_mfma_f32_16x16x32_bf16 v[16:19], v[186:189], v[210:213], v[16:19]
	v_mfma_f32_16x16x32_bf16 v[8:11], v[178:181], v[218:221], v[8:11]
	v_mfma_f32_16x16x32_bf16 v[0:3], v[186:189], v[218:221], v[0:3]
	s_setprio 0
	s_barrier
	s_add_i32 vcc_hi, vcc_hi, 2
	s_add_u32 s97, s97, 0x100
	s_addc_u32 vcc_lo, vcc_lo, 0
	s_add_u32 s62, s62, 0x100
	s_addc_u32 s63, s63, 0
	s_cmp_gt_u32 vcc_hi, 29
	s_cbranch_scc0 .LBB0_150
	s_and_b64 vcc, exec, s[26:27]
	s_cbranch_vccz .LBB0_153
	s_barrier

; #define PG8_STAGE(bufoff, gbase, voff) do { _Pragma("unroll") for (int _i = 0; _i < 2; ++_i) \
;         __builtin_amdgcn_global_load_lds((const unsigned*)((const char*)(gbase) + (voff)[_i]), (LAS unsigned*)(lds + (bufoff) + ldsw + _i * 8192), 16, 0, 0); } while (0)
; #define PG8_LDA(dst, b, h) do { _Pragma("unroll") for (int m = 0; m < 4; ++m) _Pragma("unroll") for (int k = 0; k < 2; ++k) dst[m][k] = *(const LAS bf16x8*)(lds + PG8_SA(b, h) + aoff + m * 2048 + k * 1024); } while (0)
; #define PG8_LDB(dst, b, h) do { _Pragma("unroll") for (int n = 0; n < 2; ++n) _Pragma("unroll") for (int k = 0; k < 2; ++k) dst[n][k] = *(const LAS bf16x8*)(lds + PG8_SB(b, h) + boff + n * 2048 + k * 1024); } while (0)
; #define PG8_MMA(ai, bj, At, Bt) do { __builtin_amdgcn_s_setprio(1); _Pragma("unroll") for (int m = 0; m < 4; ++m) _Pragma("unroll") for (int n = 0; n < 2; ++n) _Pragma("unroll") for (int k = 0; k < 2; ++k) \
;         acc[ai][bj][m][n] = __builtin_amdgcn_mfma_f32_16x16x32_bf16(Bt[n][k], At[m][k], acc[ai][bj][m][n], 0, 0, 0); __builtin_amdgcn_s_setprio(0); } while (0)
; #define PG8_WAIT_V(n) asm volatile("s_waitcnt vmcnt(" #n ")" ::: "memory")
; #define PG8_BAR __builtin_amdgcn_s_barrier()
; template <class Epi>
; __device__ __forceinline__ void gemm_phase(LAS unsigned char* lds, const Gemm g, const StaticOrder& S, const Epi& E, const int tid) {
;     ...
;         const char* nA = has_next ? (const char*)g.A + (size_t)nxt.pm * tstep : cA; const char* nB = has_next ? (const char*)g.Bt + (size_t)nxt.pn * tstep : cB;
;         for (int t = 0; t < nt; t += 2) {
;             const bool last = (t == nt - 2);
;             const char* a1 = cA + (size_t)(t + 1) * kstep;
;             const char* a2 = last ? nA : cA + (size_t)(t + 2) * kstep; const char* b2 = last ? nB : cB + (size_t)(t + 2) * kstep;
;             const char* a3 = a2 + kstep; const char* b3 = b2 + kstep;
;             PG8_LDB(B0, 0, 0); PG8_LDB(B1, 0, 1); PG8_SCHED; PG8_LDA(At, 0, 0); PG8_STAGE(PG8_SA(1, 1), a1 + hstep, voffA);
;             PG8_WAIT_V(8); PG8_WAIT_L(0); PG8_BAR; PG8_MMA(0, 0, At, B0); PG8_MMA(0, 1, At, B1); PG8_BAR; PG8_SCHED;
;             PG8_LDA(At, 0, 1); PG8_STAGE(PG8_SB(0, 0), b2, voffB); PG8_STAGE(PG8_SB(0, 1), b2 + hstep, voffB); PG8_STAGE(PG8_SA(0, 0), a2, voffA);
;             PG8_WAIT_V(8); PG8_WAIT_L(0); PG8_BAR; PG8_MMA(1, 0, At, B0); PG8_MMA(1, 1, At, B1); PG8_BAR; PG8_SCHED;
.LBB0_271:
	s_add_u32 s56, s52, 0x100
	s_addc_u32 s57, s53, 0
	s_add_i32 s10, 0, 0x10000
	s_cmpk_eq_i32 s90, 0x54
	s_cselect_b32 s61, s39, s57
	s_cselect_b32 s60, s38, s56
	v_add_u32_e32 v144, s10, v147
	s_cselect_b32 s59, s51, s89
	s_cselect_b32 s58, s50, s88
	s_add_i32 s46, 0, 0x14000
	ds_read_b128 v[150:153], v144
	ds_read_b128 v[154:157], v144 offset:1024
	ds_read_b128 v[158:161], v144 offset:2048
	ds_read_b128 v[162:165], v144 offset:3072
	v_add_u32_e32 v144, s46, v147
	ds_read_b128 v[166:169], v144
	ds_read_b128 v[172:175], v144 offset:1024
	ds_read_b128 v[178:181], v144 offset:2048
	ds_read_b128 v[182:185], v144 offset:3072
	v_lshl_add_u64 v[144:145], s[52:53], 0, v[142:143]
	s_add_i32 m0, s67, 0xc000
	ds_read_b128 v[186:189], v149
	ds_read_b128 v[190:193], v149 offset:1024
	ds_read_b128 v[194:197], v149 offset:2048
	ds_read_b128 v[198:201], v149 offset:3072
	ds_read_b128 v[202:205], v149 offset:4096
	ds_read_b128 v[206:209], v149 offset:5120
	ds_read_b128 v[210:213], v149 offset:6144
	ds_read_b128 v[214:217], v149 offset:7168
	global_load_lds_dwordx4 v[144:145], off
	v_lshl_add_u64 v[144:145], s[52:53], 0, v[140:141]
	s_add_i32 m0, s67, 0xe000
	s_nop 0
	global_load_lds_dwordx4 v[144:145], off
	s_waitcnt vmcnt(8)
	s_waitcnt lgkmcnt(0)
	s_barrier
	s_setprio 1
	v_mfma_f32_16x16x32_bf16 v[124:127], v[150:153], v[186:189], v[124:127]
	v_mfma_f32_16x16x32_bf16 v[120:123], v[158:161], v[186:189], v[120:123]
	v_mfma_f32_16x16x32_bf16 v[116:119], v[150:153], v[194:197], v[116:119]
	v_mfma_f32_16x16x32_bf16 v[108:111], v[158:161], v[194:197], v[108:111]
	v_mfma_f32_16x16x32_bf16 v[100:103], v[150:153], v[202:205], v[100:103]
	v_mfma_f32_16x16x32_bf16 v[92:95], v[158:161], v[202:205], v[92:95]
	v_mfma_f32_16x16x32_bf16 v[84:87], v[150:153], v[210:213], v[84:87]
	v_mfma_f32_16x16x32_bf16 v[76:79], v[158:161], v[210:213], v[76:79]
	v_mfma_f32_16x16x32_bf16 v[124:127], v[154:157], v[190:193], v[124:127]
	v_mfma_f32_16x16x32_bf16 v[120:123], v[162:165], v[190:193], v[120:123]
	v_mfma_f32_16x16x32_bf16 v[116:119], v[154:157], v[198:201], v[116:119]
	v_mfma_f32_16x16x32_bf16 v[108:111], v[162:165], v[198:201], v[108:111]
	v_mfma_f32_16x16x32_bf16 v[100:103], v[154:157], v[206:209], v[100:103]
	v_mfma_f32_16x16x32_bf16 v[92:95], v[162:165], v[206:209], v[92:95]
	v_mfma_f32_16x16x32_bf16 v[84:87], v[154:157], v[214:217], v[84:87]
	v_mfma_f32_16x16x32_bf16 v[76:79], v[162:165], v[214:217], v[76:79]
	s_setprio 0
	s_setprio 1
	v_mfma_f32_16x16x32_bf16 v[112:115], v[166:169], v[186:189], v[112:115]
	v_mfma_f32_16x16x32_bf16 v[104:107], v[178:181], v[186:189], v[104:107]
	v_mfma_f32_16x16x32_bf16 v[96:99], v[166:169], v[194:197], v[96:99]
	v_mfma_f32_16x16x32_bf16 v[88:91], v[178:181], v[194:197], v[88:91]
	v_mfma_f32_16x16x32_bf16 v[80:83], v[166:169], v[202:205], v[80:83]
	v_mfma_f32_16x16x32_bf16 v[72:75], v[178:181], v[202:205], v[72:75]
	v_mfma_f32_16x16x32_bf16 v[68:71], v[166:169], v[210:213], v[68:71]
	v_mfma_f32_16x16x32_bf16 v[64:67], v[178:181], v[210:213], v[64:67]
	v_mfma_f32_16x16x32_bf16 v[112:115], v[172:175], v[190:193], v[112:115]
	v_mfma_f32_16x16x32_bf16 v[104:107], v[182:185], v[190:193], v[104:107]
	v_mfma_f32_16x16x32_bf16 v[96:99], v[172:175], v[198:201], v[96:99]
	v_mfma_f32_16x16x32_bf16 v[88:91], v[182:185], v[198:201], v[88:91]
	v_mfma_f32_16x16x32_bf16 v[80:83], v[172:175], v[206:209], v[80:83]
	v_mfma_f32_16x16x32_bf16 v[72:75], v[182:185], v[206:209], v[72:75]
	v_mfma_f32_16x16x32_bf16 v[68:71], v[172:175], v[214:217], v[68:71]
	v_mfma_f32_16x16x32_bf16 v[64:67], v[182:185], v[214:217], v[64:67]
	s_setprio 0
	s_barrier
	s_add_i32 s10, s10, s66
	v_lshl_add_u64 v[144:145], s[58:59], 0, v[128:129]
	s_mov_b32 m0, s10
	ds_read_b128 v[186:189], v149 offset:16384
	ds_read_b128 v[190:193], v149 offset:17408
	ds_read_b128 v[194:197], v149 offset:18432
	ds_read_b128 v[198:201], v149 offset:19456
	ds_read_b128 v[202:205], v149 offset:20480
	ds_read_b128 v[206:209], v149 offset:21504
	ds_read_b128 v[210:213], v149 offset:22528
	ds_read_b128 v[214:217], v149 offset:23552
	global_load_lds_dwordx4 v[144:145], off
	s_add_i32 m0, s10, 0x2000
	s_add_u32 s10, s58, 0x160000
	v_lshl_add_u64 v[218:219], s[58:59], 0, v[134:135]
	s_addc_u32 s11, s59, 0
	s_add_i32 s46, s46, s66
	global_load_lds_dwordx4 v[218:219], off
	v_lshl_add_u64 v[220:221], s[10:11], 0, v[128:129]
	s_mov_b32 m0, s46
	v_lshl_add_u64 v[222:223], s[60:61], 0, v[136:137]
	global_load_lds_dwordx4 v[220:221], off
	v_lshl_add_u64 v[220:221], s[10:11], 0, v[134:135]
	s_add_i32 m0, s46, 0x2000
	s_nop 0
	global_load_lds_dwordx4 v[220:221], off
	v_lshl_add_u64 v[220:221], s[60:61], 0, v[138:139]
	s_mov_b32 m0, s67
	s_nop 0
	global_load_lds_dwordx4 v[220:221], off
	s_mov_b32 m0, s68
	s_nop 0
	global_load_lds_dwordx4 v[222:223], off
	s_waitcnt vmcnt(8)
	s_waitcnt lgkmcnt(0)
	s_barrier
; #define PG8_STAGE(bufoff, gbase, voff) do { _Pragma("unroll") for (int _i = 0; _i < 2; ++_i) \
;         __builtin_amdgcn_global_load_lds((const unsigned*)((const char*)(gbase) + (voff)[_i]), (LAS unsigned*)(lds + (bufoff) + ldsw + _i * 8192), 16, 0, 0); } while (0)
; #define PG8_LDA(dst, b, h) do { _Pragma("unroll") for (int m = 0; m < 4; ++m) _Pragma("unroll") for (int k = 0; k < 2; ++k) dst[m][k] = *(const LAS bf16x8*)(lds + PG8_SA(b, h) + aoff + m * 2048 + k * 1024); } while (0)
; #define PG8_LDB(dst, b, h) do { _Pragma("unroll") for (int n = 0; n < 2; ++n) _Pragma("unroll") for (int k = 0; k < 2; ++k) dst[n][k] = *(const LAS bf16x8*)(lds + PG8_SB(b, h) + boff + n * 2048 + k * 1024); } while (0)
; #define PG8_MMA(ai, bj, At, Bt) do { __builtin_amdgcn_s_setprio(1); _Pragma("unroll") for (int m = 0; m < 4; ++m) _Pragma("unroll") for (int n = 0; n < 2; ++n) _Pragma("unroll") for (int k = 0; k < 2; ++k) \
;         acc[ai][bj][m][n] = __builtin_amdgcn_mfma_f32_16x16x32_bf16(Bt[n][k], At[m][k], acc[ai][bj][m][n], 0, 0, 0); __builtin_amdgcn_s_setprio(0); } while (0)
; #define PG8_WAIT_V(n) asm volatile("s_waitcnt vmcnt(" #n ")" ::: "memory")
; #define PG8_WAIT_L(n) asm volatile("s_waitcnt lgkmcnt(" #n ")" ::: "memory")
; #define PG8_BAR __builtin_amdgcn_s_barrier()
; #define PG8_SCHED __builtin_amdgcn_sched_barrier(0)
; template <class Epi>
; __device__ __forceinline__ void gemm_phase(LAS unsigned char* lds, const Gemm g, const StaticOrder& S, const Epi& E, const int tid) {
;     ...
;             PG8_WAIT_V(8); PG8_WAIT_L(0); PG8_BAR; PG8_MMA(1, 0, At, B0); PG8_MMA(1, 1, At, B1); PG8_BAR; PG8_SCHED;
;             PG8_LDB(B0, 1, 0); PG8_LDB(B1, 1, 1); PG8_SCHED; PG8_LDA(At, 1, 0); PG8_STAGE(PG8_SA(0, 1), a2 + hstep, voffA);
;             PG8_WAIT_V(8); PG8_WAIT_L(0); PG8_BAR; PG8_MMA(0, 0, At, B0); PG8_MMA(0, 1, At, B1); PG8_BAR; PG8_SCHED;
	s_setprio 1
	v_mfma_f32_16x16x32_bf16 v[60:63], v[150:153], v[186:189], v[60:63]
	v_mfma_f32_16x16x32_bf16 v[56:59], v[158:161], v[186:189], v[56:59]
	v_mfma_f32_16x16x32_bf16 v[52:55], v[150:153], v[194:197], v[52:55]
	v_mfma_f32_16x16x32_bf16 v[44:47], v[158:161], v[194:197], v[44:47]
	v_mfma_f32_16x16x32_bf16 v[36:39], v[150:153], v[202:205], v[36:39]
	v_mfma_f32_16x16x32_bf16 v[28:31], v[158:161], v[202:205], v[28:31]
	v_mfma_f32_16x16x32_bf16 v[20:23], v[150:153], v[210:213], v[20:23]
	v_mfma_f32_16x16x32_bf16 v[12:15], v[158:161], v[210:213], v[12:15]
	v_mfma_f32_16x16x32_bf16 v[60:63], v[154:157], v[190:193], v[60:63]
	v_mfma_f32_16x16x32_bf16 v[56:59], v[162:165], v[190:193], v[56:59]
	v_mfma_f32_16x16x32_bf16 v[52:55], v[154:157], v[198:201], v[52:55]
	v_mfma_f32_16x16x32_bf16 v[44:47], v[162:165], v[198:201], v[44:47]
	v_mfma_f32_16x16x32_bf16 v[36:39], v[154:157], v[206:209], v[36:39]
	v_mfma_f32_16x16x32_bf16 v[28:31], v[162:165], v[206:209], v[28:31]
	v_mfma_f32_16x16x32_bf16 v[20:23], v[154:157], v[214:217], v[20:23]
	v_mfma_f32_16x16x32_bf16 v[12:15], v[162:165], v[214:217], v[12:15]
	s_setprio 0
	s_setprio 1
	v_mfma_f32_16x16x32_bf16 v[48:51], v[166:169], v[186:189], v[48:51]
	v_mfma_f32_16x16x32_bf16 v[40:43], v[178:181], v[186:189], v[40:43]
	v_mfma_f32_16x16x32_bf16 v[32:35], v[166:169], v[194:197], v[32:35]
	v_mfma_f32_16x16x32_bf16 v[24:27], v[178:181], v[194:197], v[24:27]
	v_mfma_f32_16x16x32_bf16 v[16:19], v[166:169], v[202:205], v[16:19]
	v_mfma_f32_16x16x32_bf16 v[8:11], v[178:181], v[202:205], v[8:11]
	v_mfma_f32_16x16x32_bf16 v[4:7], v[166:169], v[210:213], v[4:7]
	v_mfma_f32_16x16x32_bf16 v[0:3], v[178:181], v[210:213], v[0:3]
	v_mfma_f32_16x16x32_bf16 v[48:51], v[172:175], v[190:193], v[48:51]
	v_mfma_f32_16x16x32_bf16 v[40:43], v[182:185], v[190:193], v[40:43]
	v_mfma_f32_16x16x32_bf16 v[32:35], v[172:175], v[198:201], v[32:35]
	v_mfma_f32_16x16x32_bf16 v[24:27], v[182:185], v[198:201], v[24:27]
	v_mfma_f32_16x16x32_bf16 v[16:19], v[172:175], v[206:209], v[16:19]
	v_mfma_f32_16x16x32_bf16 v[8:11], v[182:185], v[206:209], v[8:11]
	v_mfma_f32_16x16x32_bf16 v[4:7], v[172:175], v[214:217], v[4:7]
	v_mfma_f32_16x16x32_bf16 v[0:3], v[182:185], v[214:217], v[0:3]
	s_setprio 0
	s_barrier
	s_add_i32 s46, 0, 0x18000
	s_add_i32 s47, 0, 0x1c000
	v_add_u32_e32 v162, s46, v147
	v_add_u32_e32 v170, s47, v147
	ds_read_b128 v[150:153], v162
	ds_read_b128 v[154:157], v162 offset:1024
	ds_read_b128 v[158:161], v162 offset:2048
	ds_read_b128 v[162:165], v162 offset:3072
	ds_read_b128 v[166:169], v170
	ds_read_b128 v[172:175], v170 offset:1024
	ds_read_b128 v[178:181], v170 offset:2048
	ds_read_b128 v[182:185], v170 offset:3072
	s_add_u32 s10, s60, 0x160000
	s_addc_u32 s11, s61, 0
	s_mov_b32 m0, s69
	v_lshl_add_u64 v[226:227], s[10:11], 0, v[138:139]
	ds_read_b128 v[186:189], v149 offset:32768
	ds_read_b128 v[190:193], v149 offset:33792
	ds_read_b128 v[194:197], v149 offset:34816
	ds_read_b128 v[198:201], v149 offset:35840
	ds_read_b128 v[202:205], v149 offset:36864
	ds_read_b128 v[206:209], v149 offset:37888
	ds_read_b128 v[210:213], v149 offset:38912
	ds_read_b128 v[214:217], v149 offset:39936
	global_load_lds_dwordx4 v[226:227], off
	v_lshl_add_u64 v[226:227], s[10:11], 0, v[136:137]
	s_mov_b32 m0, s80
	s_nop 0
	global_load_lds_dwordx4 v[226:227], off
	s_waitcnt vmcnt(8)
	s_waitcnt lgkmcnt(0)
	s_barrier
	s_setprio 1
	v_mfma_f32_16x16x32_bf16 v[124:127], v[150:153], v[186:189], v[124:127]
	v_mfma_f32_16x16x32_bf16 v[120:123], v[158:161], v[186:189], v[120:123]
	v_mfma_f32_16x16x32_bf16 v[116:119], v[150:153], v[194:197], v[116:119]
	v_mfma_f32_16x16x32_bf16 v[108:111], v[158:161], v[194:197], v[108:111]
	v_mfma_f32_16x16x32_bf16 v[100:103], v[150:153], v[202:205], v[100:103]
	v_mfma_f32_16x16x32_bf16 v[92:95], v[158:161], v[202:205], v[92:95]
	v_mfma_f32_16x16x32_bf16 v[84:87], v[150:153], v[210:213], v[84:87]
	v_mfma_f32_16x16x32_bf16 v[76:79], v[158:161], v[210:213], v[76:79]
	v_mfma_f32_16x16x32_bf16 v[124:127], v[154:157], v[190:193], v[124:127]
	v_mfma_f32_16x16x32_bf16 v[120:123], v[162:165], v[190:193], v[120:123]
	v_mfma_f32_16x16x32_bf16 v[116:119], v[154:157], v[198:201], v[116:119]
	v_mfma_f32_16x16x32_bf16 v[108:111], v[162:165], v[198:201], v[108:111]
	v_mfma_f32_16x16x32_bf16 v[100:103], v[154:157], v[206:209], v[100:103]
	v_mfma_f32_16x16x32_bf16 v[92:95], v[162:165], v[206:209], v[92:95]
	v_mfma_f32_16x16x32_bf16 v[84:87], v[154:157], v[214:217], v[84:87]
	v_mfma_f32_16x16x32_bf16 v[76:79], v[162:165], v[214:217], v[76:79]
	s_setprio 0
	s_setprio 1
	v_mfma_f32_16x16x32_bf16 v[112:115], v[166:169], v[186:189], v[112:115]
	v_mfma_f32_16x16x32_bf16 v[104:107], v[178:181], v[186:189], v[104:107]
	v_mfma_f32_16x16x32_bf16 v[96:99], v[166:169], v[194:197], v[96:99]
	v_mfma_f32_16x16x32_bf16 v[88:91], v[178:181], v[194:197], v[88:91]
	v_mfma_f32_16x16x32_bf16 v[80:83], v[166:169], v[202:205], v[80:83]
	v_mfma_f32_16x16x32_bf16 v[72:75], v[178:181], v[202:205], v[72:75]
	v_mfma_f32_16x16x32_bf16 v[68:71], v[166:169], v[210:213], v[68:71]
	v_mfma_f32_16x16x32_bf16 v[64:67], v[178:181], v[210:213], v[64:67]
	v_mfma_f32_16x16x32_bf16 v[112:115], v[172:175], v[190:193], v[112:115]
	v_mfma_f32_16x16x32_bf16 v[104:107], v[182:185], v[190:193], v[104:107]
	v_mfma_f32_16x16x32_bf16 v[96:99], v[172:175], v[198:201], v[96:99]
	v_mfma_f32_16x16x32_bf16 v[88:91], v[182:185], v[198:201], v[88:91]
	v_mfma_f32_16x16x32_bf16 v[80:83], v[172:175], v[206:209], v[80:83]
	v_mfma_f32_16x16x32_bf16 v[72:75], v[182:185], v[206:209], v[72:75]
	v_mfma_f32_16x16x32_bf16 v[68:71], v[172:175], v[214:217], v[68:71]
	v_mfma_f32_16x16x32_bf16 v[64:67], v[182:185], v[214:217], v[64:67]
	s_setprio 0
	s_barrier
; #define PG8_STAGE(bufoff, gbase, voff) do { _Pragma("unroll") for (int _i = 0; _i < 2; ++_i) \
;         __builtin_amdgcn_global_load_lds((const unsigned*)((const char*)(gbase) + (voff)[_i]), (LAS unsigned*)(lds + (bufoff) + ldsw + _i * 8192), 16, 0, 0); } while (0)
; #define PG8_LDA(dst, b, h) do { _Pragma("unroll") for (int m = 0; m < 4; ++m) _Pragma("unroll") for (int k = 0; k < 2; ++k) dst[m][k] = *(const LAS bf16x8*)(lds + PG8_SA(b, h) + aoff + m * 2048 + k * 1024); } while (0)
; #define PG8_MMA(ai, bj, At, Bt) do { __builtin_amdgcn_s_setprio(1); _Pragma("unroll") for (int m = 0; m < 4; ++m) _Pragma("unroll") for (int n = 0; n < 2; ++n) _Pragma("unroll") for (int k = 0; k < 2; ++k) \
;         acc[ai][bj][m][n] = __builtin_amdgcn_mfma_f32_16x16x32_bf16(Bt[n][k], At[m][k], acc[ai][bj][m][n], 0, 0, 0); __builtin_amdgcn_s_setprio(0); } while (0)
; #define PG8_WAIT_V(n) asm volatile("s_waitcnt vmcnt(" #n ")" ::: "memory")
; #define PG8_WAIT_L(n) asm volatile("s_waitcnt lgkmcnt(" #n ")" ::: "memory")
; #define PG8_BAR __builtin_amdgcn_s_barrier()
; #define PG8_SCHED __builtin_amdgcn_sched_barrier(0)
; template <class Epi>
; __device__ __forceinline__ void gemm_phase(LAS unsigned char* lds, const Gemm g, const StaticOrder& S, const Epi& E, const int tid) {
;     ...
;         for (int t = 0; t < nt; t += 2) {
;     ...
;             PG8_LDA(At, 1, 1); PG8_STAGE(PG8_SB(1, 0), b3, voffB); PG8_STAGE(PG8_SB(1, 1), b3 + hstep, voffB); PG8_STAGE(PG8_SA(1, 0), a3, voffA);
;             PG8_WAIT_V(8); PG8_WAIT_L(0); PG8_BAR; PG8_MMA(1, 0, At, B0); PG8_MMA(1, 1, At, B1); PG8_BAR; PG8_SCHED;
;         }
	s_add_i32 s10, s46, s66
	v_lshl_add_u64 v[144:145], v[144:145], 0, s[8:9]
	s_mov_b32 m0, s10
	ds_read_b128 v[186:189], v149 offset:49152
	ds_read_b128 v[190:193], v149 offset:50176
	ds_read_b128 v[194:197], v149 offset:51200
	ds_read_b128 v[198:201], v149 offset:52224
	ds_read_b128 v[202:205], v149 offset:53248
	ds_read_b128 v[206:209], v149 offset:54272
	ds_read_b128 v[210:213], v149 offset:55296
	ds_read_b128 v[214:217], v149 offset:56320
	global_load_lds_dwordx4 v[144:145], off
	s_add_i32 m0, s10, 0x2000
	s_add_u32 s10, s58, 0x160080
	v_lshl_add_u64 v[144:145], v[218:219], 0, s[8:9]
	s_addc_u32 s11, s59, 0
	s_add_i32 s46, s47, s66
	global_load_lds_dwordx4 v[144:145], off
	v_lshl_add_u64 v[144:145], s[10:11], 0, v[128:129]
	s_mov_b32 m0, s46
	s_nop 0
	global_load_lds_dwordx4 v[144:145], off
	v_lshl_add_u64 v[144:145], s[10:11], 0, v[134:135]
	s_add_i32 m0, s46, 0x2000
	s_nop 0
	global_load_lds_dwordx4 v[144:145], off
	v_lshl_add_u64 v[144:145], v[220:221], 0, s[8:9]
	s_mov_b32 m0, s81
	s_nop 0
	global_load_lds_dwordx4 v[144:145], off
	v_lshl_add_u64 v[144:145], v[222:223], 0, s[8:9]
	s_mov_b32 m0, s82
	s_nop 0
	global_load_lds_dwordx4 v[144:145], off
	s_waitcnt vmcnt(8)
	s_waitcnt lgkmcnt(0)
	s_barrier
	s_setprio 1
	v_mfma_f32_16x16x32_bf16 v[60:63], v[150:153], v[186:189], v[60:63]
	v_mfma_f32_16x16x32_bf16 v[56:59], v[158:161], v[186:189], v[56:59]
	v_mfma_f32_16x16x32_bf16 v[52:55], v[150:153], v[194:197], v[52:55]
	v_mfma_f32_16x16x32_bf16 v[44:47], v[158:161], v[194:197], v[44:47]
	v_mfma_f32_16x16x32_bf16 v[36:39], v[150:153], v[202:205], v[36:39]
	v_mfma_f32_16x16x32_bf16 v[28:31], v[158:161], v[202:205], v[28:31]
	v_mfma_f32_16x16x32_bf16 v[20:23], v[150:153], v[210:213], v[20:23]
	v_mfma_f32_16x16x32_bf16 v[12:15], v[158:161], v[210:213], v[12:15]
	v_mfma_f32_16x16x32_bf16 v[60:63], v[154:157], v[190:193], v[60:63]
	v_mfma_f32_16x16x32_bf16 v[56:59], v[162:165], v[190:193], v[56:59]
	v_mfma_f32_16x16x32_bf16 v[52:55], v[154:157], v[198:201], v[52:55]
	v_mfma_f32_16x16x32_bf16 v[44:47], v[162:165], v[198:201], v[44:47]
	v_mfma_f32_16x16x32_bf16 v[36:39], v[154:157], v[206:209], v[36:39]
	v_mfma_f32_16x16x32_bf16 v[28:31], v[162:165], v[206:209], v[28:31]
	v_mfma_f32_16x16x32_bf16 v[20:23], v[154:157], v[214:217], v[20:23]
	v_mfma_f32_16x16x32_bf16 v[12:15], v[162:165], v[214:217], v[12:15]
	s_setprio 0
	s_setprio 1
	v_mfma_f32_16x16x32_bf16 v[48:51], v[166:169], v[186:189], v[48:51]
	v_mfma_f32_16x16x32_bf16 v[40:43], v[178:181], v[186:189], v[40:43]
	v_mfma_f32_16x16x32_bf16 v[32:35], v[166:169], v[194:197], v[32:35]
	v_mfma_f32_16x16x32_bf16 v[24:27], v[178:181], v[194:197], v[24:27]
	v_mfma_f32_16x16x32_bf16 v[16:19], v[166:169], v[202:205], v[16:19]
	v_mfma_f32_16x16x32_bf16 v[8:11], v[178:181], v[202:205], v[8:11]
	v_mfma_f32_16x16x32_bf16 v[4:7], v[166:169], v[210:213], v[4:7]
	v_mfma_f32_16x16x32_bf16 v[0:3], v[178:181], v[210:213], v[0:3]
	v_mfma_f32_16x16x32_bf16 v[48:51], v[172:175], v[190:193], v[48:51]
	v_mfma_f32_16x16x32_bf16 v[40:43], v[182:185], v[190:193], v[40:43]
	v_mfma_f32_16x16x32_bf16 v[32:35], v[172:175], v[198:201], v[32:35]
	v_mfma_f32_16x16x32_bf16 v[24:27], v[182:185], v[198:201], v[24:27]
	v_mfma_f32_16x16x32_bf16 v[16:19], v[172:175], v[206:209], v[16:19]
	v_mfma_f32_16x16x32_bf16 v[8:11], v[182:185], v[206:209], v[8:11]
	v_mfma_f32_16x16x32_bf16 v[4:7], v[172:175], v[214:217], v[4:7]
	v_mfma_f32_16x16x32_bf16 v[0:3], v[182:185], v[214:217], v[0:3]
	s_setprio 0
	s_barrier
	s_add_i32 s90, s90, 2
	s_add_u32 s88, s88, 0x100
	s_addc_u32 s89, s89, 0
	s_cmpk_gt_u32 s90, 0x55
	s_mov_b64 s[52:53], s[56:57]
	s_cbranch_scc0 .LBB0_271
	s_and_b64 vcc, exec, s[28:29]
	s_cbranch_vccz .LBB0_274
	s_barrier

; #define PG8_STAGE(bufoff, gbase, voff) do { _Pragma("unroll") for (int _i = 0; _i < 2; ++_i) \
;         __builtin_amdgcn_global_load_lds((const unsigned*)((const char*)(gbase) + (voff)[_i]), (LAS unsigned*)(lds + (bufoff) + ldsw + _i * 8192), 16, 0, 0); } while (0)
; #define PG8_LDA(dst, b, h) do { _Pragma("unroll") for (int m = 0; m < 4; ++m) _Pragma("unroll") for (int k = 0; k < 2; ++k) dst[m][k] = *(const LAS bf16x8*)(lds + PG8_SA(b, h) + aoff + m * 2048 + k * 1024); } while (0)
; #define PG8_LDB(dst, b, h) do { _Pragma("unroll") for (int n = 0; n < 2; ++n) _Pragma("unroll") for (int k = 0; k < 2; ++k) dst[n][k] = *(const LAS bf16x8*)(lds + PG8_SB(b, h) + boff + n * 2048 + k * 1024); } while (0)
; #define PG8_MMA(ai, bj, At, Bt) do { __builtin_amdgcn_s_setprio(1); _Pragma("unroll") for (int m = 0; m < 4; ++m) _Pragma("unroll") for (int n = 0; n < 2; ++n) _Pragma("unroll") for (int k = 0; k < 2; ++k) \
;         acc[ai][bj][m][n] = __builtin_amdgcn_mfma_f32_16x16x32_bf16(Bt[n][k], At[m][k], acc[ai][bj][m][n], 0, 0, 0); __builtin_amdgcn_s_setprio(0); } while (0)
; #define PG8_WAIT_V(n) asm volatile("s_waitcnt vmcnt(" #n ")" ::: "memory")
; #define PG8_WAIT_L(n) asm volatile("s_waitcnt lgkmcnt(" #n ")" ::: "memory")
; #define PG8_BAR __builtin_amdgcn_s_barrier()
; #define PG8_SCHED __builtin_amdgcn_sched_barrier(0)
; template <class Epi>
; __device__ __forceinline__ void gemm_phase(LAS unsigned char* lds, const Gemm g, const StaticOrder& S, const Epi& E, const int tid) {
;     ...
;         for (int t = 0; t < nt; t += 2) {
;             const bool last = (t == nt - 2);
;             const char* a1 = cA + (size_t)(t + 1) * kstep;
;             const char* a2 = last ? nA : cA + (size_t)(t + 2) * kstep; const char* b2 = last ? nB : cB + (size_t)(t + 2) * kstep;
;             const char* a3 = a2 + kstep; const char* b3 = b2 + kstep;
;             PG8_LDB(B0, 0, 0); PG8_LDB(B1, 0, 1); PG8_SCHED; PG8_LDA(At, 0, 0); PG8_STAGE(PG8_SA(1, 1), a1 + hstep, voffA);
;             PG8_WAIT_V(8); PG8_WAIT_L(0); PG8_BAR; PG8_MMA(0, 0, At, B0); PG8_MMA(0, 1, At, B1); PG8_BAR; PG8_SCHED;
;             PG8_LDA(At, 0, 1); PG8_STAGE(PG8_SB(0, 0), b2, voffB); PG8_STAGE(PG8_SB(0, 1), b2 + hstep, voffB); PG8_STAGE(PG8_SA(0, 0), a2, voffA);
;             PG8_WAIT_V(8); PG8_WAIT_L(0); PG8_BAR; PG8_MMA(1, 0, At, B0); PG8_MMA(1, 1, At, B1); PG8_BAR; PG8_SCHED;
.LBB0_382:
	ds_read_b128 v[150:153], v146
	ds_read_b128 v[154:157], v146 offset:1024
	ds_read_b128 v[158:161], v146 offset:2048
	ds_read_b128 v[162:165], v146 offset:3072
	ds_read_b128 v[166:169], v147
	ds_read_b128 v[170:173], v147 offset:1024
	ds_read_b128 v[174:177], v147 offset:2048
	ds_read_b128 v[178:181], v147 offset:3072
	s_add_u32 s46, s38, 0x100
	s_addc_u32 s47, s39, 0
	s_cmpk_eq_i32 s67, 0x54
	s_cselect_b32 s51, s29, s47
	s_cselect_b32 s50, s28, s46
	s_cselect_b32 s49, s35, s66
	s_cselect_b32 s48, s34, s65
	v_lshl_add_u64 v[140:141], s[38:39], 0, v[138:139]
	s_add_i32 m0, s30, 0xc000
	ds_read_b128 v[182:185], v148
	ds_read_b128 v[186:189], v148 offset:1024
	ds_read_b128 v[190:193], v148 offset:2048
	ds_read_b128 v[194:197], v148 offset:3072
	ds_read_b128 v[198:201], v148 offset:4096
	ds_read_b128 v[202:205], v148 offset:5120
	ds_read_b128 v[206:209], v148 offset:6144
	ds_read_b128 v[210:213], v148 offset:7168
	global_load_lds_dwordx4 v[140:141], off
	v_lshl_add_u64 v[140:141], s[38:39], 0, v[136:137]
	s_add_i32 m0, s30, 0xe000
	s_nop 0
	global_load_lds_dwordx4 v[140:141], off
	s_waitcnt vmcnt(8)
	s_waitcnt lgkmcnt(0)
	s_barrier
	s_setprio 1
	v_mfma_f32_16x16x32_bf16 v[124:127], v[150:153], v[182:185], v[124:127]
	v_mfma_f32_16x16x32_bf16 v[120:123], v[158:161], v[182:185], v[120:123]
	v_mfma_f32_16x16x32_bf16 v[116:119], v[150:153], v[190:193], v[116:119]
	v_mfma_f32_16x16x32_bf16 v[108:111], v[158:161], v[190:193], v[108:111]
	v_mfma_f32_16x16x32_bf16 v[100:103], v[150:153], v[198:201], v[100:103]
	v_mfma_f32_16x16x32_bf16 v[92:95], v[158:161], v[198:201], v[92:95]
	v_mfma_f32_16x16x32_bf16 v[84:87], v[150:153], v[206:209], v[84:87]
	v_mfma_f32_16x16x32_bf16 v[76:79], v[158:161], v[206:209], v[76:79]
	v_mfma_f32_16x16x32_bf16 v[124:127], v[154:157], v[186:189], v[124:127]
	v_mfma_f32_16x16x32_bf16 v[120:123], v[162:165], v[186:189], v[120:123]
	v_mfma_f32_16x16x32_bf16 v[116:119], v[154:157], v[194:197], v[116:119]
	v_mfma_f32_16x16x32_bf16 v[108:111], v[162:165], v[194:197], v[108:111]
	v_mfma_f32_16x16x32_bf16 v[100:103], v[154:157], v[202:205], v[100:103]
	v_mfma_f32_16x16x32_bf16 v[92:95], v[162:165], v[202:205], v[92:95]
	v_mfma_f32_16x16x32_bf16 v[84:87], v[154:157], v[210:213], v[84:87]
	v_mfma_f32_16x16x32_bf16 v[76:79], v[162:165], v[210:213], v[76:79]
	s_setprio 0
	s_setprio 1
	v_mfma_f32_16x16x32_bf16 v[112:115], v[166:169], v[182:185], v[112:115]
	v_mfma_f32_16x16x32_bf16 v[104:107], v[174:177], v[182:185], v[104:107]
	v_mfma_f32_16x16x32_bf16 v[96:99], v[166:169], v[190:193], v[96:99]
	v_mfma_f32_16x16x32_bf16 v[88:91], v[174:177], v[190:193], v[88:91]
	v_mfma_f32_16x16x32_bf16 v[80:83], v[166:169], v[198:201], v[80:83]
	v_mfma_f32_16x16x32_bf16 v[72:75], v[174:177], v[198:201], v[72:75]
	v_mfma_f32_16x16x32_bf16 v[68:71], v[166:169], v[206:209], v[68:71]
	v_mfma_f32_16x16x32_bf16 v[64:67], v[174:177], v[206:209], v[64:67]
	v_mfma_f32_16x16x32_bf16 v[112:115], v[170:173], v[186:189], v[112:115]
	v_mfma_f32_16x16x32_bf16 v[104:107], v[178:181], v[186:189], v[104:107]
	v_mfma_f32_16x16x32_bf16 v[96:99], v[170:173], v[194:197], v[96:99]
	v_mfma_f32_16x16x32_bf16 v[88:91], v[178:181], v[194:197], v[88:91]
	v_mfma_f32_16x16x32_bf16 v[80:83], v[170:173], v[202:205], v[80:83]
	v_mfma_f32_16x16x32_bf16 v[72:75], v[178:181], v[202:205], v[72:75]
	v_mfma_f32_16x16x32_bf16 v[68:71], v[170:173], v[210:213], v[68:71]
	v_mfma_f32_16x16x32_bf16 v[64:67], v[178:181], v[210:213], v[64:67]
	s_setprio 0
	s_barrier
	s_add_i32 s38, s59, s23
	v_lshl_add_u64 v[140:141], s[48:49], 0, v[132:133]
	s_mov_b32 m0, s38
	ds_read_b128 v[182:185], v148 offset:16384
	ds_read_b128 v[186:189], v148 offset:17408
	ds_read_b128 v[190:193], v148 offset:18432
	ds_read_b128 v[194:197], v148 offset:19456
	ds_read_b128 v[198:201], v148 offset:20480
	ds_read_b128 v[202:205], v148 offset:21504
	ds_read_b128 v[206:209], v148 offset:22528
	ds_read_b128 v[210:213], v148 offset:23552
	global_load_lds_dwordx4 v[140:141], off
	s_add_i32 m0, s38, 0x2000
	s_add_u32 s38, s48, 0x160000
	v_lshl_add_u64 v[214:215], s[48:49], 0, v[128:129]
	s_addc_u32 s39, s49, 0
	s_add_i32 s68, s60, s23
	global_load_lds_dwordx4 v[214:215], off
	v_lshl_add_u64 v[216:217], s[38:39], 0, v[132:133]
	s_mov_b32 m0, s68
	v_lshl_add_u64 v[218:219], s[50:51], 0, v[130:131]
	global_load_lds_dwordx4 v[216:217], off
	v_lshl_add_u64 v[216:217], s[38:39], 0, v[128:129]
	s_add_i32 m0, s68, 0x2000
	s_nop 0
	global_load_lds_dwordx4 v[216:217], off
	v_lshl_add_u64 v[216:217], s[50:51], 0, v[134:135]
	s_mov_b32 m0, s30
	s_nop 0
	global_load_lds_dwordx4 v[216:217], off
	s_mov_b32 m0, s31
	s_nop 0
	global_load_lds_dwordx4 v[218:219], off
	s_waitcnt vmcnt(8)
	s_waitcnt lgkmcnt(0)
	s_barrier
; #define PG8_STAGE(bufoff, gbase, voff) do { _Pragma("unroll") for (int _i = 0; _i < 2; ++_i) \
;         __builtin_amdgcn_global_load_lds((const unsigned*)((const char*)(gbase) + (voff)[_i]), (LAS unsigned*)(lds + (bufoff) + ldsw + _i * 8192), 16, 0, 0); } while (0)
; #define PG8_LDA(dst, b, h) do { _Pragma("unroll") for (int m = 0; m < 4; ++m) _Pragma("unroll") for (int k = 0; k < 2; ++k) dst[m][k] = *(const LAS bf16x8*)(lds + PG8_SA(b, h) + aoff + m * 2048 + k * 1024); } while (0)
; #define PG8_LDB(dst, b, h) do { _Pragma("unroll") for (int n = 0; n < 2; ++n) _Pragma("unroll") for (int k = 0; k < 2; ++k) dst[n][k] = *(const LAS bf16x8*)(lds + PG8_SB(b, h) + boff + n * 2048 + k * 1024); } while (0)
; #define PG8_MMA(ai, bj, At, Bt) do { __builtin_amdgcn_s_setprio(1); _Pragma("unroll") for (int m = 0; m < 4; ++m) _Pragma("unroll") for (int n = 0; n < 2; ++n) _Pragma("unroll") for (int k = 0; k < 2; ++k) \
;         acc[ai][bj][m][n] = __builtin_amdgcn_mfma_f32_16x16x32_bf16(Bt[n][k], At[m][k], acc[ai][bj][m][n], 0, 0, 0); __builtin_amdgcn_s_setprio(0); } while (0)
; #define PG8_WAIT_V(n) asm volatile("s_waitcnt vmcnt(" #n ")" ::: "memory")
; #define PG8_WAIT_L(n) asm volatile("s_waitcnt lgkmcnt(" #n ")" ::: "memory")
; #define PG8_BAR __builtin_amdgcn_s_barrier()
; #define PG8_SCHED __builtin_amdgcn_sched_barrier(0)
; template <class Epi>
; __device__ __forceinline__ void gemm_phase(LAS unsigned char* lds, const Gemm g, const StaticOrder& S, const Epi& E, const int tid) {
;     ...
;             PG8_WAIT_V(8); PG8_WAIT_L(0); PG8_BAR; PG8_MMA(1, 0, At, B0); PG8_MMA(1, 1, At, B1); PG8_BAR; PG8_SCHED;
;             PG8_LDB(B0, 1, 0); PG8_LDB(B1, 1, 1); PG8_SCHED; PG8_LDA(At, 1, 0); PG8_STAGE(PG8_SA(0, 1), a2 + hstep, voffA);
;             PG8_WAIT_V(8); PG8_WAIT_L(0); PG8_BAR; PG8_MMA(0, 0, At, B0); PG8_MMA(0, 1, At, B1); PG8_BAR; PG8_SCHED;
	s_setprio 1
	v_mfma_f32_16x16x32_bf16 v[60:63], v[150:153], v[182:185], v[60:63]
	v_mfma_f32_16x16x32_bf16 v[56:59], v[158:161], v[182:185], v[56:59]
	v_mfma_f32_16x16x32_bf16 v[52:55], v[150:153], v[190:193], v[52:55]
	v_mfma_f32_16x16x32_bf16 v[44:47], v[158:161], v[190:193], v[44:47]
	v_mfma_f32_16x16x32_bf16 v[36:39], v[150:153], v[198:201], v[36:39]
	v_mfma_f32_16x16x32_bf16 v[28:31], v[158:161], v[198:201], v[28:31]
	v_mfma_f32_16x16x32_bf16 v[20:23], v[150:153], v[206:209], v[20:23]
	v_mfma_f32_16x16x32_bf16 v[12:15], v[158:161], v[206:209], v[12:15]
	v_mfma_f32_16x16x32_bf16 v[60:63], v[154:157], v[186:189], v[60:63]
	v_mfma_f32_16x16x32_bf16 v[56:59], v[162:165], v[186:189], v[56:59]
	v_mfma_f32_16x16x32_bf16 v[52:55], v[154:157], v[194:197], v[52:55]
	v_mfma_f32_16x16x32_bf16 v[44:47], v[162:165], v[194:197], v[44:47]
	v_mfma_f32_16x16x32_bf16 v[36:39], v[154:157], v[202:205], v[36:39]
	v_mfma_f32_16x16x32_bf16 v[28:31], v[162:165], v[202:205], v[28:31]
	v_mfma_f32_16x16x32_bf16 v[20:23], v[154:157], v[210:213], v[20:23]
	v_mfma_f32_16x16x32_bf16 v[12:15], v[162:165], v[210:213], v[12:15]
	s_setprio 0
	s_setprio 1
	v_mfma_f32_16x16x32_bf16 v[48:51], v[166:169], v[182:185], v[48:51]
	v_mfma_f32_16x16x32_bf16 v[40:43], v[174:177], v[182:185], v[40:43]
	v_mfma_f32_16x16x32_bf16 v[32:35], v[166:169], v[190:193], v[32:35]
	v_mfma_f32_16x16x32_bf16 v[24:27], v[174:177], v[190:193], v[24:27]
	v_mfma_f32_16x16x32_bf16 v[16:19], v[166:169], v[198:201], v[16:19]
	v_mfma_f32_16x16x32_bf16 v[8:11], v[174:177], v[198:201], v[8:11]
	v_mfma_f32_16x16x32_bf16 v[4:7], v[166:169], v[206:209], v[4:7]
	v_mfma_f32_16x16x32_bf16 v[0:3], v[174:177], v[206:209], v[0:3]
	v_mfma_f32_16x16x32_bf16 v[48:51], v[170:173], v[186:189], v[48:51]
	v_mfma_f32_16x16x32_bf16 v[40:43], v[178:181], v[186:189], v[40:43]
	v_mfma_f32_16x16x32_bf16 v[32:35], v[170:173], v[194:197], v[32:35]
	v_mfma_f32_16x16x32_bf16 v[24:27], v[178:181], v[194:197], v[24:27]
	v_mfma_f32_16x16x32_bf16 v[16:19], v[170:173], v[202:205], v[16:19]
	v_mfma_f32_16x16x32_bf16 v[8:11], v[178:181], v[202:205], v[8:11]
	v_mfma_f32_16x16x32_bf16 v[4:7], v[170:173], v[210:213], v[4:7]
	v_mfma_f32_16x16x32_bf16 v[0:3], v[178:181], v[210:213], v[0:3]
	s_setprio 0
	s_barrier
	s_add_i32 s68, 0, 0x18000
	v_add_u32_e32 v149, s68, v144
	s_add_i32 s69, 0, 0x1c000
	ds_read_b128 v[150:153], v149
	ds_read_b128 v[154:157], v149 offset:1024
	ds_read_b128 v[158:161], v149 offset:2048
	ds_read_b128 v[162:165], v149 offset:3072
	v_add_u32_e32 v149, s69, v144
	ds_read_b128 v[166:169], v149
	ds_read_b128 v[170:173], v149 offset:1024
	ds_read_b128 v[174:177], v149 offset:2048
	ds_read_b128 v[178:181], v149 offset:3072
	s_add_u32 s38, s50, 0x160000
	s_addc_u32 s39, s51, 0
	s_mov_b32 m0, s52
	v_lshl_add_u64 v[220:221], s[38:39], 0, v[134:135]
	ds_read_b128 v[182:185], v148 offset:32768
	ds_read_b128 v[186:189], v148 offset:33792
	ds_read_b128 v[190:193], v148 offset:34816
	ds_read_b128 v[194:197], v148 offset:35840
	ds_read_b128 v[198:201], v148 offset:36864
	ds_read_b128 v[202:205], v148 offset:37888
	ds_read_b128 v[206:209], v148 offset:38912
	ds_read_b128 v[210:213], v148 offset:39936
	global_load_lds_dwordx4 v[220:221], off
	v_lshl_add_u64 v[220:221], s[38:39], 0, v[130:131]
	s_mov_b32 m0, s53
	s_nop 0
	global_load_lds_dwordx4 v[220:221], off
	s_waitcnt vmcnt(8)
	s_waitcnt lgkmcnt(0)
	s_barrier
	s_setprio 1
	v_mfma_f32_16x16x32_bf16 v[124:127], v[150:153], v[182:185], v[124:127]
	v_mfma_f32_16x16x32_bf16 v[120:123], v[158:161], v[182:185], v[120:123]
	v_mfma_f32_16x16x32_bf16 v[116:119], v[150:153], v[190:193], v[116:119]
	v_mfma_f32_16x16x32_bf16 v[108:111], v[158:161], v[190:193], v[108:111]
	v_mfma_f32_16x16x32_bf16 v[100:103], v[150:153], v[198:201], v[100:103]
	v_mfma_f32_16x16x32_bf16 v[92:95], v[158:161], v[198:201], v[92:95]
	v_mfma_f32_16x16x32_bf16 v[84:87], v[150:153], v[206:209], v[84:87]
	v_mfma_f32_16x16x32_bf16 v[76:79], v[158:161], v[206:209], v[76:79]
	v_mfma_f32_16x16x32_bf16 v[124:127], v[154:157], v[186:189], v[124:127]
	v_mfma_f32_16x16x32_bf16 v[120:123], v[162:165], v[186:189], v[120:123]
	v_mfma_f32_16x16x32_bf16 v[116:119], v[154:157], v[194:197], v[116:119]
	v_mfma_f32_16x16x32_bf16 v[108:111], v[162:165], v[194:197], v[108:111]
	v_mfma_f32_16x16x32_bf16 v[100:103], v[154:157], v[202:205], v[100:103]
	v_mfma_f32_16x16x32_bf16 v[92:95], v[162:165], v[202:205], v[92:95]
	v_mfma_f32_16x16x32_bf16 v[84:87], v[154:157], v[210:213], v[84:87]
	v_mfma_f32_16x16x32_bf16 v[76:79], v[162:165], v[210:213], v[76:79]
	s_setprio 0
	s_setprio 1
	v_mfma_f32_16x16x32_bf16 v[112:115], v[166:169], v[182:185], v[112:115]
	v_mfma_f32_16x16x32_bf16 v[104:107], v[174:177], v[182:185], v[104:107]
	v_mfma_f32_16x16x32_bf16 v[96:99], v[166:169], v[190:193], v[96:99]
	v_mfma_f32_16x16x32_bf16 v[88:91], v[174:177], v[190:193], v[88:91]
	v_mfma_f32_16x16x32_bf16 v[80:83], v[166:169], v[198:201], v[80:83]
	v_mfma_f32_16x16x32_bf16 v[72:75], v[174:177], v[198:201], v[72:75]
	v_mfma_f32_16x16x32_bf16 v[68:71], v[166:169], v[206:209], v[68:71]
	v_mfma_f32_16x16x32_bf16 v[64:67], v[174:177], v[206:209], v[64:67]
	v_mfma_f32_16x16x32_bf16 v[112:115], v[170:173], v[186:189], v[112:115]
	v_mfma_f32_16x16x32_bf16 v[104:107], v[178:181], v[186:189], v[104:107]
	v_mfma_f32_16x16x32_bf16 v[96:99], v[170:173], v[194:197], v[96:99]
	v_mfma_f32_16x16x32_bf16 v[88:91], v[178:181], v[194:197], v[88:91]
	v_mfma_f32_16x16x32_bf16 v[80:83], v[170:173], v[202:205], v[80:83]
	v_mfma_f32_16x16x32_bf16 v[72:75], v[178:181], v[202:205], v[72:75]
	v_mfma_f32_16x16x32_bf16 v[68:71], v[170:173], v[210:213], v[68:71]
	v_mfma_f32_16x16x32_bf16 v[64:67], v[178:181], v[210:213], v[64:67]
	s_setprio 0
	s_barrier
; #define PG8_STAGE(bufoff, gbase, voff) do { _Pragma("unroll") for (int _i = 0; _i < 2; ++_i) \
;         __builtin_amdgcn_global_load_lds((const unsigned*)((const char*)(gbase) + (voff)[_i]), (LAS unsigned*)(lds + (bufoff) + ldsw + _i * 8192), 16, 0, 0); } while (0)
; #define PG8_LDA(dst, b, h) do { _Pragma("unroll") for (int m = 0; m < 4; ++m) _Pragma("unroll") for (int k = 0; k < 2; ++k) dst[m][k] = *(const LAS bf16x8*)(lds + PG8_SA(b, h) + aoff + m * 2048 + k * 1024); } while (0)
; #define PG8_MMA(ai, bj, At, Bt) do { __builtin_amdgcn_s_setprio(1); _Pragma("unroll") for (int m = 0; m < 4; ++m) _Pragma("unroll") for (int n = 0; n < 2; ++n) _Pragma("unroll") for (int k = 0; k < 2; ++k) \
;         acc[ai][bj][m][n] = __builtin_amdgcn_mfma_f32_16x16x32_bf16(Bt[n][k], At[m][k], acc[ai][bj][m][n], 0, 0, 0); __builtin_amdgcn_s_setprio(0); } while (0)
; #define PG8_WAIT_V(n) asm volatile("s_waitcnt vmcnt(" #n ")" ::: "memory")
; #define PG8_WAIT_L(n) asm volatile("s_waitcnt lgkmcnt(" #n ")" ::: "memory")
; #define PG8_BAR __builtin_amdgcn_s_barrier()
; #define PG8_SCHED __builtin_amdgcn_sched_barrier(0)
; template <class Epi>
; __device__ __forceinline__ void gemm_phase(LAS unsigned char* lds, const Gemm g, const StaticOrder& S, const Epi& E, const int tid) {
;     ...
;         for (int t = 0; t < nt; t += 2) {
;     ...
;             PG8_LDA(At, 1, 1); PG8_STAGE(PG8_SB(1, 0), b3, voffB); PG8_STAGE(PG8_SB(1, 1), b3 + hstep, voffB); PG8_STAGE(PG8_SA(1, 0), a3, voffA);
;             PG8_WAIT_V(8); PG8_WAIT_L(0); PG8_BAR; PG8_MMA(1, 0, At, B0); PG8_MMA(1, 1, At, B1); PG8_BAR; PG8_SCHED;
;         }
	s_add_i32 s38, s68, s23
	v_lshl_add_u64 v[140:141], v[140:141], 0, s[24:25]
	s_mov_b32 m0, s38
	ds_read_b128 v[182:185], v148 offset:49152
	ds_read_b128 v[186:189], v148 offset:50176
	ds_read_b128 v[190:193], v148 offset:51200
	ds_read_b128 v[194:197], v148 offset:52224
	ds_read_b128 v[198:201], v148 offset:53248
	ds_read_b128 v[202:205], v148 offset:54272
	ds_read_b128 v[206:209], v148 offset:55296
	ds_read_b128 v[210:213], v148 offset:56320
	global_load_lds_dwordx4 v[140:141], off
	s_add_i32 m0, s38, 0x2000
	s_add_u32 s38, s48, 0x160080
	v_lshl_add_u64 v[140:141], v[214:215], 0, s[24:25]
	s_addc_u32 s39, s49, 0
	s_add_i32 s48, s69, s23
	global_load_lds_dwordx4 v[140:141], off
	v_lshl_add_u64 v[140:141], s[38:39], 0, v[132:133]
	s_mov_b32 m0, s48
	s_nop 0
	global_load_lds_dwordx4 v[140:141], off
	v_lshl_add_u64 v[140:141], s[38:39], 0, v[128:129]
	s_add_i32 m0, s48, 0x2000
	s_nop 0
	global_load_lds_dwordx4 v[140:141], off
	v_lshl_add_u64 v[140:141], v[216:217], 0, s[24:25]
	s_mov_b32 m0, s57
	s_nop 0
	global_load_lds_dwordx4 v[140:141], off
	v_lshl_add_u64 v[140:141], v[218:219], 0, s[24:25]
	s_mov_b32 m0, s58
	s_nop 0
	global_load_lds_dwordx4 v[140:141], off
	s_waitcnt vmcnt(8)
	s_waitcnt lgkmcnt(0)
	s_barrier
	s_setprio 1
	v_mfma_f32_16x16x32_bf16 v[60:63], v[150:153], v[182:185], v[60:63]
	v_mfma_f32_16x16x32_bf16 v[56:59], v[158:161], v[182:185], v[56:59]
	v_mfma_f32_16x16x32_bf16 v[52:55], v[150:153], v[190:193], v[52:55]
	v_mfma_f32_16x16x32_bf16 v[44:47], v[158:161], v[190:193], v[44:47]
	v_mfma_f32_16x16x32_bf16 v[36:39], v[150:153], v[198:201], v[36:39]
	v_mfma_f32_16x16x32_bf16 v[28:31], v[158:161], v[198:201], v[28:31]
	v_mfma_f32_16x16x32_bf16 v[20:23], v[150:153], v[206:209], v[20:23]
	v_mfma_f32_16x16x32_bf16 v[12:15], v[158:161], v[206:209], v[12:15]
	v_mfma_f32_16x16x32_bf16 v[60:63], v[154:157], v[186:189], v[60:63]
	v_mfma_f32_16x16x32_bf16 v[56:59], v[162:165], v[186:189], v[56:59]
	v_mfma_f32_16x16x32_bf16 v[52:55], v[154:157], v[194:197], v[52:55]
	v_mfma_f32_16x16x32_bf16 v[44:47], v[162:165], v[194:197], v[44:47]
	v_mfma_f32_16x16x32_bf16 v[36:39], v[154:157], v[202:205], v[36:39]
	v_mfma_f32_16x16x32_bf16 v[28:31], v[162:165], v[202:205], v[28:31]
	v_mfma_f32_16x16x32_bf16 v[20:23], v[154:157], v[210:213], v[20:23]
	v_mfma_f32_16x16x32_bf16 v[12:15], v[162:165], v[210:213], v[12:15]
	s_setprio 0
	s_setprio 1
	v_mfma_f32_16x16x32_bf16 v[48:51], v[166:169], v[182:185], v[48:51]
	v_mfma_f32_16x16x32_bf16 v[40:43], v[174:177], v[182:185], v[40:43]
	v_mfma_f32_16x16x32_bf16 v[32:35], v[166:169], v[190:193], v[32:35]
	v_mfma_f32_16x16x32_bf16 v[24:27], v[174:177], v[190:193], v[24:27]
	v_mfma_f32_16x16x32_bf16 v[16:19], v[166:169], v[198:201], v[16:19]
	v_mfma_f32_16x16x32_bf16 v[8:11], v[174:177], v[198:201], v[8:11]
	v_mfma_f32_16x16x32_bf16 v[4:7], v[166:169], v[206:209], v[4:7]
	v_mfma_f32_16x16x32_bf16 v[0:3], v[174:177], v[206:209], v[0:3]
	v_mfma_f32_16x16x32_bf16 v[48:51], v[170:173], v[186:189], v[48:51]
	v_mfma_f32_16x16x32_bf16 v[40:43], v[178:181], v[186:189], v[40:43]
	v_mfma_f32_16x16x32_bf16 v[32:35], v[170:173], v[194:197], v[32:35]
	v_mfma_f32_16x16x32_bf16 v[24:27], v[178:181], v[194:197], v[24:27]
	v_mfma_f32_16x16x32_bf16 v[16:19], v[170:173], v[202:205], v[16:19]
	v_mfma_f32_16x16x32_bf16 v[8:11], v[178:181], v[202:205], v[8:11]
	v_mfma_f32_16x16x32_bf16 v[4:7], v[170:173], v[210:213], v[4:7]
	v_mfma_f32_16x16x32_bf16 v[0:3], v[178:181], v[210:213], v[0:3]
	s_setprio 0
	s_barrier
	s_add_i32 s67, s67, 2
	s_add_u32 s65, s65, 0x100
	s_addc_u32 s66, s66, 0
	s_cmpk_gt_u32 s67, 0x55
	s_mov_b64 s[38:39], s[46:47]
	s_cbranch_scc0 .LBB0_382
	s_and_b64 vcc, exec, s[26:27]
	s_cbranch_vccz .LBB0_385
	s_barrier

; #define PG8_STAGE(bufoff, gbase, voff) do { _Pragma("unroll") for (int _i = 0; _i < 2; ++_i) \
;         __builtin_amdgcn_global_load_lds((const unsigned*)((const char*)(gbase) + (voff)[_i]), (LAS unsigned*)(lds + (bufoff) + ldsw + _i * 8192), 16, 0, 0); } while (0)
; #define PG8_LDA(dst, b, h) do { _Pragma("unroll") for (int m = 0; m < 4; ++m) _Pragma("unroll") for (int k = 0; k < 2; ++k) dst[m][k] = *(const LAS bf16x8*)(lds + PG8_SA(b, h) + aoff + m * 2048 + k * 1024); } while (0)
; #define PG8_LDB(dst, b, h) do { _Pragma("unroll") for (int n = 0; n < 2; ++n) _Pragma("unroll") for (int k = 0; k < 2; ++k) dst[n][k] = *(const LAS bf16x8*)(lds + PG8_SB(b, h) + boff + n * 2048 + k * 1024); } while (0)
; #define PG8_MMA(ai, bj, At, Bt) do { __builtin_amdgcn_s_setprio(1); _Pragma("unroll") for (int m = 0; m < 4; ++m) _Pragma("unroll") for (int n = 0; n < 2; ++n) _Pragma("unroll") for (int k = 0; k < 2; ++k) \
;         acc[ai][bj][m][n] = __builtin_amdgcn_mfma_f32_16x16x32_bf16(Bt[n][k], At[m][k], acc[ai][bj][m][n], 0, 0, 0); __builtin_amdgcn_s_setprio(0); } while (0)
; #define PG8_WAIT_V(n) asm volatile("s_waitcnt vmcnt(" #n ")" ::: "memory")
; #define PG8_WAIT_L(n) asm volatile("s_waitcnt lgkmcnt(" #n ")" ::: "memory")
; #define PG8_BAR __builtin_amdgcn_s_barrier()
; #define PG8_SCHED __builtin_amdgcn_sched_barrier(0)
; template <class Epi>
; __device__ __forceinline__ void gemm_phase(LAS unsigned char* lds, const Gemm g, const StaticOrder& S, const Epi& E, const int tid) {
;     ...
;         for (int t = 0; t < nt; t += 2) {
;             const bool last = (t == nt - 2);
;             const char* a1 = cA + (size_t)(t + 1) * kstep;
;             const char* a2 = last ? nA : cA + (size_t)(t + 2) * kstep; const char* b2 = last ? nB : cB + (size_t)(t + 2) * kstep;
;             const char* a3 = a2 + kstep; const char* b3 = b2 + kstep;
;             PG8_LDB(B0, 0, 0); PG8_LDB(B1, 0, 1); PG8_SCHED; PG8_LDA(At, 0, 0); PG8_STAGE(PG8_SA(1, 1), a1 + hstep, voffA);
;             PG8_WAIT_V(8); PG8_WAIT_L(0); PG8_BAR; PG8_MMA(0, 0, At, B0); PG8_MMA(0, 1, At, B1); PG8_BAR; PG8_SCHED;
;             PG8_LDA(At, 0, 1); PG8_STAGE(PG8_SB(0, 0), b2, voffB); PG8_STAGE(PG8_SB(0, 1), b2 + hstep, voffB); PG8_STAGE(PG8_SA(0, 0), a2, voffA);
;             PG8_WAIT_V(8); PG8_WAIT_L(0); PG8_BAR; PG8_MMA(1, 0, At, B0); PG8_MMA(1, 1, At, B1); PG8_BAR; PG8_SCHED;
.LBB0_628:
	ds_read_b128 v[152:155], v163
	ds_read_b128 v[172:175], v163 offset:1024
	ds_read_b128 v[176:179], v163 offset:2048
	ds_read_b128 v[180:183], v163 offset:3072
	ds_read_b128 v[184:187], v164
	ds_read_b128 v[188:191], v164 offset:1024
	ds_read_b128 v[192:195], v164 offset:2048
	ds_read_b128 v[196:199], v164 offset:3072
	s_add_u32 s28, s26, 0xfff80080
	s_addc_u32 s29, s27, -1
	s_cmp_eq_u32 s79, 28
	s_cselect_b32 s35, s25, s29
	s_cselect_b32 s34, s39, s28
	s_cselect_b32 s29, s53, s78
	s_cselect_b32 s28, s55, s77
	v_lshl_add_u64 v[234:235], s[26:27], 0, v[144:145]
	s_add_i32 m0, s21, 0xc000
	ds_read_b128 v[200:203], v165
	ds_read_b128 v[204:207], v165 offset:1024
	ds_read_b128 v[208:211], v165 offset:2048
	ds_read_b128 v[212:215], v165 offset:3072
	ds_read_b128 v[216:219], v165 offset:4096
	ds_read_b128 v[220:223], v165 offset:5120
	ds_read_b128 v[226:229], v165 offset:6144
	ds_read_b128 v[230:233], v165 offset:7168
	global_load_lds_dwordx4 v[234:235], off
	v_lshl_add_u64 v[234:235], s[26:27], 0, v[142:143]
	s_add_i32 m0, s21, 0xe000
	s_nop 0
	global_load_lds_dwordx4 v[234:235], off
	s_waitcnt vmcnt(8)
	s_waitcnt lgkmcnt(0)
	s_barrier
	s_setprio 1
	v_mfma_f32_16x16x32_bf16 v[124:127], v[152:155], v[200:203], v[124:127]
	v_mfma_f32_16x16x32_bf16 v[120:123], v[176:179], v[200:203], v[120:123]
	v_mfma_f32_16x16x32_bf16 v[108:111], v[152:155], v[208:211], v[108:111]
	v_mfma_f32_16x16x32_bf16 v[104:107], v[176:179], v[208:211], v[104:107]
	v_mfma_f32_16x16x32_bf16 v[92:95], v[152:155], v[216:219], v[92:95]
	v_mfma_f32_16x16x32_bf16 v[88:91], v[176:179], v[216:219], v[88:91]
	v_mfma_f32_16x16x32_bf16 v[76:79], v[152:155], v[226:229], v[76:79]
	v_mfma_f32_16x16x32_bf16 v[72:75], v[176:179], v[226:229], v[72:75]
	v_mfma_f32_16x16x32_bf16 v[124:127], v[172:175], v[204:207], v[124:127]
	v_mfma_f32_16x16x32_bf16 v[120:123], v[180:183], v[204:207], v[120:123]
	v_mfma_f32_16x16x32_bf16 v[108:111], v[172:175], v[212:215], v[108:111]
	v_mfma_f32_16x16x32_bf16 v[104:107], v[180:183], v[212:215], v[104:107]
	v_mfma_f32_16x16x32_bf16 v[92:95], v[172:175], v[220:223], v[92:95]
	v_mfma_f32_16x16x32_bf16 v[88:91], v[180:183], v[220:223], v[88:91]
	v_mfma_f32_16x16x32_bf16 v[76:79], v[172:175], v[230:233], v[76:79]
	v_mfma_f32_16x16x32_bf16 v[72:75], v[180:183], v[230:233], v[72:75]
	s_setprio 0
	s_setprio 1
	v_mfma_f32_16x16x32_bf16 v[116:119], v[184:187], v[200:203], v[116:119]
	v_mfma_f32_16x16x32_bf16 v[112:115], v[192:195], v[200:203], v[112:115]
	v_mfma_f32_16x16x32_bf16 v[100:103], v[184:187], v[208:211], v[100:103]
	v_mfma_f32_16x16x32_bf16 v[96:99], v[192:195], v[208:211], v[96:99]
	v_mfma_f32_16x16x32_bf16 v[84:87], v[184:187], v[216:219], v[84:87]
	v_mfma_f32_16x16x32_bf16 v[80:83], v[192:195], v[216:219], v[80:83]
	v_mfma_f32_16x16x32_bf16 v[68:71], v[184:187], v[226:229], v[68:71]
	v_mfma_f32_16x16x32_bf16 v[64:67], v[192:195], v[226:229], v[64:67]
	v_mfma_f32_16x16x32_bf16 v[116:119], v[188:191], v[204:207], v[116:119]
	v_mfma_f32_16x16x32_bf16 v[112:115], v[196:199], v[204:207], v[112:115]
	v_mfma_f32_16x16x32_bf16 v[100:103], v[188:191], v[212:215], v[100:103]
	v_mfma_f32_16x16x32_bf16 v[96:99], v[196:199], v[212:215], v[96:99]
	v_mfma_f32_16x16x32_bf16 v[84:87], v[188:191], v[220:223], v[84:87]
	v_mfma_f32_16x16x32_bf16 v[80:83], v[196:199], v[220:223], v[80:83]
	v_mfma_f32_16x16x32_bf16 v[68:71], v[188:191], v[230:233], v[68:71]
	v_mfma_f32_16x16x32_bf16 v[64:67], v[196:199], v[230:233], v[64:67]
	s_setprio 0
	s_barrier
	s_add_i32 s80, s65, s20
	v_lshl_add_u64 v[234:235], s[28:29], 0, v[130:131]
	s_mov_b32 m0, s80
	ds_read_b128 v[200:203], v165 offset:16384
	ds_read_b128 v[204:207], v165 offset:17408
	ds_read_b128 v[208:211], v165 offset:18432
	ds_read_b128 v[212:215], v165 offset:19456
	ds_read_b128 v[216:219], v165 offset:20480
	ds_read_b128 v[220:223], v165 offset:21504
	ds_read_b128 v[226:229], v165 offset:22528
	ds_read_b128 v[230:233], v165 offset:23552
	global_load_lds_dwordx4 v[234:235], off
	s_add_i32 m0, s80, 0x2000
	s_add_u32 s80, s28, 0x80000
	v_lshl_add_u64 v[236:237], s[28:29], 0, v[134:135]
	s_addc_u32 s81, s29, 0
	s_add_i32 s82, s66, s20
	global_load_lds_dwordx4 v[236:237], off
	v_lshl_add_u64 v[238:239], s[80:81], 0, v[130:131]
	s_mov_b32 m0, s82
	v_lshl_add_u64 v[240:241], s[34:35], 0, v[132:133]
	global_load_lds_dwordx4 v[238:239], off
	v_lshl_add_u64 v[238:239], s[80:81], 0, v[134:135]
	s_add_i32 m0, s82, 0x2000
	s_nop 0
	global_load_lds_dwordx4 v[238:239], off
	v_lshl_add_u64 v[238:239], s[34:35], 0, v[128:129]
	s_mov_b32 m0, s21
	s_nop 0
	global_load_lds_dwordx4 v[238:239], off
	s_mov_b32 m0, s23
	s_nop 0
	global_load_lds_dwordx4 v[240:241], off
	s_waitcnt vmcnt(8)
	s_waitcnt lgkmcnt(0)
	s_barrier
; #define PG8_STAGE(bufoff, gbase, voff) do { _Pragma("unroll") for (int _i = 0; _i < 2; ++_i) \
;         __builtin_amdgcn_global_load_lds((const unsigned*)((const char*)(gbase) + (voff)[_i]), (LAS unsigned*)(lds + (bufoff) + ldsw + _i * 8192), 16, 0, 0); } while (0)
; #define PG8_LDA(dst, b, h) do { _Pragma("unroll") for (int m = 0; m < 4; ++m) _Pragma("unroll") for (int k = 0; k < 2; ++k) dst[m][k] = *(const LAS bf16x8*)(lds + PG8_SA(b, h) + aoff + m * 2048 + k * 1024); } while (0)
; #define PG8_LDB(dst, b, h) do { _Pragma("unroll") for (int n = 0; n < 2; ++n) _Pragma("unroll") for (int k = 0; k < 2; ++k) dst[n][k] = *(const LAS bf16x8*)(lds + PG8_SB(b, h) + boff + n * 2048 + k * 1024); } while (0)
; #define PG8_MMA(ai, bj, At, Bt) do { __builtin_amdgcn_s_setprio(1); _Pragma("unroll") for (int m = 0; m < 4; ++m) _Pragma("unroll") for (int n = 0; n < 2; ++n) _Pragma("unroll") for (int k = 0; k < 2; ++k) \
;         acc[ai][bj][m][n] = __builtin_amdgcn_mfma_f32_16x16x32_bf16(Bt[n][k], At[m][k], acc[ai][bj][m][n], 0, 0, 0); __builtin_amdgcn_s_setprio(0); } while (0)
; #define PG8_WAIT_V(n) asm volatile("s_waitcnt vmcnt(" #n ")" ::: "memory")
; #define PG8_WAIT_L(n) asm volatile("s_waitcnt lgkmcnt(" #n ")" ::: "memory")
; #define PG8_BAR __builtin_amdgcn_s_barrier()
; #define PG8_SCHED __builtin_amdgcn_sched_barrier(0)
; template <class Epi>
; __device__ __forceinline__ void gemm_phase(LAS unsigned char* lds, const Gemm g, const StaticOrder& S, const Epi& E, const int tid) {
;     ...
;             PG8_WAIT_V(8); PG8_WAIT_L(0); PG8_BAR; PG8_MMA(1, 0, At, B0); PG8_MMA(1, 1, At, B1); PG8_BAR; PG8_SCHED;
;             PG8_LDB(B0, 1, 0); PG8_LDB(B1, 1, 1); PG8_SCHED; PG8_LDA(At, 1, 0); PG8_STAGE(PG8_SA(0, 1), a2 + hstep, voffA);
;             PG8_WAIT_V(8); PG8_WAIT_L(0); PG8_BAR; PG8_MMA(0, 0, At, B0); PG8_MMA(0, 1, At, B1); PG8_BAR; PG8_SCHED;
	s_setprio 1
	v_mfma_f32_16x16x32_bf16 v[60:63], v[152:155], v[200:203], v[60:63]
	v_mfma_f32_16x16x32_bf16 v[56:59], v[176:179], v[200:203], v[56:59]
	v_mfma_f32_16x16x32_bf16 v[44:47], v[152:155], v[208:211], v[44:47]
	v_mfma_f32_16x16x32_bf16 v[40:43], v[176:179], v[208:211], v[40:43]
	v_mfma_f32_16x16x32_bf16 v[28:31], v[152:155], v[216:219], v[28:31]
	v_mfma_f32_16x16x32_bf16 v[24:27], v[176:179], v[216:219], v[24:27]
	v_mfma_f32_16x16x32_bf16 v[12:15], v[152:155], v[226:229], v[12:15]
	v_mfma_f32_16x16x32_bf16 v[8:11], v[176:179], v[226:229], v[8:11]
	v_mfma_f32_16x16x32_bf16 v[60:63], v[172:175], v[204:207], v[60:63]
	v_mfma_f32_16x16x32_bf16 v[56:59], v[180:183], v[204:207], v[56:59]
	v_mfma_f32_16x16x32_bf16 v[44:47], v[172:175], v[212:215], v[44:47]
	v_mfma_f32_16x16x32_bf16 v[40:43], v[180:183], v[212:215], v[40:43]
	v_mfma_f32_16x16x32_bf16 v[28:31], v[172:175], v[220:223], v[28:31]
	v_mfma_f32_16x16x32_bf16 v[24:27], v[180:183], v[220:223], v[24:27]
	v_mfma_f32_16x16x32_bf16 v[12:15], v[172:175], v[230:233], v[12:15]
	v_mfma_f32_16x16x32_bf16 v[8:11], v[180:183], v[230:233], v[8:11]
	s_setprio 0
	s_setprio 1
	v_mfma_f32_16x16x32_bf16 v[52:55], v[184:187], v[200:203], v[52:55]
	v_mfma_f32_16x16x32_bf16 v[48:51], v[192:195], v[200:203], v[48:51]
	v_mfma_f32_16x16x32_bf16 v[36:39], v[184:187], v[208:211], v[36:39]
	v_mfma_f32_16x16x32_bf16 v[32:35], v[192:195], v[208:211], v[32:35]
	v_mfma_f32_16x16x32_bf16 v[20:23], v[184:187], v[216:219], v[20:23]
	v_mfma_f32_16x16x32_bf16 v[16:19], v[192:195], v[216:219], v[16:19]
	v_mfma_f32_16x16x32_bf16 v[4:7], v[184:187], v[226:229], v[4:7]
	v_mfma_f32_16x16x32_bf16 v[0:3], v[192:195], v[226:229], v[0:3]
	v_mfma_f32_16x16x32_bf16 v[52:55], v[188:191], v[204:207], v[52:55]
	v_mfma_f32_16x16x32_bf16 v[48:51], v[196:199], v[204:207], v[48:51]
	v_mfma_f32_16x16x32_bf16 v[36:39], v[188:191], v[212:215], v[36:39]
	v_mfma_f32_16x16x32_bf16 v[32:35], v[196:199], v[212:215], v[32:35]
	v_mfma_f32_16x16x32_bf16 v[20:23], v[188:191], v[220:223], v[20:23]
	v_mfma_f32_16x16x32_bf16 v[16:19], v[196:199], v[220:223], v[16:19]
	v_mfma_f32_16x16x32_bf16 v[4:7], v[188:191], v[230:233], v[4:7]
	v_mfma_f32_16x16x32_bf16 v[0:3], v[196:199], v[230:233], v[0:3]
	s_setprio 0
	s_barrier
	s_add_i32 s80, 0, 0x18000
	v_add_u32_e32 v136, s80, v159
	s_add_i32 s81, 0, 0x1c000
	ds_read_b128 v[152:155], v136
	ds_read_b128 v[172:175], v136 offset:1024
	ds_read_b128 v[176:179], v136 offset:2048
	ds_read_b128 v[180:183], v136 offset:3072
	v_add_u32_e32 v136, s81, v159
	ds_read_b128 v[184:187], v136
	ds_read_b128 v[188:191], v136 offset:1024
	ds_read_b128 v[192:195], v136 offset:2048
	ds_read_b128 v[196:199], v136 offset:3072
	s_add_u32 s34, s34, 0x80000
	s_addc_u32 s35, s35, 0
	s_mov_b32 m0, s30
	v_lshl_add_u64 v[242:243], s[34:35], 0, v[128:129]
	ds_read_b128 v[200:203], v165 offset:32768
	ds_read_b128 v[204:207], v165 offset:33792
	ds_read_b128 v[208:211], v165 offset:34816
	ds_read_b128 v[212:215], v165 offset:35840
	ds_read_b128 v[216:219], v165 offset:36864
	ds_read_b128 v[220:223], v165 offset:37888
	ds_read_b128 v[226:229], v165 offset:38912
	ds_read_b128 v[230:233], v165 offset:39936
	global_load_lds_dwordx4 v[242:243], off
	v_lshl_add_u64 v[242:243], s[34:35], 0, v[132:133]
	s_mov_b32 m0, s31
	s_nop 0
	global_load_lds_dwordx4 v[242:243], off
	s_waitcnt vmcnt(8)
	s_waitcnt lgkmcnt(0)
	s_barrier
	s_setprio 1
	v_mfma_f32_16x16x32_bf16 v[124:127], v[152:155], v[200:203], v[124:127]
	v_mfma_f32_16x16x32_bf16 v[120:123], v[176:179], v[200:203], v[120:123]
	v_mfma_f32_16x16x32_bf16 v[108:111], v[152:155], v[208:211], v[108:111]
	v_mfma_f32_16x16x32_bf16 v[104:107], v[176:179], v[208:211], v[104:107]
	v_mfma_f32_16x16x32_bf16 v[92:95], v[152:155], v[216:219], v[92:95]
	v_mfma_f32_16x16x32_bf16 v[88:91], v[176:179], v[216:219], v[88:91]
	v_mfma_f32_16x16x32_bf16 v[76:79], v[152:155], v[226:229], v[76:79]
	v_mfma_f32_16x16x32_bf16 v[72:75], v[176:179], v[226:229], v[72:75]
	v_mfma_f32_16x16x32_bf16 v[124:127], v[172:175], v[204:207], v[124:127]
	v_mfma_f32_16x16x32_bf16 v[120:123], v[180:183], v[204:207], v[120:123]
	v_mfma_f32_16x16x32_bf16 v[108:111], v[172:175], v[212:215], v[108:111]
	v_mfma_f32_16x16x32_bf16 v[104:107], v[180:183], v[212:215], v[104:107]
	v_mfma_f32_16x16x32_bf16 v[92:95], v[172:175], v[220:223], v[92:95]
	v_mfma_f32_16x16x32_bf16 v[88:91], v[180:183], v[220:223], v[88:91]
	v_mfma_f32_16x16x32_bf16 v[76:79], v[172:175], v[230:233], v[76:79]
	v_mfma_f32_16x16x32_bf16 v[72:75], v[180:183], v[230:233], v[72:75]
	s_setprio 0
	s_setprio 1
	v_mfma_f32_16x16x32_bf16 v[116:119], v[184:187], v[200:203], v[116:119]
	v_mfma_f32_16x16x32_bf16 v[112:115], v[192:195], v[200:203], v[112:115]
	v_mfma_f32_16x16x32_bf16 v[100:103], v[184:187], v[208:211], v[100:103]
	v_mfma_f32_16x16x32_bf16 v[96:99], v[192:195], v[208:211], v[96:99]
	v_mfma_f32_16x16x32_bf16 v[84:87], v[184:187], v[216:219], v[84:87]
	v_mfma_f32_16x16x32_bf16 v[80:83], v[192:195], v[216:219], v[80:83]
	v_mfma_f32_16x16x32_bf16 v[68:71], v[184:187], v[226:229], v[68:71]
	v_mfma_f32_16x16x32_bf16 v[64:67], v[192:195], v[226:229], v[64:67]
	v_mfma_f32_16x16x32_bf16 v[116:119], v[188:191], v[204:207], v[116:119]
	v_mfma_f32_16x16x32_bf16 v[112:115], v[196:199], v[204:207], v[112:115]
	v_mfma_f32_16x16x32_bf16 v[100:103], v[188:191], v[212:215], v[100:103]
	v_mfma_f32_16x16x32_bf16 v[96:99], v[196:199], v[212:215], v[96:99]
	v_mfma_f32_16x16x32_bf16 v[84:87], v[188:191], v[220:223], v[84:87]
	v_mfma_f32_16x16x32_bf16 v[80:83], v[196:199], v[220:223], v[80:83]
	v_mfma_f32_16x16x32_bf16 v[68:71], v[188:191], v[230:233], v[68:71]
	v_mfma_f32_16x16x32_bf16 v[64:67], v[196:199], v[230:233], v[64:67]
	s_setprio 0
	s_barrier
; #define PG8_STAGE(bufoff, gbase, voff) do { _Pragma("unroll") for (int _i = 0; _i < 2; ++_i) \
;         __builtin_amdgcn_global_load_lds((const unsigned*)((const char*)(gbase) + (voff)[_i]), (LAS unsigned*)(lds + (bufoff) + ldsw + _i * 8192), 16, 0, 0); } while (0)
; #define PG8_LDA(dst, b, h) do { _Pragma("unroll") for (int m = 0; m < 4; ++m) _Pragma("unroll") for (int k = 0; k < 2; ++k) dst[m][k] = *(const LAS bf16x8*)(lds + PG8_SA(b, h) + aoff + m * 2048 + k * 1024); } while (0)
; #define PG8_MMA(ai, bj, At, Bt) do { __builtin_amdgcn_s_setprio(1); _Pragma("unroll") for (int m = 0; m < 4; ++m) _Pragma("unroll") for (int n = 0; n < 2; ++n) _Pragma("unroll") for (int k = 0; k < 2; ++k) \
;         acc[ai][bj][m][n] = __builtin_amdgcn_mfma_f32_16x16x32_bf16(Bt[n][k], At[m][k], acc[ai][bj][m][n], 0, 0, 0); __builtin_amdgcn_s_setprio(0); } while (0)
; #define PG8_WAIT_V(n) asm volatile("s_waitcnt vmcnt(" #n ")" ::: "memory")
; #define PG8_WAIT_L(n) asm volatile("s_waitcnt lgkmcnt(" #n ")" ::: "memory")
; #define PG8_BAR __builtin_amdgcn_s_barrier()
; #define PG8_SCHED __builtin_amdgcn_sched_barrier(0)
; template <class Epi>
; __device__ __forceinline__ void gemm_phase(LAS unsigned char* lds, const Gemm g, const StaticOrder& S, const Epi& E, const int tid) {
;     ...
;         for (int t = 0; t < nt; t += 2) {
;     ...
;             PG8_LDA(At, 1, 1); PG8_STAGE(PG8_SB(1, 0), b3, voffB); PG8_STAGE(PG8_SB(1, 1), b3 + hstep, voffB); PG8_STAGE(PG8_SA(1, 0), a3, voffA);
;             PG8_WAIT_V(8); PG8_WAIT_L(0); PG8_BAR; PG8_MMA(1, 0, At, B0); PG8_MMA(1, 1, At, B1); PG8_BAR; PG8_SCHED;
;         }
	s_add_i32 s34, s80, s20
	v_lshl_add_u64 v[234:235], v[234:235], 0, s[46:47]
	s_mov_b32 m0, s34
	ds_read_b128 v[200:203], v165 offset:49152
	ds_read_b128 v[204:207], v165 offset:50176
	ds_read_b128 v[208:211], v165 offset:51200
	ds_read_b128 v[212:215], v165 offset:52224
	ds_read_b128 v[216:219], v165 offset:53248
	ds_read_b128 v[220:223], v165 offset:54272
	ds_read_b128 v[226:229], v165 offset:55296
	ds_read_b128 v[230:233], v165 offset:56320
	global_load_lds_dwordx4 v[234:235], off
	s_add_i32 m0, s34, 0x2000
	s_add_u32 s28, s28, 0x80080
	v_lshl_add_u64 v[234:235], v[236:237], 0, s[46:47]
	s_addc_u32 s29, s29, 0
	s_add_i32 s34, s81, s20
	global_load_lds_dwordx4 v[234:235], off
	v_lshl_add_u64 v[234:235], s[28:29], 0, v[130:131]
	s_mov_b32 m0, s34
	s_nop 0
	global_load_lds_dwordx4 v[234:235], off
	v_lshl_add_u64 v[234:235], s[28:29], 0, v[134:135]
	s_add_i32 m0, s34, 0x2000
	s_nop 0
	global_load_lds_dwordx4 v[234:235], off
	v_lshl_add_u64 v[234:235], v[238:239], 0, s[46:47]
	s_mov_b32 m0, s61
	s_nop 0
	global_load_lds_dwordx4 v[234:235], off
	v_lshl_add_u64 v[234:235], v[240:241], 0, s[46:47]
	s_mov_b32 m0, s62
	s_nop 0
	global_load_lds_dwordx4 v[234:235], off
	s_waitcnt vmcnt(8)
	s_waitcnt lgkmcnt(0)
	s_barrier
	s_setprio 1
	v_mfma_f32_16x16x32_bf16 v[60:63], v[152:155], v[200:203], v[60:63]
	v_mfma_f32_16x16x32_bf16 v[56:59], v[176:179], v[200:203], v[56:59]
	v_mfma_f32_16x16x32_bf16 v[44:47], v[152:155], v[208:211], v[44:47]
	v_mfma_f32_16x16x32_bf16 v[40:43], v[176:179], v[208:211], v[40:43]
	v_mfma_f32_16x16x32_bf16 v[28:31], v[152:155], v[216:219], v[28:31]
	v_mfma_f32_16x16x32_bf16 v[24:27], v[176:179], v[216:219], v[24:27]
	v_mfma_f32_16x16x32_bf16 v[12:15], v[152:155], v[226:229], v[12:15]
	v_mfma_f32_16x16x32_bf16 v[8:11], v[176:179], v[226:229], v[8:11]
	v_mfma_f32_16x16x32_bf16 v[60:63], v[172:175], v[204:207], v[60:63]
	v_mfma_f32_16x16x32_bf16 v[56:59], v[180:183], v[204:207], v[56:59]
	v_mfma_f32_16x16x32_bf16 v[44:47], v[172:175], v[212:215], v[44:47]
	v_mfma_f32_16x16x32_bf16 v[40:43], v[180:183], v[212:215], v[40:43]
	v_mfma_f32_16x16x32_bf16 v[28:31], v[172:175], v[220:223], v[28:31]
	v_mfma_f32_16x16x32_bf16 v[24:27], v[180:183], v[220:223], v[24:27]
	v_mfma_f32_16x16x32_bf16 v[12:15], v[172:175], v[230:233], v[12:15]
	v_mfma_f32_16x16x32_bf16 v[8:11], v[180:183], v[230:233], v[8:11]
	s_setprio 0
	s_setprio 1
	v_mfma_f32_16x16x32_bf16 v[52:55], v[184:187], v[200:203], v[52:55]
	v_mfma_f32_16x16x32_bf16 v[48:51], v[192:195], v[200:203], v[48:51]
	v_mfma_f32_16x16x32_bf16 v[36:39], v[184:187], v[208:211], v[36:39]
	v_mfma_f32_16x16x32_bf16 v[32:35], v[192:195], v[208:211], v[32:35]
	v_mfma_f32_16x16x32_bf16 v[20:23], v[184:187], v[216:219], v[20:23]
	v_mfma_f32_16x16x32_bf16 v[16:19], v[192:195], v[216:219], v[16:19]
	v_mfma_f32_16x16x32_bf16 v[4:7], v[184:187], v[226:229], v[4:7]
	v_mfma_f32_16x16x32_bf16 v[0:3], v[192:195], v[226:229], v[0:3]
	v_mfma_f32_16x16x32_bf16 v[52:55], v[188:191], v[204:207], v[52:55]
	v_mfma_f32_16x16x32_bf16 v[48:51], v[196:199], v[204:207], v[48:51]
	v_mfma_f32_16x16x32_bf16 v[36:39], v[188:191], v[212:215], v[36:39]
	v_mfma_f32_16x16x32_bf16 v[32:35], v[196:199], v[212:215], v[32:35]
	v_mfma_f32_16x16x32_bf16 v[20:23], v[188:191], v[220:223], v[20:23]
	v_mfma_f32_16x16x32_bf16 v[16:19], v[196:199], v[220:223], v[16:19]
	v_mfma_f32_16x16x32_bf16 v[4:7], v[188:191], v[230:233], v[4:7]
	v_mfma_f32_16x16x32_bf16 v[0:3], v[196:199], v[230:233], v[0:3]
	s_setprio 0
	s_barrier
	s_add_i32 s79, s79, 2
	s_add_u32 s77, s77, 0x100
	s_addc_u32 s78, s78, 0
	s_add_u32 s26, s26, 0x100
	s_addc_u32 s27, s27, 0
	s_cmp_gt_u32 s79, 29
	s_cbranch_scc0 .LBB0_628
	s_and_b64 vcc, exec, s[48:49]
	s_cbranch_vccz .LBB0_631
	s_barrier

; #define PG8_STAGE(bufoff, gbase, voff) do { _Pragma("unroll") for (int _i = 0; _i < 2; ++_i) \
;         __builtin_amdgcn_global_load_lds((const unsigned*)((const char*)(gbase) + (voff)[_i]), (LAS unsigned*)(lds + (bufoff) + ldsw + _i * 8192), 16, 0, 0); } while (0)
; #define PG8_LDA(dst, b, h) do { _Pragma("unroll") for (int m = 0; m < 4; ++m) _Pragma("unroll") for (int k = 0; k < 2; ++k) dst[m][k] = *(const LAS bf16x8*)(lds + PG8_SA(b, h) + aoff + m * 2048 + k * 1024); } while (0)
; #define PG8_LDB(dst, b, h) do { _Pragma("unroll") for (int n = 0; n < 2; ++n) _Pragma("unroll") for (int k = 0; k < 2; ++k) dst[n][k] = *(const LAS bf16x8*)(lds + PG8_SB(b, h) + boff + n * 2048 + k * 1024); } while (0)
; #define PG8_MMA(ai, bj, At, Bt) do { __builtin_amdgcn_s_setprio(1); _Pragma("unroll") for (int m = 0; m < 4; ++m) _Pragma("unroll") for (int n = 0; n < 2; ++n) _Pragma("unroll") for (int k = 0; k < 2; ++k) \
;         acc[ai][bj][m][n] = __builtin_amdgcn_mfma_f32_16x16x32_bf16(Bt[n][k], At[m][k], acc[ai][bj][m][n], 0, 0, 0); __builtin_amdgcn_s_setprio(0); } while (0)
; #define PG8_WAIT_V(n) asm volatile("s_waitcnt vmcnt(" #n ")" ::: "memory")
; #define PG8_WAIT_L(n) asm volatile("s_waitcnt lgkmcnt(" #n ")" ::: "memory")
; #define PG8_BAR __builtin_amdgcn_s_barrier()
; #define PG8_SCHED __builtin_amdgcn_sched_barrier(0)
; template <class Epi>
; __device__ __forceinline__ void gemm_phase(LAS unsigned char* lds, const Gemm g, const StaticOrder& S, const Epi& E, const int tid) {
;     ...
;         for (int t = 0; t < nt; t += 2) {
;             const bool last = (t == nt - 2);
;             const char* a1 = cA + (size_t)(t + 1) * kstep;
;             const char* a2 = last ? nA : cA + (size_t)(t + 2) * kstep; const char* b2 = last ? nB : cB + (size_t)(t + 2) * kstep;
;             const char* a3 = a2 + kstep; const char* b3 = b2 + kstep;
;             PG8_LDB(B0, 0, 0); PG8_LDB(B1, 0, 1); PG8_SCHED; PG8_LDA(At, 0, 0); PG8_STAGE(PG8_SA(1, 1), a1 + hstep, voffA);
;             PG8_WAIT_V(8); PG8_WAIT_L(0); PG8_BAR; PG8_MMA(0, 0, At, B0); PG8_MMA(0, 1, At, B1); PG8_BAR; PG8_SCHED;
;             PG8_LDA(At, 0, 1); PG8_STAGE(PG8_SB(0, 0), b2, voffB); PG8_STAGE(PG8_SB(0, 1), b2 + hstep, voffB); PG8_STAGE(PG8_SA(0, 0), a2, voffA);
;             PG8_WAIT_V(8); PG8_WAIT_L(0); PG8_BAR; PG8_MMA(1, 0, At, B0); PG8_MMA(1, 1, At, B1); PG8_BAR; PG8_SCHED;
.LBB0_1533:
	ds_read_b128 v[154:157], v150
	ds_read_b128 v[158:161], v150 offset:1024
	ds_read_b128 v[162:165], v150 offset:2048
	ds_read_b128 v[166:169], v150 offset:3072
	ds_read_b128 v[170:173], v151
	ds_read_b128 v[174:177], v151 offset:1024
	ds_read_b128 v[178:181], v151 offset:2048
	ds_read_b128 v[182:185], v151 offset:3072
	s_add_u32 s46, s44, 0xfff80080
	s_addc_u32 s47, s45, -1
	s_cmp_eq_u32 s61, 28
	s_cselect_b32 s49, s35, s47
	s_cselect_b32 s48, s57, s46
	s_cselect_b32 s47, s29, s60
	s_cselect_b32 s46, s58, s59
	v_lshl_add_u64 v[144:145], s[44:45], 0, v[138:139]
	s_add_i32 m0, s31, 0xc000
	ds_read_b128 v[186:189], v152
	ds_read_b128 v[190:193], v152 offset:1024
	ds_read_b128 v[194:197], v152 offset:2048
	ds_read_b128 v[198:201], v152 offset:3072
	ds_read_b128 v[202:205], v152 offset:4096
	ds_read_b128 v[206:209], v152 offset:5120
	ds_read_b128 v[210:213], v152 offset:6144
	ds_read_b128 v[214:217], v152 offset:7168
	global_load_lds_dwordx4 v[144:145], off
	v_lshl_add_u64 v[144:145], s[44:45], 0, v[136:137]
	s_add_i32 m0, s31, 0xe000
	s_nop 0
	global_load_lds_dwordx4 v[144:145], off
	s_waitcnt vmcnt(8)
	s_waitcnt lgkmcnt(0)
	s_barrier
	s_setprio 1
	v_mfma_f32_16x16x32_bf16 v[124:127], v[154:157], v[186:189], v[124:127]
	v_mfma_f32_16x16x32_bf16 v[120:123], v[162:165], v[186:189], v[120:123]
	v_mfma_f32_16x16x32_bf16 v[116:119], v[154:157], v[194:197], v[116:119]
	v_mfma_f32_16x16x32_bf16 v[108:111], v[162:165], v[194:197], v[108:111]
	v_mfma_f32_16x16x32_bf16 v[100:103], v[154:157], v[202:205], v[100:103]
	v_mfma_f32_16x16x32_bf16 v[92:95], v[162:165], v[202:205], v[92:95]
	v_mfma_f32_16x16x32_bf16 v[84:87], v[154:157], v[210:213], v[84:87]
	v_mfma_f32_16x16x32_bf16 v[76:79], v[162:165], v[210:213], v[76:79]
	v_mfma_f32_16x16x32_bf16 v[124:127], v[158:161], v[190:193], v[124:127]
	v_mfma_f32_16x16x32_bf16 v[120:123], v[166:169], v[190:193], v[120:123]
	v_mfma_f32_16x16x32_bf16 v[116:119], v[158:161], v[198:201], v[116:119]
	v_mfma_f32_16x16x32_bf16 v[108:111], v[166:169], v[198:201], v[108:111]
	v_mfma_f32_16x16x32_bf16 v[100:103], v[158:161], v[206:209], v[100:103]
	v_mfma_f32_16x16x32_bf16 v[92:95], v[166:169], v[206:209], v[92:95]
	v_mfma_f32_16x16x32_bf16 v[84:87], v[158:161], v[214:217], v[84:87]
	v_mfma_f32_16x16x32_bf16 v[76:79], v[166:169], v[214:217], v[76:79]
	s_setprio 0
	s_setprio 1
	v_mfma_f32_16x16x32_bf16 v[112:115], v[170:173], v[186:189], v[112:115]
	v_mfma_f32_16x16x32_bf16 v[104:107], v[178:181], v[186:189], v[104:107]
	v_mfma_f32_16x16x32_bf16 v[96:99], v[170:173], v[194:197], v[96:99]
	v_mfma_f32_16x16x32_bf16 v[88:91], v[178:181], v[194:197], v[88:91]
	v_mfma_f32_16x16x32_bf16 v[80:83], v[170:173], v[202:205], v[80:83]
	v_mfma_f32_16x16x32_bf16 v[72:75], v[178:181], v[202:205], v[72:75]
	v_mfma_f32_16x16x32_bf16 v[68:71], v[170:173], v[210:213], v[68:71]
	v_mfma_f32_16x16x32_bf16 v[64:67], v[178:181], v[210:213], v[64:67]
	v_mfma_f32_16x16x32_bf16 v[112:115], v[174:177], v[190:193], v[112:115]
	v_mfma_f32_16x16x32_bf16 v[104:107], v[182:185], v[190:193], v[104:107]
	v_mfma_f32_16x16x32_bf16 v[96:99], v[174:177], v[198:201], v[96:99]
	v_mfma_f32_16x16x32_bf16 v[88:91], v[182:185], v[198:201], v[88:91]
	v_mfma_f32_16x16x32_bf16 v[80:83], v[174:177], v[206:209], v[80:83]
	v_mfma_f32_16x16x32_bf16 v[72:75], v[182:185], v[206:209], v[72:75]
	v_mfma_f32_16x16x32_bf16 v[68:71], v[174:177], v[214:217], v[68:71]
	v_mfma_f32_16x16x32_bf16 v[64:67], v[182:185], v[214:217], v[64:67]
	s_setprio 0
	s_barrier
	s_add_i32 s62, s54, s30
	v_lshl_add_u64 v[144:145], s[46:47], 0, v[130:131]
	s_mov_b32 m0, s62
	ds_read_b128 v[186:189], v152 offset:16384
	ds_read_b128 v[190:193], v152 offset:17408
	ds_read_b128 v[194:197], v152 offset:18432
	ds_read_b128 v[198:201], v152 offset:19456
	ds_read_b128 v[202:205], v152 offset:20480
	ds_read_b128 v[206:209], v152 offset:21504
	ds_read_b128 v[210:213], v152 offset:22528
	ds_read_b128 v[214:217], v152 offset:23552
	global_load_lds_dwordx4 v[144:145], off
	s_add_i32 m0, s62, 0x2000
	s_add_u32 s62, s46, 0x80000
	v_lshl_add_u64 v[218:219], s[46:47], 0, v[134:135]
	s_addc_u32 s63, s47, 0
	s_add_i32 s64, s55, s30
	global_load_lds_dwordx4 v[218:219], off
	v_lshl_add_u64 v[220:221], s[62:63], 0, v[130:131]
	s_mov_b32 m0, s64
	v_lshl_add_u64 v[222:223], s[48:49], 0, v[132:133]
	global_load_lds_dwordx4 v[220:221], off
	v_lshl_add_u64 v[220:221], s[62:63], 0, v[134:135]
	s_add_i32 m0, s64, 0x2000
	s_nop 0
	global_load_lds_dwordx4 v[220:221], off
	v_lshl_add_u64 v[220:221], s[48:49], 0, v[128:129]
	s_mov_b32 m0, s31
	s_nop 0
	global_load_lds_dwordx4 v[220:221], off
	s_mov_b32 m0, s39
	s_nop 0
	global_load_lds_dwordx4 v[222:223], off
	s_waitcnt vmcnt(8)
	s_waitcnt lgkmcnt(0)
	s_barrier
; #define PG8_STAGE(bufoff, gbase, voff) do { _Pragma("unroll") for (int _i = 0; _i < 2; ++_i) \
;         __builtin_amdgcn_global_load_lds((const unsigned*)((const char*)(gbase) + (voff)[_i]), (LAS unsigned*)(lds + (bufoff) + ldsw + _i * 8192), 16, 0, 0); } while (0)
; #define PG8_LDA(dst, b, h) do { _Pragma("unroll") for (int m = 0; m < 4; ++m) _Pragma("unroll") for (int k = 0; k < 2; ++k) dst[m][k] = *(const LAS bf16x8*)(lds + PG8_SA(b, h) + aoff + m * 2048 + k * 1024); } while (0)
; #define PG8_LDB(dst, b, h) do { _Pragma("unroll") for (int n = 0; n < 2; ++n) _Pragma("unroll") for (int k = 0; k < 2; ++k) dst[n][k] = *(const LAS bf16x8*)(lds + PG8_SB(b, h) + boff + n * 2048 + k * 1024); } while (0)
; #define PG8_MMA(ai, bj, At, Bt) do { __builtin_amdgcn_s_setprio(1); _Pragma("unroll") for (int m = 0; m < 4; ++m) _Pragma("unroll") for (int n = 0; n < 2; ++n) _Pragma("unroll") for (int k = 0; k < 2; ++k) \
;         acc[ai][bj][m][n] = __builtin_amdgcn_mfma_f32_16x16x32_bf16(Bt[n][k], At[m][k], acc[ai][bj][m][n], 0, 0, 0); __builtin_amdgcn_s_setprio(0); } while (0)
; #define PG8_WAIT_V(n) asm volatile("s_waitcnt vmcnt(" #n ")" ::: "memory")
; #define PG8_WAIT_L(n) asm volatile("s_waitcnt lgkmcnt(" #n ")" ::: "memory")
; #define PG8_BAR __builtin_amdgcn_s_barrier()
; #define PG8_SCHED __builtin_amdgcn_sched_barrier(0)
; template <class Epi>
; __device__ __forceinline__ void gemm_phase(LAS unsigned char* lds, const Gemm g, const StaticOrder& S, const Epi& E, const int tid) {
;     ...
;             PG8_WAIT_V(8); PG8_WAIT_L(0); PG8_BAR; PG8_MMA(1, 0, At, B0); PG8_MMA(1, 1, At, B1); PG8_BAR; PG8_SCHED;
;             PG8_LDB(B0, 1, 0); PG8_LDB(B1, 1, 1); PG8_SCHED; PG8_LDA(At, 1, 0); PG8_STAGE(PG8_SA(0, 1), a2 + hstep, voffA);
;             PG8_WAIT_V(8); PG8_WAIT_L(0); PG8_BAR; PG8_MMA(0, 0, At, B0); PG8_MMA(0, 1, At, B1); PG8_BAR; PG8_SCHED;
	s_setprio 1
	v_mfma_f32_16x16x32_bf16 v[60:63], v[154:157], v[186:189], v[60:63]
	v_mfma_f32_16x16x32_bf16 v[56:59], v[162:165], v[186:189], v[56:59]
	v_mfma_f32_16x16x32_bf16 v[52:55], v[154:157], v[194:197], v[52:55]
	v_mfma_f32_16x16x32_bf16 v[44:47], v[162:165], v[194:197], v[44:47]
	v_mfma_f32_16x16x32_bf16 v[36:39], v[154:157], v[202:205], v[36:39]
	v_mfma_f32_16x16x32_bf16 v[28:31], v[162:165], v[202:205], v[28:31]
	v_mfma_f32_16x16x32_bf16 v[20:23], v[154:157], v[210:213], v[20:23]
	v_mfma_f32_16x16x32_bf16 v[12:15], v[162:165], v[210:213], v[12:15]
	v_mfma_f32_16x16x32_bf16 v[60:63], v[158:161], v[190:193], v[60:63]
	v_mfma_f32_16x16x32_bf16 v[56:59], v[166:169], v[190:193], v[56:59]
	v_mfma_f32_16x16x32_bf16 v[52:55], v[158:161], v[198:201], v[52:55]
	v_mfma_f32_16x16x32_bf16 v[44:47], v[166:169], v[198:201], v[44:47]
	v_mfma_f32_16x16x32_bf16 v[36:39], v[158:161], v[206:209], v[36:39]
	v_mfma_f32_16x16x32_bf16 v[28:31], v[166:169], v[206:209], v[28:31]
	v_mfma_f32_16x16x32_bf16 v[20:23], v[158:161], v[214:217], v[20:23]
	v_mfma_f32_16x16x32_bf16 v[12:15], v[166:169], v[214:217], v[12:15]
	s_setprio 0
	s_setprio 1
	v_mfma_f32_16x16x32_bf16 v[48:51], v[170:173], v[186:189], v[48:51]
	v_mfma_f32_16x16x32_bf16 v[40:43], v[178:181], v[186:189], v[40:43]
	v_mfma_f32_16x16x32_bf16 v[32:35], v[170:173], v[194:197], v[32:35]
	v_mfma_f32_16x16x32_bf16 v[24:27], v[178:181], v[194:197], v[24:27]
	v_mfma_f32_16x16x32_bf16 v[16:19], v[170:173], v[202:205], v[16:19]
	v_mfma_f32_16x16x32_bf16 v[8:11], v[178:181], v[202:205], v[8:11]
	v_mfma_f32_16x16x32_bf16 v[4:7], v[170:173], v[210:213], v[4:7]
	v_mfma_f32_16x16x32_bf16 v[0:3], v[178:181], v[210:213], v[0:3]
	v_mfma_f32_16x16x32_bf16 v[48:51], v[174:177], v[190:193], v[48:51]
	v_mfma_f32_16x16x32_bf16 v[40:43], v[182:185], v[190:193], v[40:43]
	v_mfma_f32_16x16x32_bf16 v[32:35], v[174:177], v[198:201], v[32:35]
	v_mfma_f32_16x16x32_bf16 v[24:27], v[182:185], v[198:201], v[24:27]
	v_mfma_f32_16x16x32_bf16 v[16:19], v[174:177], v[206:209], v[16:19]
	v_mfma_f32_16x16x32_bf16 v[8:11], v[182:185], v[206:209], v[8:11]
	v_mfma_f32_16x16x32_bf16 v[4:7], v[174:177], v[214:217], v[4:7]
	v_mfma_f32_16x16x32_bf16 v[0:3], v[182:185], v[214:217], v[0:3]
	s_setprio 0
	s_barrier
	s_add_i32 s62, 0, 0x18000
	v_add_u32_e32 v153, s62, v148
	s_add_i32 s63, 0, 0x1c000
	ds_read_b128 v[154:157], v153
	ds_read_b128 v[158:161], v153 offset:1024
	ds_read_b128 v[162:165], v153 offset:2048
	ds_read_b128 v[166:169], v153 offset:3072
	v_add_u32_e32 v153, s63, v148
	ds_read_b128 v[170:173], v153
	ds_read_b128 v[174:177], v153 offset:1024
	ds_read_b128 v[178:181], v153 offset:2048
	ds_read_b128 v[182:185], v153 offset:3072
	s_add_u32 s48, s48, 0x80000
	s_addc_u32 s49, s49, 0
	s_mov_b32 m0, s50
	v_lshl_add_u64 v[226:227], s[48:49], 0, v[128:129]
	ds_read_b128 v[186:189], v152 offset:32768
	ds_read_b128 v[190:193], v152 offset:33792
	ds_read_b128 v[194:197], v152 offset:34816
	ds_read_b128 v[198:201], v152 offset:35840
	ds_read_b128 v[202:205], v152 offset:36864
	ds_read_b128 v[206:209], v152 offset:37888
	ds_read_b128 v[210:213], v152 offset:38912
	ds_read_b128 v[214:217], v152 offset:39936
	global_load_lds_dwordx4 v[226:227], off
	v_lshl_add_u64 v[226:227], s[48:49], 0, v[132:133]
	s_mov_b32 m0, s51
	s_nop 0
	global_load_lds_dwordx4 v[226:227], off
	s_waitcnt vmcnt(8)
	s_waitcnt lgkmcnt(0)
	s_barrier
	s_setprio 1
	v_mfma_f32_16x16x32_bf16 v[124:127], v[154:157], v[186:189], v[124:127]
	v_mfma_f32_16x16x32_bf16 v[120:123], v[162:165], v[186:189], v[120:123]
	v_mfma_f32_16x16x32_bf16 v[116:119], v[154:157], v[194:197], v[116:119]
	v_mfma_f32_16x16x32_bf16 v[108:111], v[162:165], v[194:197], v[108:111]
	v_mfma_f32_16x16x32_bf16 v[100:103], v[154:157], v[202:205], v[100:103]
	v_mfma_f32_16x16x32_bf16 v[92:95], v[162:165], v[202:205], v[92:95]
	v_mfma_f32_16x16x32_bf16 v[84:87], v[154:157], v[210:213], v[84:87]
	v_mfma_f32_16x16x32_bf16 v[76:79], v[162:165], v[210:213], v[76:79]
	v_mfma_f32_16x16x32_bf16 v[124:127], v[158:161], v[190:193], v[124:127]
	v_mfma_f32_16x16x32_bf16 v[120:123], v[166:169], v[190:193], v[120:123]
	v_mfma_f32_16x16x32_bf16 v[116:119], v[158:161], v[198:201], v[116:119]
	v_mfma_f32_16x16x32_bf16 v[108:111], v[166:169], v[198:201], v[108:111]
	v_mfma_f32_16x16x32_bf16 v[100:103], v[158:161], v[206:209], v[100:103]
	v_mfma_f32_16x16x32_bf16 v[92:95], v[166:169], v[206:209], v[92:95]
	v_mfma_f32_16x16x32_bf16 v[84:87], v[158:161], v[214:217], v[84:87]
	v_mfma_f32_16x16x32_bf16 v[76:79], v[166:169], v[214:217], v[76:79]
	s_setprio 0
	s_setprio 1
	v_mfma_f32_16x16x32_bf16 v[112:115], v[170:173], v[186:189], v[112:115]
	v_mfma_f32_16x16x32_bf16 v[104:107], v[178:181], v[186:189], v[104:107]
	v_mfma_f32_16x16x32_bf16 v[96:99], v[170:173], v[194:197], v[96:99]
	v_mfma_f32_16x16x32_bf16 v[88:91], v[178:181], v[194:197], v[88:91]
	v_mfma_f32_16x16x32_bf16 v[80:83], v[170:173], v[202:205], v[80:83]
	v_mfma_f32_16x16x32_bf16 v[72:75], v[178:181], v[202:205], v[72:75]
	v_mfma_f32_16x16x32_bf16 v[68:71], v[170:173], v[210:213], v[68:71]
	v_mfma_f32_16x16x32_bf16 v[64:67], v[178:181], v[210:213], v[64:67]
	v_mfma_f32_16x16x32_bf16 v[112:115], v[174:177], v[190:193], v[112:115]
	v_mfma_f32_16x16x32_bf16 v[104:107], v[182:185], v[190:193], v[104:107]
	v_mfma_f32_16x16x32_bf16 v[96:99], v[174:177], v[198:201], v[96:99]
	v_mfma_f32_16x16x32_bf16 v[88:91], v[182:185], v[198:201], v[88:91]
	v_mfma_f32_16x16x32_bf16 v[80:83], v[174:177], v[206:209], v[80:83]
	v_mfma_f32_16x16x32_bf16 v[72:75], v[182:185], v[206:209], v[72:75]
	v_mfma_f32_16x16x32_bf16 v[68:71], v[174:177], v[214:217], v[68:71]
	v_mfma_f32_16x16x32_bf16 v[64:67], v[182:185], v[214:217], v[64:67]
	s_setprio 0
	s_barrier
; #define PG8_STAGE(bufoff, gbase, voff) do { _Pragma("unroll") for (int _i = 0; _i < 2; ++_i) \
;         __builtin_amdgcn_global_load_lds((const unsigned*)((const char*)(gbase) + (voff)[_i]), (LAS unsigned*)(lds + (bufoff) + ldsw + _i * 8192), 16, 0, 0); } while (0)
; #define PG8_LDA(dst, b, h) do { _Pragma("unroll") for (int m = 0; m < 4; ++m) _Pragma("unroll") for (int k = 0; k < 2; ++k) dst[m][k] = *(const LAS bf16x8*)(lds + PG8_SA(b, h) + aoff + m * 2048 + k * 1024); } while (0)
; #define PG8_MMA(ai, bj, At, Bt) do { __builtin_amdgcn_s_setprio(1); _Pragma("unroll") for (int m = 0; m < 4; ++m) _Pragma("unroll") for (int n = 0; n < 2; ++n) _Pragma("unroll") for (int k = 0; k < 2; ++k) \
;         acc[ai][bj][m][n] = __builtin_amdgcn_mfma_f32_16x16x32_bf16(Bt[n][k], At[m][k], acc[ai][bj][m][n], 0, 0, 0); __builtin_amdgcn_s_setprio(0); } while (0)
; #define PG8_WAIT_V(n) asm volatile("s_waitcnt vmcnt(" #n ")" ::: "memory")
; #define PG8_WAIT_L(n) asm volatile("s_waitcnt lgkmcnt(" #n ")" ::: "memory")
; #define PG8_BAR __builtin_amdgcn_s_barrier()
; #define PG8_SCHED __builtin_amdgcn_sched_barrier(0)
; template <class Epi>
; __device__ __forceinline__ void gemm_phase(LAS unsigned char* lds, const Gemm g, const StaticOrder& S, const Epi& E, const int tid) {
;     ...
;         for (int t = 0; t < nt; t += 2) {
;     ...
;             PG8_LDA(At, 1, 1); PG8_STAGE(PG8_SB(1, 0), b3, voffB); PG8_STAGE(PG8_SB(1, 1), b3 + hstep, voffB); PG8_STAGE(PG8_SA(1, 0), a3, voffA);
;             PG8_WAIT_V(8); PG8_WAIT_L(0); PG8_BAR; PG8_MMA(1, 0, At, B0); PG8_MMA(1, 1, At, B1); PG8_BAR; PG8_SCHED;
;         }
	s_add_i32 s48, s62, s30
	v_lshl_add_u64 v[144:145], v[144:145], 0, s[24:25]
	s_mov_b32 m0, s48
	ds_read_b128 v[186:189], v152 offset:49152
	ds_read_b128 v[190:193], v152 offset:50176
	ds_read_b128 v[194:197], v152 offset:51200
	ds_read_b128 v[198:201], v152 offset:52224
	ds_read_b128 v[202:205], v152 offset:53248
	ds_read_b128 v[206:209], v152 offset:54272
	ds_read_b128 v[210:213], v152 offset:55296
	ds_read_b128 v[214:217], v152 offset:56320
	global_load_lds_dwordx4 v[144:145], off
	s_add_i32 m0, s48, 0x2000
	s_add_u32 s46, s46, 0x80080
	v_lshl_add_u64 v[144:145], v[218:219], 0, s[24:25]
	s_addc_u32 s47, s47, 0
	s_add_i32 s48, s63, s30
	global_load_lds_dwordx4 v[144:145], off
	v_lshl_add_u64 v[144:145], s[46:47], 0, v[130:131]
	s_mov_b32 m0, s48
	s_nop 0
	global_load_lds_dwordx4 v[144:145], off
	v_lshl_add_u64 v[144:145], s[46:47], 0, v[134:135]
	s_add_i32 m0, s48, 0x2000
	s_nop 0
	global_load_lds_dwordx4 v[144:145], off
	v_lshl_add_u64 v[144:145], v[220:221], 0, s[24:25]
	s_mov_b32 m0, s0
	s_nop 0
	global_load_lds_dwordx4 v[144:145], off
	v_lshl_add_u64 v[144:145], v[222:223], 0, s[24:25]
	s_mov_b32 m0, s53
	s_nop 0
	global_load_lds_dwordx4 v[144:145], off
	s_waitcnt vmcnt(8)
	s_waitcnt lgkmcnt(0)
	s_barrier
	s_setprio 1
	v_mfma_f32_16x16x32_bf16 v[60:63], v[154:157], v[186:189], v[60:63]
	v_mfma_f32_16x16x32_bf16 v[56:59], v[162:165], v[186:189], v[56:59]
	v_mfma_f32_16x16x32_bf16 v[52:55], v[154:157], v[194:197], v[52:55]
	v_mfma_f32_16x16x32_bf16 v[44:47], v[162:165], v[194:197], v[44:47]
	v_mfma_f32_16x16x32_bf16 v[36:39], v[154:157], v[202:205], v[36:39]
	v_mfma_f32_16x16x32_bf16 v[28:31], v[162:165], v[202:205], v[28:31]
	v_mfma_f32_16x16x32_bf16 v[20:23], v[154:157], v[210:213], v[20:23]
	v_mfma_f32_16x16x32_bf16 v[12:15], v[162:165], v[210:213], v[12:15]
	v_mfma_f32_16x16x32_bf16 v[60:63], v[158:161], v[190:193], v[60:63]
	v_mfma_f32_16x16x32_bf16 v[56:59], v[166:169], v[190:193], v[56:59]
	v_mfma_f32_16x16x32_bf16 v[52:55], v[158:161], v[198:201], v[52:55]
	v_mfma_f32_16x16x32_bf16 v[44:47], v[166:169], v[198:201], v[44:47]
	v_mfma_f32_16x16x32_bf16 v[36:39], v[158:161], v[206:209], v[36:39]
	v_mfma_f32_16x16x32_bf16 v[28:31], v[166:169], v[206:209], v[28:31]
	v_mfma_f32_16x16x32_bf16 v[20:23], v[158:161], v[214:217], v[20:23]
	v_mfma_f32_16x16x32_bf16 v[12:15], v[166:169], v[214:217], v[12:15]
	s_setprio 0
	s_setprio 1
	v_mfma_f32_16x16x32_bf16 v[48:51], v[170:173], v[186:189], v[48:51]
	v_mfma_f32_16x16x32_bf16 v[40:43], v[178:181], v[186:189], v[40:43]
	v_mfma_f32_16x16x32_bf16 v[32:35], v[170:173], v[194:197], v[32:35]
	v_mfma_f32_16x16x32_bf16 v[24:27], v[178:181], v[194:197], v[24:27]
	v_mfma_f32_16x16x32_bf16 v[16:19], v[170:173], v[202:205], v[16:19]
	v_mfma_f32_16x16x32_bf16 v[8:11], v[178:181], v[202:205], v[8:11]
	v_mfma_f32_16x16x32_bf16 v[4:7], v[170:173], v[210:213], v[4:7]
	v_mfma_f32_16x16x32_bf16 v[0:3], v[178:181], v[210:213], v[0:3]
	v_mfma_f32_16x16x32_bf16 v[48:51], v[174:177], v[190:193], v[48:51]
	v_mfma_f32_16x16x32_bf16 v[40:43], v[182:185], v[190:193], v[40:43]
	v_mfma_f32_16x16x32_bf16 v[32:35], v[174:177], v[198:201], v[32:35]
	v_mfma_f32_16x16x32_bf16 v[24:27], v[182:185], v[198:201], v[24:27]
	v_mfma_f32_16x16x32_bf16 v[16:19], v[174:177], v[206:209], v[16:19]
	v_mfma_f32_16x16x32_bf16 v[8:11], v[182:185], v[206:209], v[8:11]
	v_mfma_f32_16x16x32_bf16 v[4:7], v[174:177], v[214:217], v[4:7]
	v_mfma_f32_16x16x32_bf16 v[0:3], v[182:185], v[214:217], v[0:3]
	s_setprio 0
	s_barrier
	s_add_i32 s61, s61, 2
	s_add_u32 s59, s59, 0x100
	s_addc_u32 s60, s60, 0
	s_add_u32 s44, s44, 0x100
	s_addc_u32 s45, s45, 0
	s_cmp_gt_u32 s61, 29
	s_cbranch_scc0 .LBB0_1533
	s_and_b64 vcc, exec, s[26:27]
	s_cbranch_vccz .LBB0_1536
	s_barrier

; #define PG8_STAGE(bufoff, gbase, voff) do { _Pragma("unroll") for (int _i = 0; _i < 2; ++_i) \
;         __builtin_amdgcn_global_load_lds((const unsigned*)((const char*)(gbase) + (voff)[_i]), (LAS unsigned*)(lds + (bufoff) + ldsw + _i * 8192), 16, 0, 0); } while (0)
; #define PG8_LDA(dst, b, h) do { _Pragma("unroll") for (int m = 0; m < 4; ++m) _Pragma("unroll") for (int k = 0; k < 2; ++k) dst[m][k] = *(const LAS bf16x8*)(lds + PG8_SA(b, h) + aoff + m * 2048 + k * 1024); } while (0)
; #define PG8_LDB(dst, b, h) do { _Pragma("unroll") for (int n = 0; n < 2; ++n) _Pragma("unroll") for (int k = 0; k < 2; ++k) dst[n][k] = *(const LAS bf16x8*)(lds + PG8_SB(b, h) + boff + n * 2048 + k * 1024); } while (0)
; #define PG8_MMA(ai, bj, At, Bt) do { __builtin_amdgcn_s_setprio(1); _Pragma("unroll") for (int m = 0; m < 4; ++m) _Pragma("unroll") for (int n = 0; n < 2; ++n) _Pragma("unroll") for (int k = 0; k < 2; ++k) \
;         acc[ai][bj][m][n] = __builtin_amdgcn_mfma_f32_16x16x32_bf16(Bt[n][k], At[m][k], acc[ai][bj][m][n], 0, 0, 0); __builtin_amdgcn_s_setprio(0); } while (0)
; #define PG8_WAIT_V(n) asm volatile("s_waitcnt vmcnt(" #n ")" ::: "memory")
; #define PG8_WAIT_L(n) asm volatile("s_waitcnt lgkmcnt(" #n ")" ::: "memory")
; #define PG8_BAR __builtin_amdgcn_s_barrier()
; #define PG8_SCHED __builtin_amdgcn_sched_barrier(0)
; template <class Epi>
; __device__ __forceinline__ void gemm_phase(LAS unsigned char* lds, const Gemm g, const StaticOrder& S, const Epi& E, const int tid) {
;     ...
;         for (int t = 0; t < nt; t += 2) {
;             const bool last = (t == nt - 2);
;             const char* a1 = cA + (size_t)(t + 1) * kstep;
;             const char* a2 = last ? nA : cA + (size_t)(t + 2) * kstep; const char* b2 = last ? nB : cB + (size_t)(t + 2) * kstep;
;             const char* a3 = a2 + kstep; const char* b3 = b2 + kstep;
;             PG8_LDB(B0, 0, 0); PG8_LDB(B1, 0, 1); PG8_SCHED; PG8_LDA(At, 0, 0); PG8_STAGE(PG8_SA(1, 1), a1 + hstep, voffA);
;             PG8_WAIT_V(8); PG8_WAIT_L(0); PG8_BAR; PG8_MMA(0, 0, At, B0); PG8_MMA(0, 1, At, B1); PG8_BAR; PG8_SCHED;
;             PG8_LDA(At, 0, 1); PG8_STAGE(PG8_SB(0, 0), b2, voffB); PG8_STAGE(PG8_SB(0, 1), b2 + hstep, voffB); PG8_STAGE(PG8_SA(0, 0), a2, voffA);
;             PG8_WAIT_V(8); PG8_WAIT_L(0); PG8_BAR; PG8_MMA(1, 0, At, B0); PG8_MMA(1, 1, At, B1); PG8_BAR; PG8_SCHED;
.LBB0_1706:
	s_add_u32 s64, s62, 0xfff80080
	s_addc_u32 s65, s63, -1
	s_add_i32 s95, 0, 0x10000
	s_cmp_eq_u32 s94, 28
	s_cselect_b32 s67, s57, s65
	s_cselect_b32 s66, s90, s64
	v_add_u32_e32 v148, s95, v151
	s_cselect_b32 s65, s55, s93
	s_cselect_b32 s64, s91, s92
	s_add_i32 vcc_lo, 0, 0x14000
	ds_read_b128 v[154:157], v148
	ds_read_b128 v[162:165], v148 offset:1024
	ds_read_b128 v[166:169], v148 offset:2048
	ds_read_b128 v[170:173], v148 offset:3072
	v_add_u32_e32 v148, vcc_lo, v151
	ds_read_b128 v[174:177], v148
	ds_read_b128 v[178:181], v148 offset:1024
	ds_read_b128 v[182:185], v148 offset:2048
	ds_read_b128 v[186:189], v148 offset:3072
	v_lshl_add_u64 v[148:149], s[62:63], 0, v[146:147]
	s_add_i32 m0, s81, 0xc000
	ds_read_b128 v[190:193], v153
	ds_read_b128 v[194:197], v153 offset:1024
	ds_read_b128 v[198:201], v153 offset:2048
	ds_read_b128 v[202:205], v153 offset:3072
	ds_read_b128 v[206:209], v153 offset:4096
	ds_read_b128 v[210:213], v153 offset:5120
	ds_read_b128 v[214:217], v153 offset:6144
	ds_read_b128 v[218:221], v153 offset:7168
	global_load_lds_dwordx4 v[148:149], off
	v_lshl_add_u64 v[148:149], s[62:63], 0, v[144:145]
	s_add_i32 m0, s81, 0xe000
	s_nop 0
	global_load_lds_dwordx4 v[148:149], off
	s_waitcnt vmcnt(8)
	s_waitcnt lgkmcnt(0)
	s_barrier
	s_setprio 1
	v_mfma_f32_16x16x32_bf16 v[124:127], v[154:157], v[190:193], v[124:127]
	v_mfma_f32_16x16x32_bf16 v[116:119], v[166:169], v[190:193], v[116:119]
	v_mfma_f32_16x16x32_bf16 v[108:111], v[154:157], v[198:201], v[108:111]
	v_mfma_f32_16x16x32_bf16 v[100:103], v[166:169], v[198:201], v[100:103]
	v_mfma_f32_16x16x32_bf16 v[92:95], v[154:157], v[206:209], v[92:95]
	v_mfma_f32_16x16x32_bf16 v[84:87], v[166:169], v[206:209], v[84:87]
	v_mfma_f32_16x16x32_bf16 v[76:79], v[154:157], v[214:217], v[76:79]
	v_mfma_f32_16x16x32_bf16 v[68:71], v[166:169], v[214:217], v[68:71]
	v_mfma_f32_16x16x32_bf16 v[124:127], v[162:165], v[194:197], v[124:127]
	v_mfma_f32_16x16x32_bf16 v[116:119], v[170:173], v[194:197], v[116:119]
	v_mfma_f32_16x16x32_bf16 v[108:111], v[162:165], v[202:205], v[108:111]
	v_mfma_f32_16x16x32_bf16 v[100:103], v[170:173], v[202:205], v[100:103]
	v_mfma_f32_16x16x32_bf16 v[92:95], v[162:165], v[210:213], v[92:95]
	v_mfma_f32_16x16x32_bf16 v[84:87], v[170:173], v[210:213], v[84:87]
	v_mfma_f32_16x16x32_bf16 v[76:79], v[162:165], v[218:221], v[76:79]
	v_mfma_f32_16x16x32_bf16 v[68:71], v[170:173], v[218:221], v[68:71]
	s_setprio 0
	s_setprio 1
	v_mfma_f32_16x16x32_bf16 v[120:123], v[174:177], v[190:193], v[120:123]
	v_mfma_f32_16x16x32_bf16 v[112:115], v[182:185], v[190:193], v[112:115]
	v_mfma_f32_16x16x32_bf16 v[104:107], v[174:177], v[198:201], v[104:107]
	v_mfma_f32_16x16x32_bf16 v[96:99], v[182:185], v[198:201], v[96:99]
	v_mfma_f32_16x16x32_bf16 v[88:91], v[174:177], v[206:209], v[88:91]
	v_mfma_f32_16x16x32_bf16 v[80:83], v[182:185], v[206:209], v[80:83]
	v_mfma_f32_16x16x32_bf16 v[72:75], v[174:177], v[214:217], v[72:75]
	v_mfma_f32_16x16x32_bf16 v[64:67], v[182:185], v[214:217], v[64:67]
	v_mfma_f32_16x16x32_bf16 v[120:123], v[178:181], v[194:197], v[120:123]
	v_mfma_f32_16x16x32_bf16 v[112:115], v[186:189], v[194:197], v[112:115]
	v_mfma_f32_16x16x32_bf16 v[104:107], v[178:181], v[202:205], v[104:107]
	v_mfma_f32_16x16x32_bf16 v[96:99], v[186:189], v[202:205], v[96:99]
	v_mfma_f32_16x16x32_bf16 v[88:91], v[178:181], v[210:213], v[88:91]
	v_mfma_f32_16x16x32_bf16 v[80:83], v[186:189], v[210:213], v[80:83]
	v_mfma_f32_16x16x32_bf16 v[72:75], v[178:181], v[218:221], v[72:75]
	v_mfma_f32_16x16x32_bf16 v[64:67], v[186:189], v[218:221], v[64:67]
	s_setprio 0
	s_barrier
	s_add_i32 s95, s95, s80
	v_lshl_add_u64 v[148:149], s[64:65], 0, v[128:129]
	s_mov_b32 m0, s95
	ds_read_b128 v[190:193], v153 offset:16384
	ds_read_b128 v[194:197], v153 offset:17408
	ds_read_b128 v[198:201], v153 offset:18432
	ds_read_b128 v[202:205], v153 offset:19456
	ds_read_b128 v[206:209], v153 offset:20480
	ds_read_b128 v[210:213], v153 offset:21504
	ds_read_b128 v[214:217], v153 offset:22528
	ds_read_b128 v[218:221], v153 offset:23552
	global_load_lds_dwordx4 v[148:149], off
	s_add_i32 m0, s95, 0x2000
	s_add_u32 s96, s64, 0x80000
	v_lshl_add_u64 v[222:223], s[64:65], 0, v[138:139]
	s_addc_u32 s97, s65, 0
	s_add_i32 s95, vcc_lo, s80
	global_load_lds_dwordx4 v[222:223], off
	v_lshl_add_u64 v[226:227], s[96:97], 0, v[128:129]
	s_mov_b32 m0, s95
	v_lshl_add_u64 v[228:229], s[66:67], 0, v[140:141]
	global_load_lds_dwordx4 v[226:227], off
	v_lshl_add_u64 v[226:227], s[96:97], 0, v[138:139]
	s_add_i32 m0, s95, 0x2000
	s_nop 0
	global_load_lds_dwordx4 v[226:227], off
	v_lshl_add_u64 v[226:227], s[66:67], 0, v[142:143]
	s_mov_b32 m0, s81
	s_nop 0
	global_load_lds_dwordx4 v[226:227], off
	s_mov_b32 m0, s82
	s_nop 0
	global_load_lds_dwordx4 v[228:229], off
	s_waitcnt vmcnt(8)
	s_waitcnt lgkmcnt(0)
	s_barrier
; #define PG8_STAGE(bufoff, gbase, voff) do { _Pragma("unroll") for (int _i = 0; _i < 2; ++_i) \
;         __builtin_amdgcn_global_load_lds((const unsigned*)((const char*)(gbase) + (voff)[_i]), (LAS unsigned*)(lds + (bufoff) + ldsw + _i * 8192), 16, 0, 0); } while (0)
; #define PG8_LDA(dst, b, h) do { _Pragma("unroll") for (int m = 0; m < 4; ++m) _Pragma("unroll") for (int k = 0; k < 2; ++k) dst[m][k] = *(const LAS bf16x8*)(lds + PG8_SA(b, h) + aoff + m * 2048 + k * 1024); } while (0)
; #define PG8_LDB(dst, b, h) do { _Pragma("unroll") for (int n = 0; n < 2; ++n) _Pragma("unroll") for (int k = 0; k < 2; ++k) dst[n][k] = *(const LAS bf16x8*)(lds + PG8_SB(b, h) + boff + n * 2048 + k * 1024); } while (0)
; #define PG8_MMA(ai, bj, At, Bt) do { __builtin_amdgcn_s_setprio(1); _Pragma("unroll") for (int m = 0; m < 4; ++m) _Pragma("unroll") for (int n = 0; n < 2; ++n) _Pragma("unroll") for (int k = 0; k < 2; ++k) \
;         acc[ai][bj][m][n] = __builtin_amdgcn_mfma_f32_16x16x32_bf16(Bt[n][k], At[m][k], acc[ai][bj][m][n], 0, 0, 0); __builtin_amdgcn_s_setprio(0); } while (0)
; #define PG8_WAIT_V(n) asm volatile("s_waitcnt vmcnt(" #n ")" ::: "memory")
; #define PG8_WAIT_L(n) asm volatile("s_waitcnt lgkmcnt(" #n ")" ::: "memory")
; #define PG8_BAR __builtin_amdgcn_s_barrier()
; #define PG8_SCHED __builtin_amdgcn_sched_barrier(0)
; template <class Epi>
; __device__ __forceinline__ void gemm_phase(LAS unsigned char* lds, const Gemm g, const StaticOrder& S, const Epi& E, const int tid) {
;     ...
;             PG8_WAIT_V(8); PG8_WAIT_L(0); PG8_BAR; PG8_MMA(1, 0, At, B0); PG8_MMA(1, 1, At, B1); PG8_BAR; PG8_SCHED;
;             PG8_LDB(B0, 1, 0); PG8_LDB(B1, 1, 1); PG8_SCHED; PG8_LDA(At, 1, 0); PG8_STAGE(PG8_SA(0, 1), a2 + hstep, voffA);
;             PG8_WAIT_V(8); PG8_WAIT_L(0); PG8_BAR; PG8_MMA(0, 0, At, B0); PG8_MMA(0, 1, At, B1); PG8_BAR; PG8_SCHED;
	s_setprio 1
	v_mfma_f32_16x16x32_bf16 v[60:63], v[154:157], v[190:193], v[60:63]
	v_mfma_f32_16x16x32_bf16 v[52:55], v[166:169], v[190:193], v[52:55]
	v_mfma_f32_16x16x32_bf16 v[44:47], v[154:157], v[198:201], v[44:47]
	v_mfma_f32_16x16x32_bf16 v[36:39], v[166:169], v[198:201], v[36:39]
	v_mfma_f32_16x16x32_bf16 v[28:31], v[154:157], v[206:209], v[28:31]
	v_mfma_f32_16x16x32_bf16 v[20:23], v[166:169], v[206:209], v[20:23]
	v_mfma_f32_16x16x32_bf16 v[12:15], v[154:157], v[214:217], v[12:15]
	v_mfma_f32_16x16x32_bf16 v[4:7], v[166:169], v[214:217], v[4:7]
	v_mfma_f32_16x16x32_bf16 v[60:63], v[162:165], v[194:197], v[60:63]
	v_mfma_f32_16x16x32_bf16 v[52:55], v[170:173], v[194:197], v[52:55]
	v_mfma_f32_16x16x32_bf16 v[44:47], v[162:165], v[202:205], v[44:47]
	v_mfma_f32_16x16x32_bf16 v[36:39], v[170:173], v[202:205], v[36:39]
	v_mfma_f32_16x16x32_bf16 v[28:31], v[162:165], v[210:213], v[28:31]
	v_mfma_f32_16x16x32_bf16 v[20:23], v[170:173], v[210:213], v[20:23]
	v_mfma_f32_16x16x32_bf16 v[12:15], v[162:165], v[218:221], v[12:15]
	v_mfma_f32_16x16x32_bf16 v[4:7], v[170:173], v[218:221], v[4:7]
	s_setprio 0
	s_setprio 1
	v_mfma_f32_16x16x32_bf16 v[56:59], v[174:177], v[190:193], v[56:59]
	v_mfma_f32_16x16x32_bf16 v[48:51], v[182:185], v[190:193], v[48:51]
	v_mfma_f32_16x16x32_bf16 v[40:43], v[174:177], v[198:201], v[40:43]
	v_mfma_f32_16x16x32_bf16 v[32:35], v[182:185], v[198:201], v[32:35]
	v_mfma_f32_16x16x32_bf16 v[24:27], v[174:177], v[206:209], v[24:27]
	v_mfma_f32_16x16x32_bf16 v[16:19], v[182:185], v[206:209], v[16:19]
	v_mfma_f32_16x16x32_bf16 v[8:11], v[174:177], v[214:217], v[8:11]
	v_mfma_f32_16x16x32_bf16 v[0:3], v[182:185], v[214:217], v[0:3]
	v_mfma_f32_16x16x32_bf16 v[56:59], v[178:181], v[194:197], v[56:59]
	v_mfma_f32_16x16x32_bf16 v[48:51], v[186:189], v[194:197], v[48:51]
	v_mfma_f32_16x16x32_bf16 v[40:43], v[178:181], v[202:205], v[40:43]
	v_mfma_f32_16x16x32_bf16 v[32:35], v[186:189], v[202:205], v[32:35]
	v_mfma_f32_16x16x32_bf16 v[24:27], v[178:181], v[210:213], v[24:27]
	v_mfma_f32_16x16x32_bf16 v[16:19], v[186:189], v[210:213], v[16:19]
	v_mfma_f32_16x16x32_bf16 v[8:11], v[178:181], v[218:221], v[8:11]
	v_mfma_f32_16x16x32_bf16 v[0:3], v[186:189], v[218:221], v[0:3]
	s_setprio 0
	s_barrier
	s_add_i32 s95, 0, 0x18000
	v_add_u32_e32 v161, s95, v151
	s_add_i32 s96, 0, 0x1c000
	ds_read_b128 v[154:157], v161
	ds_read_b128 v[162:165], v161 offset:1024
	ds_read_b128 v[166:169], v161 offset:2048
	ds_read_b128 v[170:173], v161 offset:3072
	v_add_u32_e32 v161, s96, v151
	ds_read_b128 v[174:177], v161
	ds_read_b128 v[178:181], v161 offset:1024
	ds_read_b128 v[182:185], v161 offset:2048
	ds_read_b128 v[186:189], v161 offset:3072
	s_add_u32 s66, s66, 0x80000
	s_addc_u32 s67, s67, 0
	s_mov_b32 m0, s83
	v_lshl_add_u64 v[230:231], s[66:67], 0, v[142:143]
	ds_read_b128 v[190:193], v153 offset:32768
	ds_read_b128 v[194:197], v153 offset:33792
	ds_read_b128 v[198:201], v153 offset:34816
	ds_read_b128 v[202:205], v153 offset:35840
	ds_read_b128 v[206:209], v153 offset:36864
	ds_read_b128 v[210:213], v153 offset:37888
	ds_read_b128 v[214:217], v153 offset:38912
	ds_read_b128 v[218:221], v153 offset:39936
	global_load_lds_dwordx4 v[230:231], off
	v_lshl_add_u64 v[230:231], s[66:67], 0, v[140:141]
	s_mov_b32 m0, s84
	s_nop 0
	global_load_lds_dwordx4 v[230:231], off
	s_waitcnt vmcnt(8)
	s_waitcnt lgkmcnt(0)
	s_barrier
	s_setprio 1
	v_mfma_f32_16x16x32_bf16 v[124:127], v[154:157], v[190:193], v[124:127]
	v_mfma_f32_16x16x32_bf16 v[116:119], v[166:169], v[190:193], v[116:119]
	v_mfma_f32_16x16x32_bf16 v[108:111], v[154:157], v[198:201], v[108:111]
	v_mfma_f32_16x16x32_bf16 v[100:103], v[166:169], v[198:201], v[100:103]
	v_mfma_f32_16x16x32_bf16 v[92:95], v[154:157], v[206:209], v[92:95]
	v_mfma_f32_16x16x32_bf16 v[84:87], v[166:169], v[206:209], v[84:87]
	v_mfma_f32_16x16x32_bf16 v[76:79], v[154:157], v[214:217], v[76:79]
	v_mfma_f32_16x16x32_bf16 v[68:71], v[166:169], v[214:217], v[68:71]
	v_mfma_f32_16x16x32_bf16 v[124:127], v[162:165], v[194:197], v[124:127]
	v_mfma_f32_16x16x32_bf16 v[116:119], v[170:173], v[194:197], v[116:119]
	v_mfma_f32_16x16x32_bf16 v[108:111], v[162:165], v[202:205], v[108:111]
	v_mfma_f32_16x16x32_bf16 v[100:103], v[170:173], v[202:205], v[100:103]
	v_mfma_f32_16x16x32_bf16 v[92:95], v[162:165], v[210:213], v[92:95]
	v_mfma_f32_16x16x32_bf16 v[84:87], v[170:173], v[210:213], v[84:87]
	v_mfma_f32_16x16x32_bf16 v[76:79], v[162:165], v[218:221], v[76:79]
	v_mfma_f32_16x16x32_bf16 v[68:71], v[170:173], v[218:221], v[68:71]
	s_setprio 0
	s_setprio 1
	v_mfma_f32_16x16x32_bf16 v[120:123], v[174:177], v[190:193], v[120:123]
	v_mfma_f32_16x16x32_bf16 v[112:115], v[182:185], v[190:193], v[112:115]
	v_mfma_f32_16x16x32_bf16 v[104:107], v[174:177], v[198:201], v[104:107]
	v_mfma_f32_16x16x32_bf16 v[96:99], v[182:185], v[198:201], v[96:99]
	v_mfma_f32_16x16x32_bf16 v[88:91], v[174:177], v[206:209], v[88:91]
	v_mfma_f32_16x16x32_bf16 v[80:83], v[182:185], v[206:209], v[80:83]
	v_mfma_f32_16x16x32_bf16 v[72:75], v[174:177], v[214:217], v[72:75]
	v_mfma_f32_16x16x32_bf16 v[64:67], v[182:185], v[214:217], v[64:67]
	v_mfma_f32_16x16x32_bf16 v[120:123], v[178:181], v[194:197], v[120:123]
	v_mfma_f32_16x16x32_bf16 v[112:115], v[186:189], v[194:197], v[112:115]
	v_mfma_f32_16x16x32_bf16 v[104:107], v[178:181], v[202:205], v[104:107]
	v_mfma_f32_16x16x32_bf16 v[96:99], v[186:189], v[202:205], v[96:99]
	v_mfma_f32_16x16x32_bf16 v[88:91], v[178:181], v[210:213], v[88:91]
	v_mfma_f32_16x16x32_bf16 v[80:83], v[186:189], v[210:213], v[80:83]
	v_mfma_f32_16x16x32_bf16 v[72:75], v[178:181], v[218:221], v[72:75]
	v_mfma_f32_16x16x32_bf16 v[64:67], v[186:189], v[218:221], v[64:67]
	s_setprio 0
	s_barrier
; #define PG8_STAGE(bufoff, gbase, voff) do { _Pragma("unroll") for (int _i = 0; _i < 2; ++_i) \
;         __builtin_amdgcn_global_load_lds((const unsigned*)((const char*)(gbase) + (voff)[_i]), (LAS unsigned*)(lds + (bufoff) + ldsw + _i * 8192), 16, 0, 0); } while (0)
; #define PG8_LDA(dst, b, h) do { _Pragma("unroll") for (int m = 0; m < 4; ++m) _Pragma("unroll") for (int k = 0; k < 2; ++k) dst[m][k] = *(const LAS bf16x8*)(lds + PG8_SA(b, h) + aoff + m * 2048 + k * 1024); } while (0)
; #define PG8_MMA(ai, bj, At, Bt) do { __builtin_amdgcn_s_setprio(1); _Pragma("unroll") for (int m = 0; m < 4; ++m) _Pragma("unroll") for (int n = 0; n < 2; ++n) _Pragma("unroll") for (int k = 0; k < 2; ++k) \
;         acc[ai][bj][m][n] = __builtin_amdgcn_mfma_f32_16x16x32_bf16(Bt[n][k], At[m][k], acc[ai][bj][m][n], 0, 0, 0); __builtin_amdgcn_s_setprio(0); } while (0)
; #define PG8_WAIT_V(n) asm volatile("s_waitcnt vmcnt(" #n ")" ::: "memory")
; #define PG8_WAIT_L(n) asm volatile("s_waitcnt lgkmcnt(" #n ")" ::: "memory")
; #define PG8_BAR __builtin_amdgcn_s_barrier()
; #define PG8_SCHED __builtin_amdgcn_sched_barrier(0)
; template <class Epi>
; __device__ __forceinline__ void gemm_phase(LAS unsigned char* lds, const Gemm g, const StaticOrder& S, const Epi& E, const int tid) {
;     ...
;         for (int t = 0; t < nt; t += 2) {
;     ...
;             PG8_LDA(At, 1, 1); PG8_STAGE(PG8_SB(1, 0), b3, voffB); PG8_STAGE(PG8_SB(1, 1), b3 + hstep, voffB); PG8_STAGE(PG8_SA(1, 0), a3, voffA);
;             PG8_WAIT_V(8); PG8_WAIT_L(0); PG8_BAR; PG8_MMA(1, 0, At, B0); PG8_MMA(1, 1, At, B1); PG8_BAR; PG8_SCHED;
;         }
	s_add_i32 s66, s95, s80
	v_lshl_add_u64 v[148:149], v[148:149], 0, s[8:9]
	s_mov_b32 m0, s66
	ds_read_b128 v[190:193], v153 offset:49152
	ds_read_b128 v[194:197], v153 offset:50176
	ds_read_b128 v[198:201], v153 offset:51200
	ds_read_b128 v[202:205], v153 offset:52224
	ds_read_b128 v[206:209], v153 offset:53248
	ds_read_b128 v[210:213], v153 offset:54272
	ds_read_b128 v[214:217], v153 offset:55296
	ds_read_b128 v[218:221], v153 offset:56320
	global_load_lds_dwordx4 v[148:149], off
	s_add_i32 m0, s66, 0x2000
	s_add_u32 s64, s64, 0x80080
	v_lshl_add_u64 v[148:149], v[222:223], 0, s[8:9]
	s_addc_u32 s65, s65, 0
	s_add_i32 s66, s96, s80
	global_load_lds_dwordx4 v[148:149], off
	v_lshl_add_u64 v[148:149], s[64:65], 0, v[128:129]
	s_mov_b32 m0, s66
	s_nop 0
	global_load_lds_dwordx4 v[148:149], off
	v_lshl_add_u64 v[148:149], s[64:65], 0, v[138:139]
	s_add_i32 m0, s66, 0x2000
	s_nop 0
	global_load_lds_dwordx4 v[148:149], off
	v_lshl_add_u64 v[148:149], v[226:227], 0, s[8:9]
	s_mov_b32 m0, s85
	s_nop 0
	global_load_lds_dwordx4 v[148:149], off
	v_lshl_add_u64 v[148:149], v[228:229], 0, s[8:9]
	s_mov_b32 m0, s86
	s_nop 0
	global_load_lds_dwordx4 v[148:149], off
	s_waitcnt vmcnt(8)
	s_waitcnt lgkmcnt(0)
	s_barrier
	s_setprio 1
	v_mfma_f32_16x16x32_bf16 v[60:63], v[154:157], v[190:193], v[60:63]
	v_mfma_f32_16x16x32_bf16 v[52:55], v[166:169], v[190:193], v[52:55]
	v_mfma_f32_16x16x32_bf16 v[44:47], v[154:157], v[198:201], v[44:47]
	v_mfma_f32_16x16x32_bf16 v[36:39], v[166:169], v[198:201], v[36:39]
	v_mfma_f32_16x16x32_bf16 v[28:31], v[154:157], v[206:209], v[28:31]
	v_mfma_f32_16x16x32_bf16 v[20:23], v[166:169], v[206:209], v[20:23]
	v_mfma_f32_16x16x32_bf16 v[12:15], v[154:157], v[214:217], v[12:15]
	v_mfma_f32_16x16x32_bf16 v[4:7], v[166:169], v[214:217], v[4:7]
	v_mfma_f32_16x16x32_bf16 v[60:63], v[162:165], v[194:197], v[60:63]
	v_mfma_f32_16x16x32_bf16 v[52:55], v[170:173], v[194:197], v[52:55]
	v_mfma_f32_16x16x32_bf16 v[44:47], v[162:165], v[202:205], v[44:47]
	v_mfma_f32_16x16x32_bf16 v[36:39], v[170:173], v[202:205], v[36:39]
	v_mfma_f32_16x16x32_bf16 v[28:31], v[162:165], v[210:213], v[28:31]
	v_mfma_f32_16x16x32_bf16 v[20:23], v[170:173], v[210:213], v[20:23]
	v_mfma_f32_16x16x32_bf16 v[12:15], v[162:165], v[218:221], v[12:15]
	v_mfma_f32_16x16x32_bf16 v[4:7], v[170:173], v[218:221], v[4:7]
	s_setprio 0
	s_setprio 1
	v_mfma_f32_16x16x32_bf16 v[56:59], v[174:177], v[190:193], v[56:59]
	v_mfma_f32_16x16x32_bf16 v[48:51], v[182:185], v[190:193], v[48:51]
	v_mfma_f32_16x16x32_bf16 v[40:43], v[174:177], v[198:201], v[40:43]
	v_mfma_f32_16x16x32_bf16 v[32:35], v[182:185], v[198:201], v[32:35]
	v_mfma_f32_16x16x32_bf16 v[24:27], v[174:177], v[206:209], v[24:27]
	v_mfma_f32_16x16x32_bf16 v[16:19], v[182:185], v[206:209], v[16:19]
	v_mfma_f32_16x16x32_bf16 v[8:11], v[174:177], v[214:217], v[8:11]
	v_mfma_f32_16x16x32_bf16 v[0:3], v[182:185], v[214:217], v[0:3]
	v_mfma_f32_16x16x32_bf16 v[56:59], v[178:181], v[194:197], v[56:59]
	v_mfma_f32_16x16x32_bf16 v[48:51], v[186:189], v[194:197], v[48:51]
	v_mfma_f32_16x16x32_bf16 v[40:43], v[178:181], v[202:205], v[40:43]
	v_mfma_f32_16x16x32_bf16 v[32:35], v[186:189], v[202:205], v[32:35]
	v_mfma_f32_16x16x32_bf16 v[24:27], v[178:181], v[210:213], v[24:27]
	v_mfma_f32_16x16x32_bf16 v[16:19], v[186:189], v[210:213], v[16:19]
	v_mfma_f32_16x16x32_bf16 v[8:11], v[178:181], v[218:221], v[8:11]
	v_mfma_f32_16x16x32_bf16 v[0:3], v[186:189], v[218:221], v[0:3]
	s_setprio 0
	s_barrier
	s_add_i32 s94, s94, 2
	s_add_u32 s92, s92, 0x100
	s_addc_u32 s93, s93, 0
	s_add_u32 s62, s62, 0x100
	s_addc_u32 s63, s63, 0
	s_cmp_gt_u32 s94, 29
	s_cbranch_scc0 .LBB0_1706
	s_and_b64 vcc, exec, s[52:53]
	s_cbranch_vccz .LBB0_1709
	s_barrier

; #define PG8_STAGE(bufoff, gbase, voff) do { _Pragma("unroll") for (int _i = 0; _i < 2; ++_i) \
;         __builtin_amdgcn_global_load_lds((const unsigned*)((const char*)(gbase) + (voff)[_i]), (LAS unsigned*)(lds + (bufoff) + ldsw + _i * 8192), 16, 0, 0); } while (0)
; #define PG8_LDA(dst, b, h) do { _Pragma("unroll") for (int m = 0; m < 4; ++m) _Pragma("unroll") for (int k = 0; k < 2; ++k) dst[m][k] = *(const LAS bf16x8*)(lds + PG8_SA(b, h) + aoff + m * 2048 + k * 1024); } while (0)
; #define PG8_LDB(dst, b, h) do { _Pragma("unroll") for (int n = 0; n < 2; ++n) _Pragma("unroll") for (int k = 0; k < 2; ++k) dst[n][k] = *(const LAS bf16x8*)(lds + PG8_SB(b, h) + boff + n * 2048 + k * 1024); } while (0)
; #define PG8_MMA(ai, bj, At, Bt) do { __builtin_amdgcn_s_setprio(1); _Pragma("unroll") for (int m = 0; m < 4; ++m) _Pragma("unroll") for (int n = 0; n < 2; ++n) _Pragma("unroll") for (int k = 0; k < 2; ++k) \
;         acc[ai][bj][m][n] = __builtin_amdgcn_mfma_f32_16x16x32_bf16(Bt[n][k], At[m][k], acc[ai][bj][m][n], 0, 0, 0); __builtin_amdgcn_s_setprio(0); } while (0)
; #define PG8_WAIT_V(n) asm volatile("s_waitcnt vmcnt(" #n ")" ::: "memory")
; #define PG8_WAIT_L(n) asm volatile("s_waitcnt lgkmcnt(" #n ")" ::: "memory")
; #define PG8_BAR __builtin_amdgcn_s_barrier()
; #define PG8_SCHED __builtin_amdgcn_sched_barrier(0)
; template <class Epi>
; __device__ __forceinline__ void gemm_phase(LAS unsigned char* lds, const Gemm g, const StaticOrder& S, const Epi& E, const int tid) {
;     ...
;         for (int t = 0; t < nt; t += 2) {
;             const bool last = (t == nt - 2);
;             const char* a1 = cA + (size_t)(t + 1) * kstep;
;             const char* a2 = last ? nA : cA + (size_t)(t + 2) * kstep; const char* b2 = last ? nB : cB + (size_t)(t + 2) * kstep;
;             const char* a3 = a2 + kstep; const char* b3 = b2 + kstep;
;             PG8_LDB(B0, 0, 0); PG8_LDB(B1, 0, 1); PG8_SCHED; PG8_LDA(At, 0, 0); PG8_STAGE(PG8_SA(1, 1), a1 + hstep, voffA);
;             PG8_WAIT_V(8); PG8_WAIT_L(0); PG8_BAR; PG8_MMA(0, 0, At, B0); PG8_MMA(0, 1, At, B1); PG8_BAR; PG8_SCHED;
;             PG8_LDA(At, 0, 1); PG8_STAGE(PG8_SB(0, 0), b2, voffB); PG8_STAGE(PG8_SB(0, 1), b2 + hstep, voffB); PG8_STAGE(PG8_SA(0, 0), a2, voffA);
;             PG8_WAIT_V(8); PG8_WAIT_L(0); PG8_BAR; PG8_MMA(1, 0, At, B0); PG8_MMA(1, 1, At, B1); PG8_BAR; PG8_SCHED;
.LBB0_1804:
	s_add_u32 s58, s56, 0x100
	s_addc_u32 s59, s57, 0
	s_add_i32 s91, 0, 0x10000
	s_cmpk_eq_i32 s90, 0x54
	s_cselect_b32 s63, s41, s59
	s_cselect_b32 s62, s40, s58
	v_add_u32_e32 v148, s91, v151
	s_cselect_b32 s61, s55, s89
	s_cselect_b32 s60, s54, s88
	s_add_i32 s92, 0, 0x14000
	ds_read_b128 v[154:157], v148
	ds_read_b128 v[162:165], v148 offset:1024
	ds_read_b128 v[166:169], v148 offset:2048
	ds_read_b128 v[170:173], v148 offset:3072
	v_add_u32_e32 v148, s92, v151
	ds_read_b128 v[174:177], v148
	ds_read_b128 v[178:181], v148 offset:1024
	ds_read_b128 v[182:185], v148 offset:2048
	ds_read_b128 v[186:189], v148 offset:3072
	v_lshl_add_u64 v[148:149], s[56:57], 0, v[146:147]
	s_add_i32 m0, s77, 0xc000
	ds_read_b128 v[190:193], v153
	ds_read_b128 v[194:197], v153 offset:1024
	ds_read_b128 v[198:201], v153 offset:2048
	ds_read_b128 v[202:205], v153 offset:3072
	ds_read_b128 v[206:209], v153 offset:4096
	ds_read_b128 v[210:213], v153 offset:5120
	ds_read_b128 v[214:217], v153 offset:6144
	ds_read_b128 v[218:221], v153 offset:7168
	global_load_lds_dwordx4 v[148:149], off
	v_lshl_add_u64 v[148:149], s[56:57], 0, v[144:145]
	s_add_i32 m0, s77, 0xe000
	s_nop 0
	global_load_lds_dwordx4 v[148:149], off
	s_waitcnt vmcnt(8)
	s_waitcnt lgkmcnt(0)
	s_barrier
	s_setprio 1
	v_mfma_f32_16x16x32_bf16 v[124:127], v[154:157], v[190:193], v[124:127]
	v_mfma_f32_16x16x32_bf16 v[120:123], v[166:169], v[190:193], v[120:123]
	v_mfma_f32_16x16x32_bf16 v[116:119], v[154:157], v[198:201], v[116:119]
	v_mfma_f32_16x16x32_bf16 v[108:111], v[166:169], v[198:201], v[108:111]
	v_mfma_f32_16x16x32_bf16 v[100:103], v[154:157], v[206:209], v[100:103]
	v_mfma_f32_16x16x32_bf16 v[92:95], v[166:169], v[206:209], v[92:95]
	v_mfma_f32_16x16x32_bf16 v[84:87], v[154:157], v[214:217], v[84:87]
	v_mfma_f32_16x16x32_bf16 v[76:79], v[166:169], v[214:217], v[76:79]
	v_mfma_f32_16x16x32_bf16 v[124:127], v[162:165], v[194:197], v[124:127]
	v_mfma_f32_16x16x32_bf16 v[120:123], v[170:173], v[194:197], v[120:123]
	v_mfma_f32_16x16x32_bf16 v[116:119], v[162:165], v[202:205], v[116:119]
	v_mfma_f32_16x16x32_bf16 v[108:111], v[170:173], v[202:205], v[108:111]
	v_mfma_f32_16x16x32_bf16 v[100:103], v[162:165], v[210:213], v[100:103]
	v_mfma_f32_16x16x32_bf16 v[92:95], v[170:173], v[210:213], v[92:95]
	v_mfma_f32_16x16x32_bf16 v[84:87], v[162:165], v[218:221], v[84:87]
	v_mfma_f32_16x16x32_bf16 v[76:79], v[170:173], v[218:221], v[76:79]
	s_setprio 0
	s_setprio 1
	v_mfma_f32_16x16x32_bf16 v[112:115], v[174:177], v[190:193], v[112:115]
	v_mfma_f32_16x16x32_bf16 v[104:107], v[182:185], v[190:193], v[104:107]
	v_mfma_f32_16x16x32_bf16 v[96:99], v[174:177], v[198:201], v[96:99]
	v_mfma_f32_16x16x32_bf16 v[88:91], v[182:185], v[198:201], v[88:91]
	v_mfma_f32_16x16x32_bf16 v[80:83], v[174:177], v[206:209], v[80:83]
	v_mfma_f32_16x16x32_bf16 v[72:75], v[182:185], v[206:209], v[72:75]
	v_mfma_f32_16x16x32_bf16 v[68:71], v[174:177], v[214:217], v[68:71]
	v_mfma_f32_16x16x32_bf16 v[64:67], v[182:185], v[214:217], v[64:67]
	v_mfma_f32_16x16x32_bf16 v[112:115], v[178:181], v[194:197], v[112:115]
	v_mfma_f32_16x16x32_bf16 v[104:107], v[186:189], v[194:197], v[104:107]
	v_mfma_f32_16x16x32_bf16 v[96:99], v[178:181], v[202:205], v[96:99]
	v_mfma_f32_16x16x32_bf16 v[88:91], v[186:189], v[202:205], v[88:91]
	v_mfma_f32_16x16x32_bf16 v[80:83], v[178:181], v[210:213], v[80:83]
	v_mfma_f32_16x16x32_bf16 v[72:75], v[186:189], v[210:213], v[72:75]
	v_mfma_f32_16x16x32_bf16 v[68:71], v[178:181], v[218:221], v[68:71]
	v_mfma_f32_16x16x32_bf16 v[64:67], v[186:189], v[218:221], v[64:67]
	s_setprio 0
	s_barrier
	s_add_i32 s56, s91, s76
	v_lshl_add_u64 v[148:149], s[60:61], 0, v[128:129]
	s_mov_b32 m0, s56
	ds_read_b128 v[190:193], v153 offset:16384
	ds_read_b128 v[194:197], v153 offset:17408
	ds_read_b128 v[198:201], v153 offset:18432
	ds_read_b128 v[202:205], v153 offset:19456
	ds_read_b128 v[206:209], v153 offset:20480
	ds_read_b128 v[210:213], v153 offset:21504
	ds_read_b128 v[214:217], v153 offset:22528
	ds_read_b128 v[218:221], v153 offset:23552
	global_load_lds_dwordx4 v[148:149], off
	s_add_i32 m0, s56, 0x2000
	s_add_u32 s56, s60, 0x160000
	v_lshl_add_u64 v[222:223], s[60:61], 0, v[138:139]
	s_addc_u32 s57, s61, 0
	s_add_i32 s91, s92, s76
	global_load_lds_dwordx4 v[222:223], off
	v_lshl_add_u64 v[226:227], s[56:57], 0, v[128:129]
	s_mov_b32 m0, s91
	v_lshl_add_u64 v[228:229], s[62:63], 0, v[140:141]
	global_load_lds_dwordx4 v[226:227], off
	v_lshl_add_u64 v[226:227], s[56:57], 0, v[138:139]
	s_add_i32 m0, s91, 0x2000
	s_nop 0
	global_load_lds_dwordx4 v[226:227], off
	v_lshl_add_u64 v[226:227], s[62:63], 0, v[142:143]
	s_mov_b32 m0, s77
	s_nop 0
	global_load_lds_dwordx4 v[226:227], off
	s_mov_b32 m0, s78
	s_nop 0
	global_load_lds_dwordx4 v[228:229], off
	s_waitcnt vmcnt(8)
	s_waitcnt lgkmcnt(0)
	s_barrier
; #define PG8_STAGE(bufoff, gbase, voff) do { _Pragma("unroll") for (int _i = 0; _i < 2; ++_i) \
;         __builtin_amdgcn_global_load_lds((const unsigned*)((const char*)(gbase) + (voff)[_i]), (LAS unsigned*)(lds + (bufoff) + ldsw + _i * 8192), 16, 0, 0); } while (0)
; #define PG8_LDA(dst, b, h) do { _Pragma("unroll") for (int m = 0; m < 4; ++m) _Pragma("unroll") for (int k = 0; k < 2; ++k) dst[m][k] = *(const LAS bf16x8*)(lds + PG8_SA(b, h) + aoff + m * 2048 + k * 1024); } while (0)
; #define PG8_LDB(dst, b, h) do { _Pragma("unroll") for (int n = 0; n < 2; ++n) _Pragma("unroll") for (int k = 0; k < 2; ++k) dst[n][k] = *(const LAS bf16x8*)(lds + PG8_SB(b, h) + boff + n * 2048 + k * 1024); } while (0)
; #define PG8_MMA(ai, bj, At, Bt) do { __builtin_amdgcn_s_setprio(1); _Pragma("unroll") for (int m = 0; m < 4; ++m) _Pragma("unroll") for (int n = 0; n < 2; ++n) _Pragma("unroll") for (int k = 0; k < 2; ++k) \
;         acc[ai][bj][m][n] = __builtin_amdgcn_mfma_f32_16x16x32_bf16(Bt[n][k], At[m][k], acc[ai][bj][m][n], 0, 0, 0); __builtin_amdgcn_s_setprio(0); } while (0)
; #define PG8_WAIT_V(n) asm volatile("s_waitcnt vmcnt(" #n ")" ::: "memory")
; #define PG8_WAIT_L(n) asm volatile("s_waitcnt lgkmcnt(" #n ")" ::: "memory")
; #define PG8_BAR __builtin_amdgcn_s_barrier()
; #define PG8_SCHED __builtin_amdgcn_sched_barrier(0)
; template <class Epi>
; __device__ __forceinline__ void gemm_phase(LAS unsigned char* lds, const Gemm g, const StaticOrder& S, const Epi& E, const int tid) {
;     ...
;             PG8_WAIT_V(8); PG8_WAIT_L(0); PG8_BAR; PG8_MMA(1, 0, At, B0); PG8_MMA(1, 1, At, B1); PG8_BAR; PG8_SCHED;
;             PG8_LDB(B0, 1, 0); PG8_LDB(B1, 1, 1); PG8_SCHED; PG8_LDA(At, 1, 0); PG8_STAGE(PG8_SA(0, 1), a2 + hstep, voffA);
;             PG8_WAIT_V(8); PG8_WAIT_L(0); PG8_BAR; PG8_MMA(0, 0, At, B0); PG8_MMA(0, 1, At, B1); PG8_BAR; PG8_SCHED;
	s_setprio 1
	v_mfma_f32_16x16x32_bf16 v[60:63], v[154:157], v[190:193], v[60:63]
	v_mfma_f32_16x16x32_bf16 v[56:59], v[166:169], v[190:193], v[56:59]
	v_mfma_f32_16x16x32_bf16 v[52:55], v[154:157], v[198:201], v[52:55]
	v_mfma_f32_16x16x32_bf16 v[44:47], v[166:169], v[198:201], v[44:47]
	v_mfma_f32_16x16x32_bf16 v[36:39], v[154:157], v[206:209], v[36:39]
	v_mfma_f32_16x16x32_bf16 v[28:31], v[166:169], v[206:209], v[28:31]
	v_mfma_f32_16x16x32_bf16 v[20:23], v[154:157], v[214:217], v[20:23]
	v_mfma_f32_16x16x32_bf16 v[12:15], v[166:169], v[214:217], v[12:15]
	v_mfma_f32_16x16x32_bf16 v[60:63], v[162:165], v[194:197], v[60:63]
	v_mfma_f32_16x16x32_bf16 v[56:59], v[170:173], v[194:197], v[56:59]
	v_mfma_f32_16x16x32_bf16 v[52:55], v[162:165], v[202:205], v[52:55]
	v_mfma_f32_16x16x32_bf16 v[44:47], v[170:173], v[202:205], v[44:47]
	v_mfma_f32_16x16x32_bf16 v[36:39], v[162:165], v[210:213], v[36:39]
	v_mfma_f32_16x16x32_bf16 v[28:31], v[170:173], v[210:213], v[28:31]
	v_mfma_f32_16x16x32_bf16 v[20:23], v[162:165], v[218:221], v[20:23]
	v_mfma_f32_16x16x32_bf16 v[12:15], v[170:173], v[218:221], v[12:15]
	s_setprio 0
	s_setprio 1
	v_mfma_f32_16x16x32_bf16 v[48:51], v[174:177], v[190:193], v[48:51]
	v_mfma_f32_16x16x32_bf16 v[40:43], v[182:185], v[190:193], v[40:43]
	v_mfma_f32_16x16x32_bf16 v[32:35], v[174:177], v[198:201], v[32:35]
	v_mfma_f32_16x16x32_bf16 v[24:27], v[182:185], v[198:201], v[24:27]
	v_mfma_f32_16x16x32_bf16 v[16:19], v[174:177], v[206:209], v[16:19]
	v_mfma_f32_16x16x32_bf16 v[8:11], v[182:185], v[206:209], v[8:11]
	v_mfma_f32_16x16x32_bf16 v[4:7], v[174:177], v[214:217], v[4:7]
	v_mfma_f32_16x16x32_bf16 v[0:3], v[182:185], v[214:217], v[0:3]
	v_mfma_f32_16x16x32_bf16 v[48:51], v[178:181], v[194:197], v[48:51]
	v_mfma_f32_16x16x32_bf16 v[40:43], v[186:189], v[194:197], v[40:43]
	v_mfma_f32_16x16x32_bf16 v[32:35], v[178:181], v[202:205], v[32:35]
	v_mfma_f32_16x16x32_bf16 v[24:27], v[186:189], v[202:205], v[24:27]
	v_mfma_f32_16x16x32_bf16 v[16:19], v[178:181], v[210:213], v[16:19]
	v_mfma_f32_16x16x32_bf16 v[8:11], v[186:189], v[210:213], v[8:11]
	v_mfma_f32_16x16x32_bf16 v[4:7], v[178:181], v[218:221], v[4:7]
	v_mfma_f32_16x16x32_bf16 v[0:3], v[186:189], v[218:221], v[0:3]
	s_setprio 0
	s_barrier
	s_add_i32 s91, 0, 0x18000
	v_add_u32_e32 v161, s91, v151
	s_add_i32 s92, 0, 0x1c000
	ds_read_b128 v[154:157], v161
	ds_read_b128 v[162:165], v161 offset:1024
	ds_read_b128 v[166:169], v161 offset:2048
	ds_read_b128 v[170:173], v161 offset:3072
	v_add_u32_e32 v161, s92, v151
	ds_read_b128 v[174:177], v161
	ds_read_b128 v[178:181], v161 offset:1024
	ds_read_b128 v[182:185], v161 offset:2048
	ds_read_b128 v[186:189], v161 offset:3072
	s_add_u32 s56, s62, 0x160000
	s_addc_u32 s57, s63, 0
	s_mov_b32 m0, s79
	v_lshl_add_u64 v[230:231], s[56:57], 0, v[142:143]
	ds_read_b128 v[190:193], v153 offset:32768
	ds_read_b128 v[194:197], v153 offset:33792
	ds_read_b128 v[198:201], v153 offset:34816
	ds_read_b128 v[202:205], v153 offset:35840
	ds_read_b128 v[206:209], v153 offset:36864
	ds_read_b128 v[210:213], v153 offset:37888
	ds_read_b128 v[214:217], v153 offset:38912
	ds_read_b128 v[218:221], v153 offset:39936
	global_load_lds_dwordx4 v[230:231], off
	v_lshl_add_u64 v[230:231], s[56:57], 0, v[140:141]
	s_mov_b32 m0, s80
	s_nop 0
	global_load_lds_dwordx4 v[230:231], off
	s_waitcnt vmcnt(8)
	s_waitcnt lgkmcnt(0)
	s_barrier
	s_setprio 1
	v_mfma_f32_16x16x32_bf16 v[124:127], v[154:157], v[190:193], v[124:127]
	v_mfma_f32_16x16x32_bf16 v[120:123], v[166:169], v[190:193], v[120:123]
	v_mfma_f32_16x16x32_bf16 v[116:119], v[154:157], v[198:201], v[116:119]
	v_mfma_f32_16x16x32_bf16 v[108:111], v[166:169], v[198:201], v[108:111]
	v_mfma_f32_16x16x32_bf16 v[100:103], v[154:157], v[206:209], v[100:103]
	v_mfma_f32_16x16x32_bf16 v[92:95], v[166:169], v[206:209], v[92:95]
	v_mfma_f32_16x16x32_bf16 v[84:87], v[154:157], v[214:217], v[84:87]
	v_mfma_f32_16x16x32_bf16 v[76:79], v[166:169], v[214:217], v[76:79]
	v_mfma_f32_16x16x32_bf16 v[124:127], v[162:165], v[194:197], v[124:127]
	v_mfma_f32_16x16x32_bf16 v[120:123], v[170:173], v[194:197], v[120:123]
	v_mfma_f32_16x16x32_bf16 v[116:119], v[162:165], v[202:205], v[116:119]
	v_mfma_f32_16x16x32_bf16 v[108:111], v[170:173], v[202:205], v[108:111]
	v_mfma_f32_16x16x32_bf16 v[100:103], v[162:165], v[210:213], v[100:103]
	v_mfma_f32_16x16x32_bf16 v[92:95], v[170:173], v[210:213], v[92:95]
	v_mfma_f32_16x16x32_bf16 v[84:87], v[162:165], v[218:221], v[84:87]
	v_mfma_f32_16x16x32_bf16 v[76:79], v[170:173], v[218:221], v[76:79]
	s_setprio 0
	s_setprio 1
	v_mfma_f32_16x16x32_bf16 v[112:115], v[174:177], v[190:193], v[112:115]
	v_mfma_f32_16x16x32_bf16 v[104:107], v[182:185], v[190:193], v[104:107]
	v_mfma_f32_16x16x32_bf16 v[96:99], v[174:177], v[198:201], v[96:99]
	v_mfma_f32_16x16x32_bf16 v[88:91], v[182:185], v[198:201], v[88:91]
	v_mfma_f32_16x16x32_bf16 v[80:83], v[174:177], v[206:209], v[80:83]
	v_mfma_f32_16x16x32_bf16 v[72:75], v[182:185], v[206:209], v[72:75]
	v_mfma_f32_16x16x32_bf16 v[68:71], v[174:177], v[214:217], v[68:71]
	v_mfma_f32_16x16x32_bf16 v[64:67], v[182:185], v[214:217], v[64:67]
	v_mfma_f32_16x16x32_bf16 v[112:115], v[178:181], v[194:197], v[112:115]
	v_mfma_f32_16x16x32_bf16 v[104:107], v[186:189], v[194:197], v[104:107]
	v_mfma_f32_16x16x32_bf16 v[96:99], v[178:181], v[202:205], v[96:99]
	v_mfma_f32_16x16x32_bf16 v[88:91], v[186:189], v[202:205], v[88:91]
	v_mfma_f32_16x16x32_bf16 v[80:83], v[178:181], v[210:213], v[80:83]
	v_mfma_f32_16x16x32_bf16 v[72:75], v[186:189], v[210:213], v[72:75]
	v_mfma_f32_16x16x32_bf16 v[68:71], v[178:181], v[218:221], v[68:71]
	v_mfma_f32_16x16x32_bf16 v[64:67], v[186:189], v[218:221], v[64:67]
	s_setprio 0
	s_barrier
; #define PG8_STAGE(bufoff, gbase, voff) do { _Pragma("unroll") for (int _i = 0; _i < 2; ++_i) \
;         __builtin_amdgcn_global_load_lds((const unsigned*)((const char*)(gbase) + (voff)[_i]), (LAS unsigned*)(lds + (bufoff) + ldsw + _i * 8192), 16, 0, 0); } while (0)
; #define PG8_LDA(dst, b, h) do { _Pragma("unroll") for (int m = 0; m < 4; ++m) _Pragma("unroll") for (int k = 0; k < 2; ++k) dst[m][k] = *(const LAS bf16x8*)(lds + PG8_SA(b, h) + aoff + m * 2048 + k * 1024); } while (0)
; #define PG8_MMA(ai, bj, At, Bt) do { __builtin_amdgcn_s_setprio(1); _Pragma("unroll") for (int m = 0; m < 4; ++m) _Pragma("unroll") for (int n = 0; n < 2; ++n) _Pragma("unroll") for (int k = 0; k < 2; ++k) \
;         acc[ai][bj][m][n] = __builtin_amdgcn_mfma_f32_16x16x32_bf16(Bt[n][k], At[m][k], acc[ai][bj][m][n], 0, 0, 0); __builtin_amdgcn_s_setprio(0); } while (0)
; #define PG8_WAIT_V(n) asm volatile("s_waitcnt vmcnt(" #n ")" ::: "memory")
; #define PG8_WAIT_L(n) asm volatile("s_waitcnt lgkmcnt(" #n ")" ::: "memory")
; #define PG8_BAR __builtin_amdgcn_s_barrier()
; #define PG8_SCHED __builtin_amdgcn_sched_barrier(0)
; template <class Epi>
; __device__ __forceinline__ void gemm_phase(LAS unsigned char* lds, const Gemm g, const StaticOrder& S, const Epi& E, const int tid) {
;     ...
;         for (int t = 0; t < nt; t += 2) {
;     ...
;             PG8_LDA(At, 1, 1); PG8_STAGE(PG8_SB(1, 0), b3, voffB); PG8_STAGE(PG8_SB(1, 1), b3 + hstep, voffB); PG8_STAGE(PG8_SA(1, 0), a3, voffA);
;             PG8_WAIT_V(8); PG8_WAIT_L(0); PG8_BAR; PG8_MMA(1, 0, At, B0); PG8_MMA(1, 1, At, B1); PG8_BAR; PG8_SCHED;
;         }
	s_add_i32 s56, s91, s76
	v_lshl_add_u64 v[148:149], v[148:149], 0, s[8:9]
	s_mov_b32 m0, s56
	ds_read_b128 v[190:193], v153 offset:49152
	ds_read_b128 v[194:197], v153 offset:50176
	ds_read_b128 v[198:201], v153 offset:51200
	ds_read_b128 v[202:205], v153 offset:52224
	ds_read_b128 v[206:209], v153 offset:53248
	ds_read_b128 v[210:213], v153 offset:54272
	ds_read_b128 v[214:217], v153 offset:55296
	ds_read_b128 v[218:221], v153 offset:56320
	global_load_lds_dwordx4 v[148:149], off
	s_add_i32 m0, s56, 0x2000
	s_add_u32 s56, s60, 0x160080
	v_lshl_add_u64 v[148:149], v[222:223], 0, s[8:9]
	s_addc_u32 s57, s61, 0
	s_add_i32 s60, s92, s76
	global_load_lds_dwordx4 v[148:149], off
	v_lshl_add_u64 v[148:149], s[56:57], 0, v[128:129]
	s_mov_b32 m0, s60
	s_nop 0
	global_load_lds_dwordx4 v[148:149], off
	v_lshl_add_u64 v[148:149], s[56:57], 0, v[138:139]
	s_add_i32 m0, s60, 0x2000
	s_nop 0
	global_load_lds_dwordx4 v[148:149], off
	v_lshl_add_u64 v[148:149], v[226:227], 0, s[8:9]
	s_mov_b32 m0, s81
	s_nop 0
	global_load_lds_dwordx4 v[148:149], off
	v_lshl_add_u64 v[148:149], v[228:229], 0, s[8:9]
	s_mov_b32 m0, s82
	s_nop 0
	global_load_lds_dwordx4 v[148:149], off
	s_waitcnt vmcnt(8)
	s_waitcnt lgkmcnt(0)
	s_barrier
	s_setprio 1
	v_mfma_f32_16x16x32_bf16 v[60:63], v[154:157], v[190:193], v[60:63]
	v_mfma_f32_16x16x32_bf16 v[56:59], v[166:169], v[190:193], v[56:59]
	v_mfma_f32_16x16x32_bf16 v[52:55], v[154:157], v[198:201], v[52:55]
	v_mfma_f32_16x16x32_bf16 v[44:47], v[166:169], v[198:201], v[44:47]
	v_mfma_f32_16x16x32_bf16 v[36:39], v[154:157], v[206:209], v[36:39]
	v_mfma_f32_16x16x32_bf16 v[28:31], v[166:169], v[206:209], v[28:31]
	v_mfma_f32_16x16x32_bf16 v[20:23], v[154:157], v[214:217], v[20:23]
	v_mfma_f32_16x16x32_bf16 v[12:15], v[166:169], v[214:217], v[12:15]
	v_mfma_f32_16x16x32_bf16 v[60:63], v[162:165], v[194:197], v[60:63]
	v_mfma_f32_16x16x32_bf16 v[56:59], v[170:173], v[194:197], v[56:59]
	v_mfma_f32_16x16x32_bf16 v[52:55], v[162:165], v[202:205], v[52:55]
	v_mfma_f32_16x16x32_bf16 v[44:47], v[170:173], v[202:205], v[44:47]
	v_mfma_f32_16x16x32_bf16 v[36:39], v[162:165], v[210:213], v[36:39]
	v_mfma_f32_16x16x32_bf16 v[28:31], v[170:173], v[210:213], v[28:31]
	v_mfma_f32_16x16x32_bf16 v[20:23], v[162:165], v[218:221], v[20:23]
	v_mfma_f32_16x16x32_bf16 v[12:15], v[170:173], v[218:221], v[12:15]
	s_setprio 0
	s_setprio 1
	v_mfma_f32_16x16x32_bf16 v[48:51], v[174:177], v[190:193], v[48:51]
	v_mfma_f32_16x16x32_bf16 v[40:43], v[182:185], v[190:193], v[40:43]
	v_mfma_f32_16x16x32_bf16 v[32:35], v[174:177], v[198:201], v[32:35]
	v_mfma_f32_16x16x32_bf16 v[24:27], v[182:185], v[198:201], v[24:27]
	v_mfma_f32_16x16x32_bf16 v[16:19], v[174:177], v[206:209], v[16:19]
	v_mfma_f32_16x16x32_bf16 v[8:11], v[182:185], v[206:209], v[8:11]
	v_mfma_f32_16x16x32_bf16 v[4:7], v[174:177], v[214:217], v[4:7]
	v_mfma_f32_16x16x32_bf16 v[0:3], v[182:185], v[214:217], v[0:3]
	v_mfma_f32_16x16x32_bf16 v[48:51], v[178:181], v[194:197], v[48:51]
	v_mfma_f32_16x16x32_bf16 v[40:43], v[186:189], v[194:197], v[40:43]
	v_mfma_f32_16x16x32_bf16 v[32:35], v[178:181], v[202:205], v[32:35]
	v_mfma_f32_16x16x32_bf16 v[24:27], v[186:189], v[202:205], v[24:27]
	v_mfma_f32_16x16x32_bf16 v[16:19], v[178:181], v[210:213], v[16:19]
	v_mfma_f32_16x16x32_bf16 v[8:11], v[186:189], v[210:213], v[8:11]
	v_mfma_f32_16x16x32_bf16 v[4:7], v[178:181], v[218:221], v[4:7]
	v_mfma_f32_16x16x32_bf16 v[0:3], v[186:189], v[218:221], v[0:3]
	s_setprio 0
	s_barrier
	s_add_i32 s90, s90, 2
	s_add_u32 s88, s88, 0x100
	s_addc_u32 s89, s89, 0
	s_cmpk_gt_u32 s90, 0x55
	s_mov_b64 s[56:57], s[58:59]
	s_cbranch_scc0 .LBB0_1804
	s_and_b64 vcc, exec, s[52:53]
	s_cbranch_vccz .LBB0_1807
	s_barrier
